# speedup vs baseline: 1.0048x; 1.0009x over previous
.LBB0_369:
	s_add_u32 s6, s8, 0xfff80080
	s_addc_u32 s7, s9, -1
	s_add_i32 s24, 0, 0x10000
	s_cmp_eq_u32 s85, 28
	s_cselect_b32 s13, s41, s7
	s_cselect_b32 s12, s43, s6
	v_add_u32_e32 v128, s24, v161
	s_cselect_b32 s7, s45, s84
	s_cselect_b32 s6, s75, s91
	s_add_i32 s28, 0, 0x14000
	ds_read_b128 v[138:141], v128
	ds_read_b128 v[142:145], v128 offset:1024
	ds_read_b128 v[146:149], v128 offset:2048
	ds_read_b128 v[150:153], v128 offset:3072
	v_add_u32_e32 v128, s28, v161
	ds_read_b128 v[154:157], v128
	ds_read_b128 v[164:167], v128 offset:1024
	ds_read_b128 v[168:171], v128 offset:2048
	ds_read_b128 v[172:175], v128 offset:3072
	v_lshl_add_u64 v[158:159], s[8:9], 0, v[134:135]
	s_add_i32 m0, s20, 0xc000
	ds_read_b128 v[176:179], v163
	ds_read_b128 v[180:183], v163 offset:1024
	ds_read_b128 v[184:187], v163 offset:2048
	ds_read_b128 v[200:203], v163 offset:3072
	ds_read_b128 v[204:207], v163 offset:4096
	ds_read_b128 v[208:211], v163 offset:5120
	ds_read_b128 v[222:225], v163 offset:6144
	ds_read_b128 v[226:229], v163 offset:7168
	global_load_lds_dwordx4 v[158:159], off
	v_lshl_add_u64 v[158:159], s[8:9], 0, v[136:137]
	s_add_i32 m0, s20, 0xe000
	s_nop 0
	global_load_lds_dwordx4 v[158:159], off
	s_waitcnt vmcnt(8)
	s_waitcnt lgkmcnt(0)
	s_barrier
	s_setprio 1
	s_waitcnt lgkmcnt(0)
	v_mfma_f32_16x16x32_bf16 v[124:127], v[138:141], v[176:179], v[124:127]
	v_mfma_f32_16x16x32_bf16 v[120:123], v[146:149], v[176:179], v[120:123]
	v_mfma_f32_16x16x32_bf16 v[108:111], v[138:141], v[184:187], v[108:111]
	v_mfma_f32_16x16x32_bf16 v[104:107], v[146:149], v[184:187], v[104:107]
	v_mfma_f32_16x16x32_bf16 v[92:95], v[138:141], v[204:207], v[92:95]
	v_mfma_f32_16x16x32_bf16 v[88:91], v[146:149], v[204:207], v[88:91]
	v_mfma_f32_16x16x32_bf16 v[76:79], v[138:141], v[222:225], v[76:79]
	v_mfma_f32_16x16x32_bf16 v[72:75], v[146:149], v[222:225], v[72:75]
	v_mfma_f32_16x16x32_bf16 v[124:127], v[142:145], v[180:183], v[124:127]
	v_mfma_f32_16x16x32_bf16 v[120:123], v[150:153], v[180:183], v[120:123]
	v_mfma_f32_16x16x32_bf16 v[108:111], v[142:145], v[200:203], v[108:111]
	v_mfma_f32_16x16x32_bf16 v[104:107], v[150:153], v[200:203], v[104:107]
	v_mfma_f32_16x16x32_bf16 v[92:95], v[142:145], v[208:211], v[92:95]
	v_mfma_f32_16x16x32_bf16 v[88:91], v[150:153], v[208:211], v[88:91]
	v_mfma_f32_16x16x32_bf16 v[76:79], v[142:145], v[226:229], v[76:79]
	v_mfma_f32_16x16x32_bf16 v[72:75], v[150:153], v[226:229], v[72:75]
	v_mfma_f32_16x16x32_bf16 v[116:119], v[154:157], v[176:179], v[116:119]
	v_mfma_f32_16x16x32_bf16 v[112:115], v[168:171], v[176:179], v[112:115]
	v_mfma_f32_16x16x32_bf16 v[100:103], v[154:157], v[184:187], v[100:103]
	v_mfma_f32_16x16x32_bf16 v[96:99], v[168:171], v[184:187], v[96:99]
	v_mfma_f32_16x16x32_bf16 v[84:87], v[154:157], v[204:207], v[84:87]
	v_mfma_f32_16x16x32_bf16 v[80:83], v[168:171], v[204:207], v[80:83]
	v_mfma_f32_16x16x32_bf16 v[68:71], v[154:157], v[222:225], v[68:71]
	v_mfma_f32_16x16x32_bf16 v[64:67], v[168:171], v[222:225], v[64:67]
	v_mfma_f32_16x16x32_bf16 v[116:119], v[164:167], v[180:183], v[116:119]
	v_mfma_f32_16x16x32_bf16 v[112:115], v[172:175], v[180:183], v[112:115]
	v_mfma_f32_16x16x32_bf16 v[100:103], v[164:167], v[200:203], v[100:103]
	v_mfma_f32_16x16x32_bf16 v[96:99], v[172:175], v[200:203], v[96:99]
	v_mfma_f32_16x16x32_bf16 v[84:87], v[164:167], v[208:211], v[84:87]
	v_mfma_f32_16x16x32_bf16 v[80:83], v[172:175], v[208:211], v[80:83]
	v_mfma_f32_16x16x32_bf16 v[68:71], v[164:167], v[226:229], v[68:71]
	v_mfma_f32_16x16x32_bf16 v[64:67], v[172:175], v[226:229], v[64:67]
	s_setprio 0
	s_barrier
	s_add_i32 s24, s24, s19
	v_lshl_add_u64 v[158:159], s[6:7], 0, v[130:131]
	s_mov_b32 m0, s24
	ds_read_b128 v[176:179], v163 offset:16384
	ds_read_b128 v[180:183], v163 offset:17408
	ds_read_b128 v[184:187], v163 offset:18432
	ds_read_b128 v[200:203], v163 offset:19456
	ds_read_b128 v[204:207], v163 offset:20480
	ds_read_b128 v[208:211], v163 offset:21504
	ds_read_b128 v[222:225], v163 offset:22528
	ds_read_b128 v[226:229], v163 offset:23552
	global_load_lds_dwordx4 v[158:159], off
	s_add_i32 m0, s24, 0x2000
	s_add_u32 s24, s6, 0x80000
	v_lshl_add_u64 v[188:189], s[6:7], 0, v[132:133]
	s_addc_u32 s25, s7, 0
	s_add_i32 s28, s28, s19
	global_load_lds_dwordx4 v[188:189], off
	v_lshl_add_u64 v[212:213], s[24:25], 0, v[130:131]
	s_mov_b32 m0, s28
	v_lshl_add_u64 v[230:231], s[12:13], 0, v[132:133]
	global_load_lds_dwordx4 v[212:213], off
	v_lshl_add_u64 v[212:213], s[24:25], 0, v[132:133]
	s_add_i32 m0, s28, 0x2000
	s_nop 0
	global_load_lds_dwordx4 v[212:213], off
	v_lshl_add_u64 v[212:213], s[12:13], 0, v[130:131]
	s_mov_b32 m0, s20
	s_nop 0
	global_load_lds_dwordx4 v[212:213], off
	s_mov_b32 m0, s21
	s_nop 0
	global_load_lds_dwordx4 v[230:231], off
	s_waitcnt vmcnt(8)
	s_waitcnt lgkmcnt(0)
	s_barrier
	s_setprio 1
	s_waitcnt lgkmcnt(0)
	v_mfma_f32_16x16x32_bf16 v[60:63], v[138:141], v[176:179], v[60:63]
	v_mfma_f32_16x16x32_bf16 v[56:59], v[146:149], v[176:179], v[56:59]
	v_mfma_f32_16x16x32_bf16 v[44:47], v[138:141], v[184:187], v[44:47]
	v_mfma_f32_16x16x32_bf16 v[40:43], v[146:149], v[184:187], v[40:43]
	v_mfma_f32_16x16x32_bf16 v[28:31], v[138:141], v[204:207], v[28:31]
	v_mfma_f32_16x16x32_bf16 v[24:27], v[146:149], v[204:207], v[24:27]
	v_mfma_f32_16x16x32_bf16 v[12:15], v[138:141], v[222:225], v[12:15]
	v_mfma_f32_16x16x32_bf16 v[8:11], v[146:149], v[222:225], v[8:11]
	v_mfma_f32_16x16x32_bf16 v[60:63], v[142:145], v[180:183], v[60:63]
	v_mfma_f32_16x16x32_bf16 v[56:59], v[150:153], v[180:183], v[56:59]
	v_mfma_f32_16x16x32_bf16 v[44:47], v[142:145], v[200:203], v[44:47]
	v_mfma_f32_16x16x32_bf16 v[40:43], v[150:153], v[200:203], v[40:43]
	v_mfma_f32_16x16x32_bf16 v[28:31], v[142:145], v[208:211], v[28:31]
	v_mfma_f32_16x16x32_bf16 v[24:27], v[150:153], v[208:211], v[24:27]
	v_mfma_f32_16x16x32_bf16 v[12:15], v[142:145], v[226:229], v[12:15]
	v_mfma_f32_16x16x32_bf16 v[8:11], v[150:153], v[226:229], v[8:11]
	v_mfma_f32_16x16x32_bf16 v[52:55], v[154:157], v[176:179], v[52:55]
	v_mfma_f32_16x16x32_bf16 v[48:51], v[168:171], v[176:179], v[48:51]
	v_mfma_f32_16x16x32_bf16 v[36:39], v[154:157], v[184:187], v[36:39]
	v_mfma_f32_16x16x32_bf16 v[32:35], v[168:171], v[184:187], v[32:35]
	v_mfma_f32_16x16x32_bf16 v[20:23], v[154:157], v[204:207], v[20:23]
	v_mfma_f32_16x16x32_bf16 v[16:19], v[168:171], v[204:207], v[16:19]
	v_mfma_f32_16x16x32_bf16 v[4:7], v[154:157], v[222:225], v[4:7]
	v_mfma_f32_16x16x32_bf16 v[0:3], v[168:171], v[222:225], v[0:3]
	v_mfma_f32_16x16x32_bf16 v[52:55], v[164:167], v[180:183], v[52:55]
	v_mfma_f32_16x16x32_bf16 v[48:51], v[172:175], v[180:183], v[48:51]
	v_mfma_f32_16x16x32_bf16 v[36:39], v[164:167], v[200:203], v[36:39]
	v_mfma_f32_16x16x32_bf16 v[32:35], v[172:175], v[200:203], v[32:35]
	v_mfma_f32_16x16x32_bf16 v[20:23], v[164:167], v[208:211], v[20:23]
	v_mfma_f32_16x16x32_bf16 v[16:19], v[172:175], v[208:211], v[16:19]
	v_mfma_f32_16x16x32_bf16 v[4:7], v[164:167], v[226:229], v[4:7]
	v_mfma_f32_16x16x32_bf16 v[0:3], v[172:175], v[226:229], v[0:3]
	s_setprio 0
	s_barrier
	s_add_i32 s24, 0, 0x18000
	v_add_u32_e32 v128, s24, v161
	s_add_i32 s25, 0, 0x1c000
	ds_read_b128 v[138:141], v128
	ds_read_b128 v[142:145], v128 offset:1024
	ds_read_b128 v[146:149], v128 offset:2048
	ds_read_b128 v[150:153], v128 offset:3072
	v_add_u32_e32 v128, s25, v161
	ds_read_b128 v[154:157], v128
	ds_read_b128 v[164:167], v128 offset:1024
	ds_read_b128 v[168:171], v128 offset:2048
	ds_read_b128 v[172:175], v128 offset:3072
	s_add_u32 s12, s12, 0x80000
	s_addc_u32 s13, s13, 0
	s_mov_b32 m0, s33
	v_lshl_add_u64 v[232:233], s[12:13], 0, v[130:131]
	ds_read_b128 v[176:179], v163 offset:32768
	ds_read_b128 v[180:183], v163 offset:33792
	ds_read_b128 v[184:187], v163 offset:34816
	ds_read_b128 v[200:203], v163 offset:35840
	ds_read_b128 v[204:207], v163 offset:36864
	ds_read_b128 v[208:211], v163 offset:37888
	ds_read_b128 v[222:225], v163 offset:38912
	ds_read_b128 v[226:229], v163 offset:39936
	global_load_lds_dwordx4 v[232:233], off
	v_lshl_add_u64 v[232:233], s[12:13], 0, v[132:133]
	s_mov_b32 m0, s16
	s_nop 0
	global_load_lds_dwordx4 v[232:233], off
	s_waitcnt vmcnt(8)
	s_waitcnt lgkmcnt(0)
	s_barrier
	s_setprio 1
	s_waitcnt lgkmcnt(0)
	v_mfma_f32_16x16x32_bf16 v[124:127], v[138:141], v[176:179], v[124:127]
	v_mfma_f32_16x16x32_bf16 v[120:123], v[146:149], v[176:179], v[120:123]
	v_mfma_f32_16x16x32_bf16 v[108:111], v[138:141], v[184:187], v[108:111]
	v_mfma_f32_16x16x32_bf16 v[104:107], v[146:149], v[184:187], v[104:107]
	v_mfma_f32_16x16x32_bf16 v[92:95], v[138:141], v[204:207], v[92:95]
	v_mfma_f32_16x16x32_bf16 v[88:91], v[146:149], v[204:207], v[88:91]
	v_mfma_f32_16x16x32_bf16 v[76:79], v[138:141], v[222:225], v[76:79]
	v_mfma_f32_16x16x32_bf16 v[72:75], v[146:149], v[222:225], v[72:75]
	v_mfma_f32_16x16x32_bf16 v[124:127], v[142:145], v[180:183], v[124:127]
	v_mfma_f32_16x16x32_bf16 v[120:123], v[150:153], v[180:183], v[120:123]
	v_mfma_f32_16x16x32_bf16 v[108:111], v[142:145], v[200:203], v[108:111]
	v_mfma_f32_16x16x32_bf16 v[104:107], v[150:153], v[200:203], v[104:107]
	v_mfma_f32_16x16x32_bf16 v[92:95], v[142:145], v[208:211], v[92:95]
	v_mfma_f32_16x16x32_bf16 v[88:91], v[150:153], v[208:211], v[88:91]
	v_mfma_f32_16x16x32_bf16 v[76:79], v[142:145], v[226:229], v[76:79]
	v_mfma_f32_16x16x32_bf16 v[72:75], v[150:153], v[226:229], v[72:75]
	v_mfma_f32_16x16x32_bf16 v[116:119], v[154:157], v[176:179], v[116:119]
	v_mfma_f32_16x16x32_bf16 v[112:115], v[168:171], v[176:179], v[112:115]
	v_mfma_f32_16x16x32_bf16 v[100:103], v[154:157], v[184:187], v[100:103]
	v_mfma_f32_16x16x32_bf16 v[96:99], v[168:171], v[184:187], v[96:99]
	v_mfma_f32_16x16x32_bf16 v[84:87], v[154:157], v[204:207], v[84:87]
	v_mfma_f32_16x16x32_bf16 v[80:83], v[168:171], v[204:207], v[80:83]
	v_mfma_f32_16x16x32_bf16 v[68:71], v[154:157], v[222:225], v[68:71]
	v_mfma_f32_16x16x32_bf16 v[64:67], v[168:171], v[222:225], v[64:67]
	v_mfma_f32_16x16x32_bf16 v[116:119], v[164:167], v[180:183], v[116:119]
	v_mfma_f32_16x16x32_bf16 v[112:115], v[172:175], v[180:183], v[112:115]
	v_mfma_f32_16x16x32_bf16 v[100:103], v[164:167], v[200:203], v[100:103]
	v_mfma_f32_16x16x32_bf16 v[96:99], v[172:175], v[200:203], v[96:99]
	v_mfma_f32_16x16x32_bf16 v[84:87], v[164:167], v[208:211], v[84:87]
	v_mfma_f32_16x16x32_bf16 v[80:83], v[172:175], v[208:211], v[80:83]
	v_mfma_f32_16x16x32_bf16 v[68:71], v[164:167], v[226:229], v[68:71]
	v_mfma_f32_16x16x32_bf16 v[64:67], v[172:175], v[226:229], v[64:67]
	s_setprio 0
	s_barrier
	s_add_i32 s12, s24, s19
	v_lshl_add_u64 v[158:159], v[158:159], 0, s[26:27]
	s_mov_b32 m0, s12
	ds_read_b128 v[176:179], v163 offset:49152
	ds_read_b128 v[180:183], v163 offset:50176
	ds_read_b128 v[184:187], v163 offset:51200
	ds_read_b128 v[200:203], v163 offset:52224
	ds_read_b128 v[204:207], v163 offset:53248
	ds_read_b128 v[208:211], v163 offset:54272
	ds_read_b128 v[222:225], v163 offset:55296
	ds_read_b128 v[226:229], v163 offset:56320
	global_load_lds_dwordx4 v[158:159], off
	s_add_i32 m0, s12, 0x2000
	s_add_u32 s6, s6, 0x80080
	v_lshl_add_u64 v[158:159], v[188:189], 0, s[26:27]
	s_addc_u32 s7, s7, 0
	s_add_i32 s12, s25, s19
	global_load_lds_dwordx4 v[158:159], off
	v_lshl_add_u64 v[158:159], s[6:7], 0, v[130:131]
	s_mov_b32 m0, s12
	s_nop 0
	global_load_lds_dwordx4 v[158:159], off
	v_lshl_add_u64 v[158:159], s[6:7], 0, v[132:133]
	s_add_i32 m0, s12, 0x2000
	s_nop 0
	global_load_lds_dwordx4 v[158:159], off
	v_lshl_add_u64 v[158:159], v[212:213], 0, s[26:27]
	s_mov_b32 m0, s72
	s_nop 0
	global_load_lds_dwordx4 v[158:159], off
	v_lshl_add_u64 v[158:159], v[230:231], 0, s[26:27]
	s_mov_b32 m0, s73
	s_nop 0
	global_load_lds_dwordx4 v[158:159], off
	s_waitcnt vmcnt(8)
	s_waitcnt lgkmcnt(0)
	s_barrier
	s_setprio 1
	s_waitcnt lgkmcnt(0)
	v_mfma_f32_16x16x32_bf16 v[60:63], v[138:141], v[176:179], v[60:63]
	v_mfma_f32_16x16x32_bf16 v[56:59], v[146:149], v[176:179], v[56:59]
	v_mfma_f32_16x16x32_bf16 v[44:47], v[138:141], v[184:187], v[44:47]
	v_mfma_f32_16x16x32_bf16 v[40:43], v[146:149], v[184:187], v[40:43]
	v_mfma_f32_16x16x32_bf16 v[28:31], v[138:141], v[204:207], v[28:31]
	v_mfma_f32_16x16x32_bf16 v[24:27], v[146:149], v[204:207], v[24:27]
	v_mfma_f32_16x16x32_bf16 v[12:15], v[138:141], v[222:225], v[12:15]
	v_mfma_f32_16x16x32_bf16 v[8:11], v[146:149], v[222:225], v[8:11]
	v_mfma_f32_16x16x32_bf16 v[60:63], v[142:145], v[180:183], v[60:63]
	v_mfma_f32_16x16x32_bf16 v[56:59], v[150:153], v[180:183], v[56:59]
	v_mfma_f32_16x16x32_bf16 v[44:47], v[142:145], v[200:203], v[44:47]
	v_mfma_f32_16x16x32_bf16 v[40:43], v[150:153], v[200:203], v[40:43]
	v_mfma_f32_16x16x32_bf16 v[28:31], v[142:145], v[208:211], v[28:31]
	v_mfma_f32_16x16x32_bf16 v[24:27], v[150:153], v[208:211], v[24:27]
	v_mfma_f32_16x16x32_bf16 v[12:15], v[142:145], v[226:229], v[12:15]
	v_mfma_f32_16x16x32_bf16 v[8:11], v[150:153], v[226:229], v[8:11]
	v_mfma_f32_16x16x32_bf16 v[52:55], v[154:157], v[176:179], v[52:55]
	v_mfma_f32_16x16x32_bf16 v[48:51], v[168:171], v[176:179], v[48:51]
	v_mfma_f32_16x16x32_bf16 v[36:39], v[154:157], v[184:187], v[36:39]
	v_mfma_f32_16x16x32_bf16 v[32:35], v[168:171], v[184:187], v[32:35]
	v_mfma_f32_16x16x32_bf16 v[20:23], v[154:157], v[204:207], v[20:23]
	v_mfma_f32_16x16x32_bf16 v[16:19], v[168:171], v[204:207], v[16:19]
	v_mfma_f32_16x16x32_bf16 v[4:7], v[154:157], v[222:225], v[4:7]
	v_mfma_f32_16x16x32_bf16 v[0:3], v[168:171], v[222:225], v[0:3]
	v_mfma_f32_16x16x32_bf16 v[52:55], v[164:167], v[180:183], v[52:55]
	v_mfma_f32_16x16x32_bf16 v[48:51], v[172:175], v[180:183], v[48:51]
	v_mfma_f32_16x16x32_bf16 v[36:39], v[164:167], v[200:203], v[36:39]
	v_mfma_f32_16x16x32_bf16 v[32:35], v[172:175], v[200:203], v[32:35]
	v_mfma_f32_16x16x32_bf16 v[20:23], v[164:167], v[208:211], v[20:23]
	v_mfma_f32_16x16x32_bf16 v[16:19], v[172:175], v[208:211], v[16:19]
	v_mfma_f32_16x16x32_bf16 v[4:7], v[164:167], v[226:229], v[4:7]
	v_mfma_f32_16x16x32_bf16 v[0:3], v[172:175], v[226:229], v[0:3]
	s_setprio 0
	s_barrier
	s_add_i32 s85, s85, 2
	s_add_u32 s8, s8, 0x100
	s_addc_u32 s9, s9, 0
	s_add_u32 s91, s91, 0x100
	s_addc_u32 s84, s84, 0
	s_cmp_gt_u32 s85, 29
	s_cbranch_scc0 .LBB0_369
	s_nop 0
	s_nop 0
	s_nop 0
	s_nop 0
	s_nop 0
	s_nop 0
	s_nop 0
	s_nop 0
	s_and_b64 vcc, exec, s[88:89]
	s_cbranch_vccz .LBB0_372
	s_barrier

.LBB0_729:
	s_add_u32 s10, s8, 0xfffc0080
	s_addc_u32 s11, s9, -1
	s_add_i32 s24, 0, 0x10000
	s_cmp_eq_u32 s85, 12
	s_cselect_b32 s13, s47, s11
	s_cselect_b32 s12, s73, s10
	s_cselect_b32 s11, s45, s84
	s_cselect_b32 s10, s74, s75
	s_add_i32 s28, 0, 0x14000
	v_add_u32_e32 v116, s24, v223
	v_add_u32_e32 v154, s28, v223
	ds_read_b128 v[88:91], v116
	ds_read_b128 v[96:99], v116 offset:1024
	ds_read_b128 v[104:107], v116 offset:2048
	ds_read_b128 v[116:119], v116 offset:3072
	ds_read_b128 v[130:133], v154
	ds_read_b128 v[138:141], v154 offset:1024
	ds_read_b128 v[146:149], v154 offset:2048
	ds_read_b128 v[154:157], v154 offset:3072
	v_lshl_add_u64 v[226:227], s[8:9], 0, v[206:207]
	s_add_i32 m0, s16, 0xc000
	ds_read_b128 v[162:165], v225
	ds_read_b128 v[166:169], v225 offset:1024
	ds_read_b128 v[170:173], v225 offset:2048
	ds_read_b128 v[174:177], v225 offset:3072
	ds_read_b128 v[178:181], v225 offset:4096
	ds_read_b128 v[182:185], v225 offset:5120
	ds_read_b128 v[186:189], v225 offset:6144
	ds_read_b128 v[210:213], v225 offset:7168
	global_load_lds_dwordx4 v[226:227], off
	v_lshl_add_u64 v[226:227], s[8:9], 0, v[208:209]
	s_add_i32 m0, s16, 0xe000
	s_nop 0
	global_load_lds_dwordx4 v[226:227], off
	s_waitcnt vmcnt(8)
	s_waitcnt lgkmcnt(0)
	s_barrier
	s_setprio 1
	s_waitcnt lgkmcnt(0)
	v_mfma_f32_16x16x32_bf16 v[158:161], v[88:91], v[162:165], v[158:161]
	v_mfma_f32_16x16x32_bf16 v[150:153], v[104:107], v[162:165], v[150:153]
	v_mfma_f32_16x16x32_bf16 v[124:127], v[88:91], v[170:173], v[124:127]
	v_mfma_f32_16x16x32_bf16 v[120:123], v[104:107], v[170:173], v[120:123]
	v_mfma_f32_16x16x32_bf16 v[100:103], v[88:91], v[178:181], v[100:103]
	v_mfma_f32_16x16x32_bf16 v[92:95], v[104:107], v[178:181], v[92:95]
	v_mfma_f32_16x16x32_bf16 v[76:79], v[88:91], v[186:189], v[76:79]
	v_mfma_f32_16x16x32_bf16 v[72:75], v[104:107], v[186:189], v[72:75]
	v_mfma_f32_16x16x32_bf16 v[158:161], v[96:99], v[166:169], v[158:161]
	v_mfma_f32_16x16x32_bf16 v[150:153], v[116:119], v[166:169], v[150:153]
	v_mfma_f32_16x16x32_bf16 v[124:127], v[96:99], v[174:177], v[124:127]
	v_mfma_f32_16x16x32_bf16 v[120:123], v[116:119], v[174:177], v[120:123]
	v_mfma_f32_16x16x32_bf16 v[100:103], v[96:99], v[182:185], v[100:103]
	v_mfma_f32_16x16x32_bf16 v[92:95], v[116:119], v[182:185], v[92:95]
	v_mfma_f32_16x16x32_bf16 v[76:79], v[96:99], v[210:213], v[76:79]
	v_mfma_f32_16x16x32_bf16 v[72:75], v[116:119], v[210:213], v[72:75]
	v_mfma_f32_16x16x32_bf16 v[142:145], v[130:133], v[162:165], v[142:145]
	v_mfma_f32_16x16x32_bf16 v[134:137], v[146:149], v[162:165], v[134:137]
	v_mfma_f32_16x16x32_bf16 v[112:115], v[130:133], v[170:173], v[112:115]
	v_mfma_f32_16x16x32_bf16 v[108:111], v[146:149], v[170:173], v[108:111]
	v_mfma_f32_16x16x32_bf16 v[84:87], v[130:133], v[178:181], v[84:87]
	v_mfma_f32_16x16x32_bf16 v[80:83], v[146:149], v[178:181], v[80:83]
	v_mfma_f32_16x16x32_bf16 v[68:71], v[130:133], v[186:189], v[68:71]
	v_mfma_f32_16x16x32_bf16 v[64:67], v[146:149], v[186:189], v[64:67]
	v_mfma_f32_16x16x32_bf16 v[142:145], v[138:141], v[166:169], v[142:145]
	v_mfma_f32_16x16x32_bf16 v[134:137], v[154:157], v[166:169], v[134:137]
	v_mfma_f32_16x16x32_bf16 v[112:115], v[138:141], v[174:177], v[112:115]
	v_mfma_f32_16x16x32_bf16 v[108:111], v[154:157], v[174:177], v[108:111]
	v_mfma_f32_16x16x32_bf16 v[84:87], v[138:141], v[182:185], v[84:87]
	v_mfma_f32_16x16x32_bf16 v[80:83], v[154:157], v[182:185], v[80:83]
	v_mfma_f32_16x16x32_bf16 v[68:71], v[138:141], v[210:213], v[68:71]
	v_mfma_f32_16x16x32_bf16 v[64:67], v[154:157], v[210:213], v[64:67]
	s_setprio 0
	s_barrier
	s_add_i32 s24, s24, s14
	v_lshl_add_u64 v[226:227], s[10:11], 0, v[128:129]
	s_mov_b32 m0, s24
	ds_read_b128 v[162:165], v225 offset:16384
	ds_read_b128 v[166:169], v225 offset:17408
	ds_read_b128 v[170:173], v225 offset:18432
	ds_read_b128 v[174:177], v225 offset:19456
	ds_read_b128 v[178:181], v225 offset:20480
	ds_read_b128 v[182:185], v225 offset:21504
	ds_read_b128 v[186:189], v225 offset:22528
	ds_read_b128 v[210:213], v225 offset:23552
	global_load_lds_dwordx4 v[226:227], off
	s_add_i32 m0, s24, 0x2000
	s_add_u32 s24, s10, 0x40000
	v_lshl_add_u64 v[228:229], s[10:11], 0, v[200:201]
	s_addc_u32 s25, s11, 0
	s_add_i32 s28, s28, s14
	global_load_lds_dwordx4 v[228:229], off
	v_lshl_add_u64 v[230:231], s[24:25], 0, v[128:129]
	s_mov_b32 m0, s28
	v_lshl_add_u64 v[232:233], s[12:13], 0, v[202:203]
	global_load_lds_dwordx4 v[230:231], off
	v_lshl_add_u64 v[230:231], s[24:25], 0, v[200:201]
	s_add_i32 m0, s28, 0x2000
	s_nop 0
	global_load_lds_dwordx4 v[230:231], off
	v_lshl_add_u64 v[230:231], s[12:13], 0, v[204:205]
	s_mov_b32 m0, s16
	s_nop 0
	global_load_lds_dwordx4 v[230:231], off
	s_mov_b32 m0, s17
	s_nop 0
	global_load_lds_dwordx4 v[232:233], off
	s_waitcnt vmcnt(8)
	s_waitcnt lgkmcnt(0)
	s_barrier
	s_setprio 1
	s_waitcnt lgkmcnt(0)
	v_mfma_f32_16x16x32_bf16 v[60:63], v[88:91], v[162:165], v[60:63]
	v_mfma_f32_16x16x32_bf16 v[56:59], v[104:107], v[162:165], v[56:59]
	v_mfma_f32_16x16x32_bf16 v[44:47], v[88:91], v[170:173], v[44:47]
	v_mfma_f32_16x16x32_bf16 v[40:43], v[104:107], v[170:173], v[40:43]
	v_mfma_f32_16x16x32_bf16 v[28:31], v[88:91], v[178:181], v[28:31]
	v_mfma_f32_16x16x32_bf16 v[24:27], v[104:107], v[178:181], v[24:27]
	v_mfma_f32_16x16x32_bf16 v[12:15], v[88:91], v[186:189], v[12:15]
	v_mfma_f32_16x16x32_bf16 v[8:11], v[104:107], v[186:189], v[8:11]
	v_mfma_f32_16x16x32_bf16 v[60:63], v[96:99], v[166:169], v[60:63]
	v_mfma_f32_16x16x32_bf16 v[56:59], v[116:119], v[166:169], v[56:59]
	v_mfma_f32_16x16x32_bf16 v[44:47], v[96:99], v[174:177], v[44:47]
	v_mfma_f32_16x16x32_bf16 v[40:43], v[116:119], v[174:177], v[40:43]
	v_mfma_f32_16x16x32_bf16 v[28:31], v[96:99], v[182:185], v[28:31]
	v_mfma_f32_16x16x32_bf16 v[24:27], v[116:119], v[182:185], v[24:27]
	v_mfma_f32_16x16x32_bf16 v[12:15], v[96:99], v[210:213], v[12:15]
	v_mfma_f32_16x16x32_bf16 v[8:11], v[116:119], v[210:213], v[8:11]
	v_mfma_f32_16x16x32_bf16 v[52:55], v[130:133], v[162:165], v[52:55]
	v_mfma_f32_16x16x32_bf16 v[48:51], v[146:149], v[162:165], v[48:51]
	v_mfma_f32_16x16x32_bf16 v[36:39], v[130:133], v[170:173], v[36:39]
	v_mfma_f32_16x16x32_bf16 v[32:35], v[146:149], v[170:173], v[32:35]
	v_mfma_f32_16x16x32_bf16 v[20:23], v[130:133], v[178:181], v[20:23]
	v_mfma_f32_16x16x32_bf16 v[16:19], v[146:149], v[178:181], v[16:19]
	v_mfma_f32_16x16x32_bf16 v[4:7], v[130:133], v[186:189], v[4:7]
	v_mfma_f32_16x16x32_bf16 v[0:3], v[146:149], v[186:189], v[0:3]
	v_mfma_f32_16x16x32_bf16 v[52:55], v[138:141], v[166:169], v[52:55]
	v_mfma_f32_16x16x32_bf16 v[48:51], v[154:157], v[166:169], v[48:51]
	v_mfma_f32_16x16x32_bf16 v[36:39], v[138:141], v[174:177], v[36:39]
	v_mfma_f32_16x16x32_bf16 v[32:35], v[154:157], v[174:177], v[32:35]
	v_mfma_f32_16x16x32_bf16 v[20:23], v[138:141], v[182:185], v[20:23]
	v_mfma_f32_16x16x32_bf16 v[16:19], v[154:157], v[182:185], v[16:19]
	v_mfma_f32_16x16x32_bf16 v[4:7], v[138:141], v[210:213], v[4:7]
	v_mfma_f32_16x16x32_bf16 v[0:3], v[154:157], v[210:213], v[0:3]
	s_setprio 0
	s_barrier
	s_add_i32 s24, 0, 0x18000
	s_add_i32 s25, 0, 0x1c000
	v_add_u32_e32 v116, s24, v223
	v_add_u32_e32 v154, s25, v223
	ds_read_b128 v[88:91], v116
	ds_read_b128 v[96:99], v116 offset:1024
	ds_read_b128 v[104:107], v116 offset:2048
	ds_read_b128 v[116:119], v116 offset:3072
	ds_read_b128 v[130:133], v154
	ds_read_b128 v[138:141], v154 offset:1024
	ds_read_b128 v[146:149], v154 offset:2048
	ds_read_b128 v[154:157], v154 offset:3072
	s_add_u32 s12, s12, 0x40000
	s_addc_u32 s13, s13, 0
	s_mov_b32 m0, s18
	v_lshl_add_u64 v[234:235], s[12:13], 0, v[204:205]
	ds_read_b128 v[162:165], v225 offset:32768
	ds_read_b128 v[166:169], v225 offset:33792
	ds_read_b128 v[170:173], v225 offset:34816
	ds_read_b128 v[174:177], v225 offset:35840
	ds_read_b128 v[178:181], v225 offset:36864
	ds_read_b128 v[182:185], v225 offset:37888
	ds_read_b128 v[186:189], v225 offset:38912
	ds_read_b128 v[210:213], v225 offset:39936
	global_load_lds_dwordx4 v[234:235], off
	v_lshl_add_u64 v[234:235], s[12:13], 0, v[202:203]
	s_mov_b32 m0, s19
	s_nop 0
	global_load_lds_dwordx4 v[234:235], off
	s_waitcnt vmcnt(8)
	s_waitcnt lgkmcnt(0)
	s_barrier
	s_setprio 1
	s_waitcnt lgkmcnt(0)
	v_mfma_f32_16x16x32_bf16 v[158:161], v[88:91], v[162:165], v[158:161]
	v_mfma_f32_16x16x32_bf16 v[150:153], v[104:107], v[162:165], v[150:153]
	v_mfma_f32_16x16x32_bf16 v[124:127], v[88:91], v[170:173], v[124:127]
	v_mfma_f32_16x16x32_bf16 v[120:123], v[104:107], v[170:173], v[120:123]
	v_mfma_f32_16x16x32_bf16 v[100:103], v[88:91], v[178:181], v[100:103]
	v_mfma_f32_16x16x32_bf16 v[92:95], v[104:107], v[178:181], v[92:95]
	v_mfma_f32_16x16x32_bf16 v[76:79], v[88:91], v[186:189], v[76:79]
	v_mfma_f32_16x16x32_bf16 v[72:75], v[104:107], v[186:189], v[72:75]
	v_mfma_f32_16x16x32_bf16 v[158:161], v[96:99], v[166:169], v[158:161]
	v_mfma_f32_16x16x32_bf16 v[150:153], v[116:119], v[166:169], v[150:153]
	v_mfma_f32_16x16x32_bf16 v[124:127], v[96:99], v[174:177], v[124:127]
	v_mfma_f32_16x16x32_bf16 v[120:123], v[116:119], v[174:177], v[120:123]
	v_mfma_f32_16x16x32_bf16 v[100:103], v[96:99], v[182:185], v[100:103]
	v_mfma_f32_16x16x32_bf16 v[92:95], v[116:119], v[182:185], v[92:95]
	v_mfma_f32_16x16x32_bf16 v[76:79], v[96:99], v[210:213], v[76:79]
	v_mfma_f32_16x16x32_bf16 v[72:75], v[116:119], v[210:213], v[72:75]
	v_mfma_f32_16x16x32_bf16 v[142:145], v[130:133], v[162:165], v[142:145]
	v_mfma_f32_16x16x32_bf16 v[134:137], v[146:149], v[162:165], v[134:137]
	v_mfma_f32_16x16x32_bf16 v[112:115], v[130:133], v[170:173], v[112:115]
	v_mfma_f32_16x16x32_bf16 v[108:111], v[146:149], v[170:173], v[108:111]
	v_mfma_f32_16x16x32_bf16 v[84:87], v[130:133], v[178:181], v[84:87]
	v_mfma_f32_16x16x32_bf16 v[80:83], v[146:149], v[178:181], v[80:83]
	v_mfma_f32_16x16x32_bf16 v[68:71], v[130:133], v[186:189], v[68:71]
	v_mfma_f32_16x16x32_bf16 v[64:67], v[146:149], v[186:189], v[64:67]
	v_mfma_f32_16x16x32_bf16 v[142:145], v[138:141], v[166:169], v[142:145]
	v_mfma_f32_16x16x32_bf16 v[134:137], v[154:157], v[166:169], v[134:137]
	v_mfma_f32_16x16x32_bf16 v[112:115], v[138:141], v[174:177], v[112:115]
	v_mfma_f32_16x16x32_bf16 v[108:111], v[154:157], v[174:177], v[108:111]
	v_mfma_f32_16x16x32_bf16 v[84:87], v[138:141], v[182:185], v[84:87]
	v_mfma_f32_16x16x32_bf16 v[80:83], v[154:157], v[182:185], v[80:83]
	v_mfma_f32_16x16x32_bf16 v[68:71], v[138:141], v[210:213], v[68:71]
	v_mfma_f32_16x16x32_bf16 v[64:67], v[154:157], v[210:213], v[64:67]
	s_setprio 0
	s_barrier
	s_add_i32 s12, s24, s14
	v_lshl_add_u64 v[226:227], v[226:227], 0, s[26:27]
	s_mov_b32 m0, s12
	ds_read_b128 v[162:165], v225 offset:49152
	ds_read_b128 v[166:169], v225 offset:50176
	ds_read_b128 v[170:173], v225 offset:51200
	ds_read_b128 v[174:177], v225 offset:52224
	ds_read_b128 v[178:181], v225 offset:53248
	ds_read_b128 v[182:185], v225 offset:54272
	ds_read_b128 v[186:189], v225 offset:55296
	ds_read_b128 v[210:213], v225 offset:56320
	global_load_lds_dwordx4 v[226:227], off
	s_add_i32 m0, s12, 0x2000
	s_add_u32 s10, s10, 0x40080
	v_lshl_add_u64 v[226:227], v[228:229], 0, s[26:27]
	s_addc_u32 s11, s11, 0
	s_add_i32 s12, s25, s14
	global_load_lds_dwordx4 v[226:227], off
	v_lshl_add_u64 v[226:227], s[10:11], 0, v[128:129]
	s_mov_b32 m0, s12
	s_nop 0
	global_load_lds_dwordx4 v[226:227], off
	v_lshl_add_u64 v[226:227], s[10:11], 0, v[200:201]
	s_add_i32 m0, s12, 0x2000
	s_nop 0
	global_load_lds_dwordx4 v[226:227], off
	v_lshl_add_u64 v[226:227], v[230:231], 0, s[26:27]
	s_mov_b32 m0, s20
	s_nop 0
	global_load_lds_dwordx4 v[226:227], off
	v_lshl_add_u64 v[226:227], v[232:233], 0, s[26:27]
	s_mov_b32 m0, s21
	s_nop 0
	global_load_lds_dwordx4 v[226:227], off
	s_waitcnt vmcnt(8)
	s_waitcnt lgkmcnt(0)
	s_barrier
	s_setprio 1
	s_waitcnt lgkmcnt(0)
	v_mfma_f32_16x16x32_bf16 v[60:63], v[88:91], v[162:165], v[60:63]
	v_mfma_f32_16x16x32_bf16 v[56:59], v[104:107], v[162:165], v[56:59]
	v_mfma_f32_16x16x32_bf16 v[44:47], v[88:91], v[170:173], v[44:47]
	v_mfma_f32_16x16x32_bf16 v[40:43], v[104:107], v[170:173], v[40:43]
	v_mfma_f32_16x16x32_bf16 v[28:31], v[88:91], v[178:181], v[28:31]
	v_mfma_f32_16x16x32_bf16 v[24:27], v[104:107], v[178:181], v[24:27]
	v_mfma_f32_16x16x32_bf16 v[12:15], v[88:91], v[186:189], v[12:15]
	v_mfma_f32_16x16x32_bf16 v[8:11], v[104:107], v[186:189], v[8:11]
	v_mfma_f32_16x16x32_bf16 v[60:63], v[96:99], v[166:169], v[60:63]
	v_mfma_f32_16x16x32_bf16 v[56:59], v[116:119], v[166:169], v[56:59]
	v_mfma_f32_16x16x32_bf16 v[44:47], v[96:99], v[174:177], v[44:47]
	v_mfma_f32_16x16x32_bf16 v[40:43], v[116:119], v[174:177], v[40:43]
	v_mfma_f32_16x16x32_bf16 v[28:31], v[96:99], v[182:185], v[28:31]
	v_mfma_f32_16x16x32_bf16 v[24:27], v[116:119], v[182:185], v[24:27]
	v_mfma_f32_16x16x32_bf16 v[12:15], v[96:99], v[210:213], v[12:15]
	v_mfma_f32_16x16x32_bf16 v[8:11], v[116:119], v[210:213], v[8:11]
	v_mfma_f32_16x16x32_bf16 v[52:55], v[130:133], v[162:165], v[52:55]
	v_mfma_f32_16x16x32_bf16 v[48:51], v[146:149], v[162:165], v[48:51]
	v_mfma_f32_16x16x32_bf16 v[36:39], v[130:133], v[170:173], v[36:39]
	v_mfma_f32_16x16x32_bf16 v[32:35], v[146:149], v[170:173], v[32:35]
	v_mfma_f32_16x16x32_bf16 v[20:23], v[130:133], v[178:181], v[20:23]
	v_mfma_f32_16x16x32_bf16 v[16:19], v[146:149], v[178:181], v[16:19]
	v_mfma_f32_16x16x32_bf16 v[4:7], v[130:133], v[186:189], v[4:7]
	v_mfma_f32_16x16x32_bf16 v[0:3], v[146:149], v[186:189], v[0:3]
	v_mfma_f32_16x16x32_bf16 v[52:55], v[138:141], v[166:169], v[52:55]
	v_mfma_f32_16x16x32_bf16 v[48:51], v[154:157], v[166:169], v[48:51]
	v_mfma_f32_16x16x32_bf16 v[36:39], v[138:141], v[174:177], v[36:39]
	v_mfma_f32_16x16x32_bf16 v[32:35], v[154:157], v[174:177], v[32:35]
	v_mfma_f32_16x16x32_bf16 v[20:23], v[138:141], v[182:185], v[20:23]
	v_mfma_f32_16x16x32_bf16 v[16:19], v[154:157], v[182:185], v[16:19]
	v_mfma_f32_16x16x32_bf16 v[4:7], v[138:141], v[210:213], v[4:7]
	v_mfma_f32_16x16x32_bf16 v[0:3], v[154:157], v[210:213], v[0:3]
	s_setprio 0
	s_barrier
	s_add_i32 s85, s85, 2
	s_add_u32 s8, s8, 0x100
	s_addc_u32 s9, s9, 0
	s_add_u32 s75, s75, 0x100
	s_addc_u32 s84, s84, 0
	s_cmp_gt_u32 s85, 13
	s_cbranch_scc0 .LBB0_729
	s_nop 0
	s_nop 0
	s_nop 0
	s_nop 0
	s_nop 0
	s_nop 0
	s_nop 0
	s_nop 0
	s_and_b64 vcc, exec, s[6:7]
	s_cbranch_vccz .LBB0_732
	s_barrier

.LBB0_838:
	s_add_u32 s10, s8, 0xfff80080
	s_addc_u32 s11, s9, -1
	s_add_i32 s24, 0, 0x10000
	s_cmp_eq_u32 s84, 28
	s_cselect_b32 s13, s47, s11
	s_cselect_b32 s12, s72, s10
	s_cselect_b32 s11, s45, s75
	s_cselect_b32 s10, s73, s74
	s_add_i32 s25, 0, 0x14000
	v_add_u32_e32 v156, s24, v149
	v_add_u32_e32 v172, s25, v149
	ds_read_b128 v[140:143], v156
	ds_read_b128 v[144:147], v156 offset:1024
	ds_read_b128 v[152:155], v156 offset:2048
	ds_read_b128 v[156:159], v156 offset:3072
	ds_read_b128 v[160:163], v172
	ds_read_b128 v[164:167], v172 offset:1024
	ds_read_b128 v[168:171], v172 offset:2048
	ds_read_b128 v[172:175], v172 offset:3072
	v_lshl_add_u64 v[188:189], s[8:9], 0, v[136:137]
	s_add_i32 m0, s16, 0xc000
	ds_read_b128 v[176:179], v151
	ds_read_b128 v[180:183], v151 offset:1024
	ds_read_b128 v[184:187], v151 offset:2048
	ds_read_b128 v[200:203], v151 offset:3072
	ds_read_b128 v[204:207], v151 offset:4096
	ds_read_b128 v[208:211], v151 offset:5120
	ds_read_b128 v[222:225], v151 offset:6144
	ds_read_b128 v[226:229], v151 offset:7168
	global_load_lds_dwordx4 v[188:189], off
	v_lshl_add_u64 v[188:189], s[8:9], 0, v[138:139]
	s_add_i32 m0, s16, 0xe000
	s_nop 0
	global_load_lds_dwordx4 v[188:189], off
	s_waitcnt vmcnt(8)
	s_waitcnt lgkmcnt(0)
	s_barrier
	s_setprio 1
	s_waitcnt lgkmcnt(0)
	v_mfma_f32_16x16x32_bf16 v[124:127], v[140:143], v[176:179], v[124:127]
	v_mfma_f32_16x16x32_bf16 v[120:123], v[152:155], v[176:179], v[120:123]
	v_mfma_f32_16x16x32_bf16 v[108:111], v[140:143], v[184:187], v[108:111]
	v_mfma_f32_16x16x32_bf16 v[104:107], v[152:155], v[184:187], v[104:107]
	v_mfma_f32_16x16x32_bf16 v[92:95], v[140:143], v[204:207], v[92:95]
	v_mfma_f32_16x16x32_bf16 v[88:91], v[152:155], v[204:207], v[88:91]
	v_mfma_f32_16x16x32_bf16 v[76:79], v[140:143], v[222:225], v[76:79]
	v_mfma_f32_16x16x32_bf16 v[72:75], v[152:155], v[222:225], v[72:75]
	v_mfma_f32_16x16x32_bf16 v[124:127], v[144:147], v[180:183], v[124:127]
	v_mfma_f32_16x16x32_bf16 v[120:123], v[156:159], v[180:183], v[120:123]
	v_mfma_f32_16x16x32_bf16 v[108:111], v[144:147], v[200:203], v[108:111]
	v_mfma_f32_16x16x32_bf16 v[104:107], v[156:159], v[200:203], v[104:107]
	v_mfma_f32_16x16x32_bf16 v[92:95], v[144:147], v[208:211], v[92:95]
	v_mfma_f32_16x16x32_bf16 v[88:91], v[156:159], v[208:211], v[88:91]
	v_mfma_f32_16x16x32_bf16 v[76:79], v[144:147], v[226:229], v[76:79]
	v_mfma_f32_16x16x32_bf16 v[72:75], v[156:159], v[226:229], v[72:75]
	v_mfma_f32_16x16x32_bf16 v[116:119], v[160:163], v[176:179], v[116:119]
	v_mfma_f32_16x16x32_bf16 v[112:115], v[168:171], v[176:179], v[112:115]
	v_mfma_f32_16x16x32_bf16 v[100:103], v[160:163], v[184:187], v[100:103]
	v_mfma_f32_16x16x32_bf16 v[96:99], v[168:171], v[184:187], v[96:99]
	v_mfma_f32_16x16x32_bf16 v[84:87], v[160:163], v[204:207], v[84:87]
	v_mfma_f32_16x16x32_bf16 v[80:83], v[168:171], v[204:207], v[80:83]
	v_mfma_f32_16x16x32_bf16 v[68:71], v[160:163], v[222:225], v[68:71]
	v_mfma_f32_16x16x32_bf16 v[64:67], v[168:171], v[222:225], v[64:67]
	v_mfma_f32_16x16x32_bf16 v[116:119], v[164:167], v[180:183], v[116:119]
	v_mfma_f32_16x16x32_bf16 v[112:115], v[172:175], v[180:183], v[112:115]
	v_mfma_f32_16x16x32_bf16 v[100:103], v[164:167], v[200:203], v[100:103]
	v_mfma_f32_16x16x32_bf16 v[96:99], v[172:175], v[200:203], v[96:99]
	v_mfma_f32_16x16x32_bf16 v[84:87], v[164:167], v[208:211], v[84:87]
	v_mfma_f32_16x16x32_bf16 v[80:83], v[172:175], v[208:211], v[80:83]
	v_mfma_f32_16x16x32_bf16 v[68:71], v[164:167], v[226:229], v[68:71]
	v_mfma_f32_16x16x32_bf16 v[64:67], v[172:175], v[226:229], v[64:67]
	s_setprio 0
	s_barrier
	s_add_i32 s24, s24, s14
	v_lshl_add_u64 v[188:189], s[10:11], 0, v[128:129]
	s_mov_b32 m0, s24
	ds_read_b128 v[176:179], v151 offset:16384
	ds_read_b128 v[180:183], v151 offset:17408
	ds_read_b128 v[184:187], v151 offset:18432
	ds_read_b128 v[200:203], v151 offset:19456
	ds_read_b128 v[204:207], v151 offset:20480
	ds_read_b128 v[208:211], v151 offset:21504
	ds_read_b128 v[222:225], v151 offset:22528
	ds_read_b128 v[226:229], v151 offset:23552
	global_load_lds_dwordx4 v[188:189], off
	s_add_i32 m0, s24, 0x2000
	s_add_u32 s94, s10, 0x80000
	v_lshl_add_u64 v[212:213], s[10:11], 0, v[130:131]
	s_addc_u32 s95, s11, 0
	s_add_i32 s24, s25, s14
	global_load_lds_dwordx4 v[212:213], off
	v_lshl_add_u64 v[230:231], s[94:95], 0, v[128:129]
	s_mov_b32 m0, s24
	v_lshl_add_u64 v[232:233], s[12:13], 0, v[132:133]
	global_load_lds_dwordx4 v[230:231], off
	v_lshl_add_u64 v[230:231], s[94:95], 0, v[130:131]
	s_add_i32 m0, s24, 0x2000
	s_nop 0
	global_load_lds_dwordx4 v[230:231], off
	v_lshl_add_u64 v[230:231], s[12:13], 0, v[134:135]
	s_mov_b32 m0, s16
	s_nop 0
	global_load_lds_dwordx4 v[230:231], off
	s_mov_b32 m0, s17
	s_nop 0
	global_load_lds_dwordx4 v[232:233], off
	s_waitcnt vmcnt(8)
	s_waitcnt lgkmcnt(0)
	s_barrier
	s_setprio 1
	s_waitcnt lgkmcnt(0)
	v_mfma_f32_16x16x32_bf16 v[60:63], v[140:143], v[176:179], v[60:63]
	v_mfma_f32_16x16x32_bf16 v[56:59], v[152:155], v[176:179], v[56:59]
	v_mfma_f32_16x16x32_bf16 v[44:47], v[140:143], v[184:187], v[44:47]
	v_mfma_f32_16x16x32_bf16 v[40:43], v[152:155], v[184:187], v[40:43]
	v_mfma_f32_16x16x32_bf16 v[28:31], v[140:143], v[204:207], v[28:31]
	v_mfma_f32_16x16x32_bf16 v[24:27], v[152:155], v[204:207], v[24:27]
	v_mfma_f32_16x16x32_bf16 v[12:15], v[140:143], v[222:225], v[12:15]
	v_mfma_f32_16x16x32_bf16 v[8:11], v[152:155], v[222:225], v[8:11]
	v_mfma_f32_16x16x32_bf16 v[60:63], v[144:147], v[180:183], v[60:63]
	v_mfma_f32_16x16x32_bf16 v[56:59], v[156:159], v[180:183], v[56:59]
	v_mfma_f32_16x16x32_bf16 v[44:47], v[144:147], v[200:203], v[44:47]
	v_mfma_f32_16x16x32_bf16 v[40:43], v[156:159], v[200:203], v[40:43]
	v_mfma_f32_16x16x32_bf16 v[28:31], v[144:147], v[208:211], v[28:31]
	v_mfma_f32_16x16x32_bf16 v[24:27], v[156:159], v[208:211], v[24:27]
	v_mfma_f32_16x16x32_bf16 v[12:15], v[144:147], v[226:229], v[12:15]
	v_mfma_f32_16x16x32_bf16 v[8:11], v[156:159], v[226:229], v[8:11]
	v_mfma_f32_16x16x32_bf16 v[52:55], v[160:163], v[176:179], v[52:55]
	v_mfma_f32_16x16x32_bf16 v[48:51], v[168:171], v[176:179], v[48:51]
	v_mfma_f32_16x16x32_bf16 v[36:39], v[160:163], v[184:187], v[36:39]
	v_mfma_f32_16x16x32_bf16 v[32:35], v[168:171], v[184:187], v[32:35]
	v_mfma_f32_16x16x32_bf16 v[20:23], v[160:163], v[204:207], v[20:23]
	v_mfma_f32_16x16x32_bf16 v[16:19], v[168:171], v[204:207], v[16:19]
	v_mfma_f32_16x16x32_bf16 v[4:7], v[160:163], v[222:225], v[4:7]
	v_mfma_f32_16x16x32_bf16 v[0:3], v[168:171], v[222:225], v[0:3]
	v_mfma_f32_16x16x32_bf16 v[52:55], v[164:167], v[180:183], v[52:55]
	v_mfma_f32_16x16x32_bf16 v[48:51], v[172:175], v[180:183], v[48:51]
	v_mfma_f32_16x16x32_bf16 v[36:39], v[164:167], v[200:203], v[36:39]
	v_mfma_f32_16x16x32_bf16 v[32:35], v[172:175], v[200:203], v[32:35]
	v_mfma_f32_16x16x32_bf16 v[20:23], v[164:167], v[208:211], v[20:23]
	v_mfma_f32_16x16x32_bf16 v[16:19], v[172:175], v[208:211], v[16:19]
	v_mfma_f32_16x16x32_bf16 v[4:7], v[164:167], v[226:229], v[4:7]
	v_mfma_f32_16x16x32_bf16 v[0:3], v[172:175], v[226:229], v[0:3]
	s_setprio 0
	s_barrier
	s_add_i32 s24, 0, 0x18000
	s_add_i32 s25, 0, 0x1c000
	v_add_u32_e32 v156, s24, v149
	v_add_u32_e32 v172, s25, v149
	ds_read_b128 v[140:143], v156
	ds_read_b128 v[144:147], v156 offset:1024
	ds_read_b128 v[152:155], v156 offset:2048
	ds_read_b128 v[156:159], v156 offset:3072
	ds_read_b128 v[160:163], v172
	ds_read_b128 v[164:167], v172 offset:1024
	ds_read_b128 v[168:171], v172 offset:2048
	ds_read_b128 v[172:175], v172 offset:3072
	s_add_u32 s12, s12, 0x80000
	s_addc_u32 s13, s13, 0
	s_mov_b32 m0, s18
	v_lshl_add_u64 v[234:235], s[12:13], 0, v[134:135]
	ds_read_b128 v[176:179], v151 offset:32768
	ds_read_b128 v[180:183], v151 offset:33792
	ds_read_b128 v[184:187], v151 offset:34816
	ds_read_b128 v[200:203], v151 offset:35840
	ds_read_b128 v[204:207], v151 offset:36864
	ds_read_b128 v[208:211], v151 offset:37888
	ds_read_b128 v[222:225], v151 offset:38912
	ds_read_b128 v[226:229], v151 offset:39936
	global_load_lds_dwordx4 v[234:235], off
	v_lshl_add_u64 v[234:235], s[12:13], 0, v[132:133]
	s_mov_b32 m0, s19
	s_nop 0
	global_load_lds_dwordx4 v[234:235], off
	s_waitcnt vmcnt(8)
	s_waitcnt lgkmcnt(0)
	s_barrier
	s_setprio 1
	s_waitcnt lgkmcnt(0)
	v_mfma_f32_16x16x32_bf16 v[124:127], v[140:143], v[176:179], v[124:127]
	v_mfma_f32_16x16x32_bf16 v[120:123], v[152:155], v[176:179], v[120:123]
	v_mfma_f32_16x16x32_bf16 v[108:111], v[140:143], v[184:187], v[108:111]
	v_mfma_f32_16x16x32_bf16 v[104:107], v[152:155], v[184:187], v[104:107]
	v_mfma_f32_16x16x32_bf16 v[92:95], v[140:143], v[204:207], v[92:95]
	v_mfma_f32_16x16x32_bf16 v[88:91], v[152:155], v[204:207], v[88:91]
	v_mfma_f32_16x16x32_bf16 v[76:79], v[140:143], v[222:225], v[76:79]
	v_mfma_f32_16x16x32_bf16 v[72:75], v[152:155], v[222:225], v[72:75]
	v_mfma_f32_16x16x32_bf16 v[124:127], v[144:147], v[180:183], v[124:127]
	v_mfma_f32_16x16x32_bf16 v[120:123], v[156:159], v[180:183], v[120:123]
	v_mfma_f32_16x16x32_bf16 v[108:111], v[144:147], v[200:203], v[108:111]
	v_mfma_f32_16x16x32_bf16 v[104:107], v[156:159], v[200:203], v[104:107]
	v_mfma_f32_16x16x32_bf16 v[92:95], v[144:147], v[208:211], v[92:95]
	v_mfma_f32_16x16x32_bf16 v[88:91], v[156:159], v[208:211], v[88:91]
	v_mfma_f32_16x16x32_bf16 v[76:79], v[144:147], v[226:229], v[76:79]
	v_mfma_f32_16x16x32_bf16 v[72:75], v[156:159], v[226:229], v[72:75]
	v_mfma_f32_16x16x32_bf16 v[116:119], v[160:163], v[176:179], v[116:119]
	v_mfma_f32_16x16x32_bf16 v[112:115], v[168:171], v[176:179], v[112:115]
	v_mfma_f32_16x16x32_bf16 v[100:103], v[160:163], v[184:187], v[100:103]
	v_mfma_f32_16x16x32_bf16 v[96:99], v[168:171], v[184:187], v[96:99]
	v_mfma_f32_16x16x32_bf16 v[84:87], v[160:163], v[204:207], v[84:87]
	v_mfma_f32_16x16x32_bf16 v[80:83], v[168:171], v[204:207], v[80:83]
	v_mfma_f32_16x16x32_bf16 v[68:71], v[160:163], v[222:225], v[68:71]
	v_mfma_f32_16x16x32_bf16 v[64:67], v[168:171], v[222:225], v[64:67]
	v_mfma_f32_16x16x32_bf16 v[116:119], v[164:167], v[180:183], v[116:119]
	v_mfma_f32_16x16x32_bf16 v[112:115], v[172:175], v[180:183], v[112:115]
	v_mfma_f32_16x16x32_bf16 v[100:103], v[164:167], v[200:203], v[100:103]
	v_mfma_f32_16x16x32_bf16 v[96:99], v[172:175], v[200:203], v[96:99]
	v_mfma_f32_16x16x32_bf16 v[84:87], v[164:167], v[208:211], v[84:87]
	v_mfma_f32_16x16x32_bf16 v[80:83], v[172:175], v[208:211], v[80:83]
	v_mfma_f32_16x16x32_bf16 v[68:71], v[164:167], v[226:229], v[68:71]
	v_mfma_f32_16x16x32_bf16 v[64:67], v[172:175], v[226:229], v[64:67]
	s_setprio 0
	s_barrier
	s_add_i32 s12, s24, s14
	v_lshl_add_u64 v[188:189], v[188:189], 0, s[26:27]
	s_mov_b32 m0, s12
	ds_read_b128 v[176:179], v151 offset:49152
	ds_read_b128 v[180:183], v151 offset:50176
	ds_read_b128 v[184:187], v151 offset:51200
	ds_read_b128 v[200:203], v151 offset:52224
	ds_read_b128 v[204:207], v151 offset:53248
	ds_read_b128 v[208:211], v151 offset:54272
	ds_read_b128 v[222:225], v151 offset:55296
	ds_read_b128 v[226:229], v151 offset:56320
	global_load_lds_dwordx4 v[188:189], off
	s_add_i32 m0, s12, 0x2000
	s_add_u32 s10, s10, 0x80080
	v_lshl_add_u64 v[188:189], v[212:213], 0, s[26:27]
	s_addc_u32 s11, s11, 0
	s_add_i32 s12, s25, s14
	global_load_lds_dwordx4 v[188:189], off
	v_lshl_add_u64 v[188:189], s[10:11], 0, v[128:129]
	s_mov_b32 m0, s12
	s_nop 0
	global_load_lds_dwordx4 v[188:189], off
	v_lshl_add_u64 v[188:189], s[10:11], 0, v[130:131]
	s_add_i32 m0, s12, 0x2000
	s_nop 0
	global_load_lds_dwordx4 v[188:189], off
	v_lshl_add_u64 v[188:189], v[230:231], 0, s[26:27]
	s_mov_b32 m0, s21
	s_nop 0
	global_load_lds_dwordx4 v[188:189], off
	v_lshl_add_u64 v[188:189], v[232:233], 0, s[26:27]
	s_mov_b32 m0, s22
	s_nop 0
	global_load_lds_dwordx4 v[188:189], off
	s_waitcnt vmcnt(8)
	s_waitcnt lgkmcnt(0)
	s_barrier
	s_setprio 1
	s_waitcnt lgkmcnt(0)
	v_mfma_f32_16x16x32_bf16 v[60:63], v[140:143], v[176:179], v[60:63]
	v_mfma_f32_16x16x32_bf16 v[56:59], v[152:155], v[176:179], v[56:59]
	v_mfma_f32_16x16x32_bf16 v[44:47], v[140:143], v[184:187], v[44:47]
	v_mfma_f32_16x16x32_bf16 v[40:43], v[152:155], v[184:187], v[40:43]
	v_mfma_f32_16x16x32_bf16 v[28:31], v[140:143], v[204:207], v[28:31]
	v_mfma_f32_16x16x32_bf16 v[24:27], v[152:155], v[204:207], v[24:27]
	v_mfma_f32_16x16x32_bf16 v[12:15], v[140:143], v[222:225], v[12:15]
	v_mfma_f32_16x16x32_bf16 v[8:11], v[152:155], v[222:225], v[8:11]
	v_mfma_f32_16x16x32_bf16 v[60:63], v[144:147], v[180:183], v[60:63]
	v_mfma_f32_16x16x32_bf16 v[56:59], v[156:159], v[180:183], v[56:59]
	v_mfma_f32_16x16x32_bf16 v[44:47], v[144:147], v[200:203], v[44:47]
	v_mfma_f32_16x16x32_bf16 v[40:43], v[156:159], v[200:203], v[40:43]
	v_mfma_f32_16x16x32_bf16 v[28:31], v[144:147], v[208:211], v[28:31]
	v_mfma_f32_16x16x32_bf16 v[24:27], v[156:159], v[208:211], v[24:27]
	v_mfma_f32_16x16x32_bf16 v[12:15], v[144:147], v[226:229], v[12:15]
	v_mfma_f32_16x16x32_bf16 v[8:11], v[156:159], v[226:229], v[8:11]
	v_mfma_f32_16x16x32_bf16 v[52:55], v[160:163], v[176:179], v[52:55]
	v_mfma_f32_16x16x32_bf16 v[48:51], v[168:171], v[176:179], v[48:51]
	v_mfma_f32_16x16x32_bf16 v[36:39], v[160:163], v[184:187], v[36:39]
	v_mfma_f32_16x16x32_bf16 v[32:35], v[168:171], v[184:187], v[32:35]
	v_mfma_f32_16x16x32_bf16 v[20:23], v[160:163], v[204:207], v[20:23]
	v_mfma_f32_16x16x32_bf16 v[16:19], v[168:171], v[204:207], v[16:19]
	v_mfma_f32_16x16x32_bf16 v[4:7], v[160:163], v[222:225], v[4:7]
	v_mfma_f32_16x16x32_bf16 v[0:3], v[168:171], v[222:225], v[0:3]
	v_mfma_f32_16x16x32_bf16 v[52:55], v[164:167], v[180:183], v[52:55]
	v_mfma_f32_16x16x32_bf16 v[48:51], v[172:175], v[180:183], v[48:51]
	v_mfma_f32_16x16x32_bf16 v[36:39], v[164:167], v[200:203], v[36:39]
	v_mfma_f32_16x16x32_bf16 v[32:35], v[172:175], v[200:203], v[32:35]
	v_mfma_f32_16x16x32_bf16 v[20:23], v[164:167], v[208:211], v[20:23]
	v_mfma_f32_16x16x32_bf16 v[16:19], v[172:175], v[208:211], v[16:19]
	v_mfma_f32_16x16x32_bf16 v[4:7], v[164:167], v[226:229], v[4:7]
	v_mfma_f32_16x16x32_bf16 v[0:3], v[172:175], v[226:229], v[0:3]
	s_setprio 0
	s_barrier
	s_add_i32 s84, s84, 2
	s_add_u32 s8, s8, 0x100
	s_addc_u32 s9, s9, 0
	s_add_u32 s74, s74, 0x100
	s_addc_u32 s75, s75, 0
	s_cmp_gt_u32 s84, 29
	s_cbranch_scc0 .LBB0_838
	s_nop 0
	s_nop 0
	s_nop 0
	s_nop 0
	s_nop 0
	s_nop 0
	s_nop 0
	s_nop 0
	s_and_b64 vcc, exec, s[42:43]
	s_cbranch_vccz .LBB0_841
	s_barrier

.LBB0_962:
	s_add_u32 s10, vcc_lo, 0xfff80080
	s_addc_u32 s11, vcc_hi, -1
	s_add_i32 s24, 0, 0x10000
	s_cmp_eq_u32 s85, 4
	s_cselect_b32 s39, s75, s11
	s_cselect_b32 s38, s91, s10
	s_cselect_b32 s11, s89, s84
	s_cselect_b32 s10, s94, s95
	s_add_i32 s83, 0, 0x14000
	v_add_u32_e32 v156, s24, v141
	v_add_u32_e32 v172, s83, v141
	ds_read_b128 v[144:147], v156
	ds_read_b128 v[148:151], v156 offset:1024
	ds_read_b128 v[152:155], v156 offset:2048
	ds_read_b128 v[156:159], v156 offset:3072
	ds_read_b128 v[160:163], v172
	ds_read_b128 v[164:167], v172 offset:1024
	ds_read_b128 v[168:171], v172 offset:2048
	ds_read_b128 v[172:175], v172 offset:3072
	v_lshl_add_u64 v[188:189], vcc, 0, v[136:137]
	s_add_i32 m0, s20, 0xc000
	ds_read_b128 v[176:179], v143
	ds_read_b128 v[180:183], v143 offset:1024
	ds_read_b128 v[184:187], v143 offset:2048
	ds_read_b128 v[200:203], v143 offset:3072
	ds_read_b128 v[204:207], v143 offset:4096
	ds_read_b128 v[208:211], v143 offset:5120
	ds_read_b128 v[222:225], v143 offset:6144
	ds_read_b128 v[226:229], v143 offset:7168
	global_load_lds_dwordx4 v[188:189], off
	v_lshl_add_u64 v[188:189], vcc, 0, v[138:139]
	s_add_i32 m0, s20, 0xe000
	s_nop 0
	global_load_lds_dwordx4 v[188:189], off
	s_waitcnt vmcnt(8)
	s_waitcnt lgkmcnt(0)
	s_barrier
	s_setprio 1
	s_waitcnt lgkmcnt(0)
	v_mfma_f32_16x16x32_bf16 v[124:127], v[144:147], v[176:179], v[124:127]
	v_mfma_f32_16x16x32_bf16 v[120:123], v[152:155], v[176:179], v[120:123]
	v_mfma_f32_16x16x32_bf16 v[116:119], v[144:147], v[184:187], v[116:119]
	v_mfma_f32_16x16x32_bf16 v[112:115], v[152:155], v[184:187], v[112:115]
	v_mfma_f32_16x16x32_bf16 v[100:103], v[144:147], v[204:207], v[100:103]
	v_mfma_f32_16x16x32_bf16 v[96:99], v[152:155], v[204:207], v[96:99]
	v_mfma_f32_16x16x32_bf16 v[84:87], v[144:147], v[222:225], v[84:87]
	v_mfma_f32_16x16x32_bf16 v[80:83], v[152:155], v[222:225], v[80:83]
	v_mfma_f32_16x16x32_bf16 v[124:127], v[148:151], v[180:183], v[124:127]
	v_mfma_f32_16x16x32_bf16 v[120:123], v[156:159], v[180:183], v[120:123]
	v_mfma_f32_16x16x32_bf16 v[116:119], v[148:151], v[200:203], v[116:119]
	v_mfma_f32_16x16x32_bf16 v[112:115], v[156:159], v[200:203], v[112:115]
	v_mfma_f32_16x16x32_bf16 v[100:103], v[148:151], v[208:211], v[100:103]
	v_mfma_f32_16x16x32_bf16 v[96:99], v[156:159], v[208:211], v[96:99]
	v_mfma_f32_16x16x32_bf16 v[84:87], v[148:151], v[226:229], v[84:87]
	v_mfma_f32_16x16x32_bf16 v[80:83], v[156:159], v[226:229], v[80:83]
	v_mfma_f32_16x16x32_bf16 v[108:111], v[160:163], v[176:179], v[108:111]
	v_mfma_f32_16x16x32_bf16 v[104:107], v[168:171], v[176:179], v[104:107]
	v_mfma_f32_16x16x32_bf16 v[92:95], v[160:163], v[184:187], v[92:95]
	v_mfma_f32_16x16x32_bf16 v[88:91], v[168:171], v[184:187], v[88:91]
	v_mfma_f32_16x16x32_bf16 v[76:79], v[160:163], v[204:207], v[76:79]
	v_mfma_f32_16x16x32_bf16 v[72:75], v[168:171], v[204:207], v[72:75]
	v_mfma_f32_16x16x32_bf16 v[68:71], v[160:163], v[222:225], v[68:71]
	v_mfma_f32_16x16x32_bf16 v[64:67], v[168:171], v[222:225], v[64:67]
	v_mfma_f32_16x16x32_bf16 v[108:111], v[164:167], v[180:183], v[108:111]
	v_mfma_f32_16x16x32_bf16 v[104:107], v[172:175], v[180:183], v[104:107]
	v_mfma_f32_16x16x32_bf16 v[92:95], v[164:167], v[200:203], v[92:95]
	v_mfma_f32_16x16x32_bf16 v[88:91], v[172:175], v[200:203], v[88:91]
	v_mfma_f32_16x16x32_bf16 v[76:79], v[164:167], v[208:211], v[76:79]
	v_mfma_f32_16x16x32_bf16 v[72:75], v[172:175], v[208:211], v[72:75]
	v_mfma_f32_16x16x32_bf16 v[68:71], v[164:167], v[226:229], v[68:71]
	v_mfma_f32_16x16x32_bf16 v[64:67], v[172:175], v[226:229], v[64:67]
	s_setprio 0
	s_barrier
	s_add_i32 s24, s24, s19
	v_lshl_add_u64 v[188:189], s[10:11], 0, v[128:129]
	s_mov_b32 m0, s24
	ds_read_b128 v[176:179], v143 offset:16384
	ds_read_b128 v[180:183], v143 offset:17408
	ds_read_b128 v[184:187], v143 offset:18432
	ds_read_b128 v[200:203], v143 offset:19456
	ds_read_b128 v[204:207], v143 offset:20480
	ds_read_b128 v[208:211], v143 offset:21504
	ds_read_b128 v[222:225], v143 offset:22528
	ds_read_b128 v[226:229], v143 offset:23552
	global_load_lds_dwordx4 v[188:189], off
	s_add_i32 m0, s24, 0x2000
	s_add_u32 s24, s10, 0x20000
	v_lshl_add_u64 v[212:213], s[10:11], 0, v[134:135]
	s_addc_u32 s25, s11, 0
	s_add_i32 s83, s83, s19
	global_load_lds_dwordx4 v[212:213], off
	v_lshl_add_u64 v[230:231], s[24:25], 0, v[128:129]
	s_mov_b32 m0, s83
	v_lshl_add_u64 v[232:233], s[38:39], 0, v[132:133]
	global_load_lds_dwordx4 v[230:231], off
	v_lshl_add_u64 v[230:231], s[24:25], 0, v[134:135]
	s_add_i32 m0, s83, 0x2000
	s_nop 0
	global_load_lds_dwordx4 v[230:231], off
	v_lshl_add_u64 v[230:231], s[38:39], 0, v[130:131]
	s_mov_b32 m0, s20
	s_nop 0
	global_load_lds_dwordx4 v[230:231], off
	s_mov_b32 m0, s21
	s_nop 0
	global_load_lds_dwordx4 v[232:233], off
	s_waitcnt vmcnt(8)
	s_waitcnt lgkmcnt(0)
	s_barrier
	s_setprio 1
	s_waitcnt lgkmcnt(0)
	v_mfma_f32_16x16x32_bf16 v[60:63], v[144:147], v[176:179], v[60:63]
	v_mfma_f32_16x16x32_bf16 v[56:59], v[152:155], v[176:179], v[56:59]
	v_mfma_f32_16x16x32_bf16 v[52:55], v[144:147], v[184:187], v[52:55]
	v_mfma_f32_16x16x32_bf16 v[48:51], v[152:155], v[184:187], v[48:51]
	v_mfma_f32_16x16x32_bf16 v[36:39], v[144:147], v[204:207], v[36:39]
	v_mfma_f32_16x16x32_bf16 v[32:35], v[152:155], v[204:207], v[32:35]
	v_mfma_f32_16x16x32_bf16 v[20:23], v[144:147], v[222:225], v[20:23]
	v_mfma_f32_16x16x32_bf16 v[16:19], v[152:155], v[222:225], v[16:19]
	v_mfma_f32_16x16x32_bf16 v[60:63], v[148:151], v[180:183], v[60:63]
	v_mfma_f32_16x16x32_bf16 v[56:59], v[156:159], v[180:183], v[56:59]
	v_mfma_f32_16x16x32_bf16 v[52:55], v[148:151], v[200:203], v[52:55]
	v_mfma_f32_16x16x32_bf16 v[48:51], v[156:159], v[200:203], v[48:51]
	v_mfma_f32_16x16x32_bf16 v[36:39], v[148:151], v[208:211], v[36:39]
	v_mfma_f32_16x16x32_bf16 v[32:35], v[156:159], v[208:211], v[32:35]
	v_mfma_f32_16x16x32_bf16 v[20:23], v[148:151], v[226:229], v[20:23]
	v_mfma_f32_16x16x32_bf16 v[16:19], v[156:159], v[226:229], v[16:19]
	v_mfma_f32_16x16x32_bf16 v[44:47], v[160:163], v[176:179], v[44:47]
	v_mfma_f32_16x16x32_bf16 v[40:43], v[168:171], v[176:179], v[40:43]
	v_mfma_f32_16x16x32_bf16 v[28:31], v[160:163], v[184:187], v[28:31]
	v_mfma_f32_16x16x32_bf16 v[24:27], v[168:171], v[184:187], v[24:27]
	v_mfma_f32_16x16x32_bf16 v[12:15], v[160:163], v[204:207], v[12:15]
	v_mfma_f32_16x16x32_bf16 v[8:11], v[168:171], v[204:207], v[8:11]
	v_mfma_f32_16x16x32_bf16 v[4:7], v[160:163], v[222:225], v[4:7]
	v_mfma_f32_16x16x32_bf16 v[0:3], v[168:171], v[222:225], v[0:3]
	v_mfma_f32_16x16x32_bf16 v[44:47], v[164:167], v[180:183], v[44:47]
	v_mfma_f32_16x16x32_bf16 v[40:43], v[172:175], v[180:183], v[40:43]
	v_mfma_f32_16x16x32_bf16 v[28:31], v[164:167], v[200:203], v[28:31]
	v_mfma_f32_16x16x32_bf16 v[24:27], v[172:175], v[200:203], v[24:27]
	v_mfma_f32_16x16x32_bf16 v[12:15], v[164:167], v[208:211], v[12:15]
	v_mfma_f32_16x16x32_bf16 v[8:11], v[172:175], v[208:211], v[8:11]
	v_mfma_f32_16x16x32_bf16 v[4:7], v[164:167], v[226:229], v[4:7]
	v_mfma_f32_16x16x32_bf16 v[0:3], v[172:175], v[226:229], v[0:3]
	s_setprio 0
	s_barrier
	s_add_i32 s83, 0, 0x18000
	s_add_i32 s28, 0, 0x1c000
	v_add_u32_e32 v156, s83, v141
	v_add_u32_e32 v172, s28, v141
	ds_read_b128 v[144:147], v156
	ds_read_b128 v[148:151], v156 offset:1024
	ds_read_b128 v[152:155], v156 offset:2048
	ds_read_b128 v[156:159], v156 offset:3072
	ds_read_b128 v[160:163], v172
	ds_read_b128 v[164:167], v172 offset:1024
	ds_read_b128 v[168:171], v172 offset:2048
	ds_read_b128 v[172:175], v172 offset:3072
	s_add_u32 s24, s38, 0x80000
	s_addc_u32 s25, s39, 0
	s_mov_b32 m0, s22
	v_lshl_add_u64 v[234:235], s[24:25], 0, v[130:131]
	ds_read_b128 v[176:179], v143 offset:32768
	ds_read_b128 v[180:183], v143 offset:33792
	ds_read_b128 v[184:187], v143 offset:34816
	ds_read_b128 v[200:203], v143 offset:35840
	ds_read_b128 v[204:207], v143 offset:36864
	ds_read_b128 v[208:211], v143 offset:37888
	ds_read_b128 v[222:225], v143 offset:38912
	ds_read_b128 v[226:229], v143 offset:39936
	global_load_lds_dwordx4 v[234:235], off
	v_lshl_add_u64 v[234:235], s[24:25], 0, v[132:133]
	s_mov_b32 m0, s33
	s_nop 0
	global_load_lds_dwordx4 v[234:235], off
	s_waitcnt vmcnt(8)
	s_waitcnt lgkmcnt(0)
	s_barrier
	s_setprio 1
	s_waitcnt lgkmcnt(0)
	v_mfma_f32_16x16x32_bf16 v[124:127], v[144:147], v[176:179], v[124:127]
	v_mfma_f32_16x16x32_bf16 v[120:123], v[152:155], v[176:179], v[120:123]
	v_mfma_f32_16x16x32_bf16 v[116:119], v[144:147], v[184:187], v[116:119]
	v_mfma_f32_16x16x32_bf16 v[112:115], v[152:155], v[184:187], v[112:115]
	v_mfma_f32_16x16x32_bf16 v[100:103], v[144:147], v[204:207], v[100:103]
	v_mfma_f32_16x16x32_bf16 v[96:99], v[152:155], v[204:207], v[96:99]
	v_mfma_f32_16x16x32_bf16 v[84:87], v[144:147], v[222:225], v[84:87]
	v_mfma_f32_16x16x32_bf16 v[80:83], v[152:155], v[222:225], v[80:83]
	v_mfma_f32_16x16x32_bf16 v[124:127], v[148:151], v[180:183], v[124:127]
	v_mfma_f32_16x16x32_bf16 v[120:123], v[156:159], v[180:183], v[120:123]
	v_mfma_f32_16x16x32_bf16 v[116:119], v[148:151], v[200:203], v[116:119]
	v_mfma_f32_16x16x32_bf16 v[112:115], v[156:159], v[200:203], v[112:115]
	v_mfma_f32_16x16x32_bf16 v[100:103], v[148:151], v[208:211], v[100:103]
	v_mfma_f32_16x16x32_bf16 v[96:99], v[156:159], v[208:211], v[96:99]
	v_mfma_f32_16x16x32_bf16 v[84:87], v[148:151], v[226:229], v[84:87]
	v_mfma_f32_16x16x32_bf16 v[80:83], v[156:159], v[226:229], v[80:83]
	v_mfma_f32_16x16x32_bf16 v[108:111], v[160:163], v[176:179], v[108:111]
	v_mfma_f32_16x16x32_bf16 v[104:107], v[168:171], v[176:179], v[104:107]
	v_mfma_f32_16x16x32_bf16 v[92:95], v[160:163], v[184:187], v[92:95]
	v_mfma_f32_16x16x32_bf16 v[88:91], v[168:171], v[184:187], v[88:91]
	v_mfma_f32_16x16x32_bf16 v[76:79], v[160:163], v[204:207], v[76:79]
	v_mfma_f32_16x16x32_bf16 v[72:75], v[168:171], v[204:207], v[72:75]
	v_mfma_f32_16x16x32_bf16 v[68:71], v[160:163], v[222:225], v[68:71]
	v_mfma_f32_16x16x32_bf16 v[64:67], v[168:171], v[222:225], v[64:67]
	v_mfma_f32_16x16x32_bf16 v[108:111], v[164:167], v[180:183], v[108:111]
	v_mfma_f32_16x16x32_bf16 v[104:107], v[172:175], v[180:183], v[104:107]
	v_mfma_f32_16x16x32_bf16 v[92:95], v[164:167], v[200:203], v[92:95]
	v_mfma_f32_16x16x32_bf16 v[88:91], v[172:175], v[200:203], v[88:91]
	v_mfma_f32_16x16x32_bf16 v[76:79], v[164:167], v[208:211], v[76:79]
	v_mfma_f32_16x16x32_bf16 v[72:75], v[172:175], v[208:211], v[72:75]
	v_mfma_f32_16x16x32_bf16 v[68:71], v[164:167], v[226:229], v[68:71]
	v_mfma_f32_16x16x32_bf16 v[64:67], v[172:175], v[226:229], v[64:67]
	s_setprio 0
	s_barrier
	s_add_i32 s24, s83, s19
	v_lshl_add_u64 v[188:189], v[188:189], 0, s[26:27]
	s_mov_b32 m0, s24
	ds_read_b128 v[176:179], v143 offset:49152
	ds_read_b128 v[180:183], v143 offset:50176
	ds_read_b128 v[184:187], v143 offset:51200
	ds_read_b128 v[200:203], v143 offset:52224
	ds_read_b128 v[204:207], v143 offset:53248
	ds_read_b128 v[208:211], v143 offset:54272
	ds_read_b128 v[222:225], v143 offset:55296
	ds_read_b128 v[226:229], v143 offset:56320
	global_load_lds_dwordx4 v[188:189], off
	s_add_i32 m0, s24, 0x2000
	s_add_u32 s10, s10, 0x20080
	v_lshl_add_u64 v[188:189], v[212:213], 0, s[26:27]
	s_addc_u32 s11, s11, 0
	s_add_i32 s24, s28, s19
	global_load_lds_dwordx4 v[188:189], off
	v_lshl_add_u64 v[188:189], s[10:11], 0, v[128:129]
	s_mov_b32 m0, s24
	s_nop 0
	global_load_lds_dwordx4 v[188:189], off
	v_lshl_add_u64 v[188:189], s[10:11], 0, v[134:135]
	s_add_i32 m0, s24, 0x2000
	s_nop 0
	global_load_lds_dwordx4 v[188:189], off
	v_lshl_add_u64 v[188:189], v[230:231], 0, s[26:27]
	s_mov_b32 m0, s45
	s_nop 0
	global_load_lds_dwordx4 v[188:189], off
	v_lshl_add_u64 v[188:189], v[232:233], 0, s[26:27]
	s_mov_b32 m0, s72
	s_nop 0
	global_load_lds_dwordx4 v[188:189], off
	s_waitcnt vmcnt(8)
	s_waitcnt lgkmcnt(0)
	s_barrier
	s_setprio 1
	s_waitcnt lgkmcnt(0)
	v_mfma_f32_16x16x32_bf16 v[60:63], v[144:147], v[176:179], v[60:63]
	v_mfma_f32_16x16x32_bf16 v[56:59], v[152:155], v[176:179], v[56:59]
	v_mfma_f32_16x16x32_bf16 v[52:55], v[144:147], v[184:187], v[52:55]
	v_mfma_f32_16x16x32_bf16 v[48:51], v[152:155], v[184:187], v[48:51]
	v_mfma_f32_16x16x32_bf16 v[36:39], v[144:147], v[204:207], v[36:39]
	v_mfma_f32_16x16x32_bf16 v[32:35], v[152:155], v[204:207], v[32:35]
	v_mfma_f32_16x16x32_bf16 v[20:23], v[144:147], v[222:225], v[20:23]
	v_mfma_f32_16x16x32_bf16 v[16:19], v[152:155], v[222:225], v[16:19]
	v_mfma_f32_16x16x32_bf16 v[60:63], v[148:151], v[180:183], v[60:63]
	v_mfma_f32_16x16x32_bf16 v[56:59], v[156:159], v[180:183], v[56:59]
	v_mfma_f32_16x16x32_bf16 v[52:55], v[148:151], v[200:203], v[52:55]
	v_mfma_f32_16x16x32_bf16 v[48:51], v[156:159], v[200:203], v[48:51]
	v_mfma_f32_16x16x32_bf16 v[36:39], v[148:151], v[208:211], v[36:39]
	v_mfma_f32_16x16x32_bf16 v[32:35], v[156:159], v[208:211], v[32:35]
	v_mfma_f32_16x16x32_bf16 v[20:23], v[148:151], v[226:229], v[20:23]
	v_mfma_f32_16x16x32_bf16 v[16:19], v[156:159], v[226:229], v[16:19]
	v_mfma_f32_16x16x32_bf16 v[44:47], v[160:163], v[176:179], v[44:47]
	v_mfma_f32_16x16x32_bf16 v[40:43], v[168:171], v[176:179], v[40:43]
	v_mfma_f32_16x16x32_bf16 v[28:31], v[160:163], v[184:187], v[28:31]
	v_mfma_f32_16x16x32_bf16 v[24:27], v[168:171], v[184:187], v[24:27]
	v_mfma_f32_16x16x32_bf16 v[12:15], v[160:163], v[204:207], v[12:15]
	v_mfma_f32_16x16x32_bf16 v[8:11], v[168:171], v[204:207], v[8:11]
	v_mfma_f32_16x16x32_bf16 v[4:7], v[160:163], v[222:225], v[4:7]
	v_mfma_f32_16x16x32_bf16 v[0:3], v[168:171], v[222:225], v[0:3]
	v_mfma_f32_16x16x32_bf16 v[44:47], v[164:167], v[180:183], v[44:47]
	v_mfma_f32_16x16x32_bf16 v[40:43], v[172:175], v[180:183], v[40:43]
	v_mfma_f32_16x16x32_bf16 v[28:31], v[164:167], v[200:203], v[28:31]
	v_mfma_f32_16x16x32_bf16 v[24:27], v[172:175], v[200:203], v[24:27]
	v_mfma_f32_16x16x32_bf16 v[12:15], v[164:167], v[208:211], v[12:15]
	v_mfma_f32_16x16x32_bf16 v[8:11], v[172:175], v[208:211], v[8:11]
	v_mfma_f32_16x16x32_bf16 v[4:7], v[164:167], v[226:229], v[4:7]
	v_mfma_f32_16x16x32_bf16 v[0:3], v[172:175], v[226:229], v[0:3]
	s_setprio 0
	s_barrier
	s_add_i32 s85, s85, 2
	s_add_u32 vcc_lo, vcc_lo, 0x100
	s_addc_u32 vcc_hi, vcc_hi, 0
	s_add_u32 s95, s95, 0x100
	s_addc_u32 s84, s84, 0
	s_cmp_gt_u32 s85, 5
	s_cbranch_scc0 .LBB0_962
	s_nop 0
	s_nop 0
	s_nop 0
	s_nop 0
	s_nop 0
	s_nop 0
	s_nop 0
	s_nop 0
	v_readlane_b32 s94, v236, 14
	s_and_b64 vcc, exec, s[42:43]
	v_readlane_b32 s95, v236, 15
	s_cbranch_vccz .LBB0_965
	s_barrier

.LBB0_1038:
	s_add_u32 s10, s8, 0xfff80080
	s_addc_u32 s11, s9, -1
	s_add_i32 s24, 0, 0x10000
	s_cmp_eq_u32 s85, 28
	s_cselect_b32 s13, s47, s11
	s_cselect_b32 s12, s73, s10
	s_cselect_b32 s11, s45, s84
	s_cselect_b32 s10, s74, s75
	s_add_i32 s28, 0, 0x14000
	v_add_u32_e32 v116, s24, v223
	v_add_u32_e32 v154, s28, v223
	ds_read_b128 v[88:91], v116
	ds_read_b128 v[96:99], v116 offset:1024
	ds_read_b128 v[104:107], v116 offset:2048
	ds_read_b128 v[116:119], v116 offset:3072
	ds_read_b128 v[130:133], v154
	ds_read_b128 v[138:141], v154 offset:1024
	ds_read_b128 v[146:149], v154 offset:2048
	ds_read_b128 v[154:157], v154 offset:3072
	v_lshl_add_u64 v[226:227], s[8:9], 0, v[206:207]
	s_add_i32 m0, s16, 0xc000
	ds_read_b128 v[162:165], v225
	ds_read_b128 v[166:169], v225 offset:1024
	ds_read_b128 v[170:173], v225 offset:2048
	ds_read_b128 v[174:177], v225 offset:3072
	ds_read_b128 v[178:181], v225 offset:4096
	ds_read_b128 v[182:185], v225 offset:5120
	ds_read_b128 v[186:189], v225 offset:6144
	ds_read_b128 v[210:213], v225 offset:7168
	global_load_lds_dwordx4 v[226:227], off
	v_lshl_add_u64 v[226:227], s[8:9], 0, v[208:209]
	s_add_i32 m0, s16, 0xe000
	s_nop 0
	global_load_lds_dwordx4 v[226:227], off
	s_waitcnt vmcnt(8)
	s_waitcnt lgkmcnt(0)
	s_barrier
	s_setprio 1
	s_waitcnt lgkmcnt(0)
	v_mfma_f32_16x16x32_bf16 v[158:161], v[88:91], v[162:165], v[158:161]
	v_mfma_f32_16x16x32_bf16 v[150:153], v[104:107], v[162:165], v[150:153]
	v_mfma_f32_16x16x32_bf16 v[124:127], v[88:91], v[170:173], v[124:127]
	v_mfma_f32_16x16x32_bf16 v[120:123], v[104:107], v[170:173], v[120:123]
	v_mfma_f32_16x16x32_bf16 v[100:103], v[88:91], v[178:181], v[100:103]
	v_mfma_f32_16x16x32_bf16 v[92:95], v[104:107], v[178:181], v[92:95]
	v_mfma_f32_16x16x32_bf16 v[76:79], v[88:91], v[186:189], v[76:79]
	v_mfma_f32_16x16x32_bf16 v[72:75], v[104:107], v[186:189], v[72:75]
	v_mfma_f32_16x16x32_bf16 v[158:161], v[96:99], v[166:169], v[158:161]
	v_mfma_f32_16x16x32_bf16 v[150:153], v[116:119], v[166:169], v[150:153]
	v_mfma_f32_16x16x32_bf16 v[124:127], v[96:99], v[174:177], v[124:127]
	v_mfma_f32_16x16x32_bf16 v[120:123], v[116:119], v[174:177], v[120:123]
	v_mfma_f32_16x16x32_bf16 v[100:103], v[96:99], v[182:185], v[100:103]
	v_mfma_f32_16x16x32_bf16 v[92:95], v[116:119], v[182:185], v[92:95]
	v_mfma_f32_16x16x32_bf16 v[76:79], v[96:99], v[210:213], v[76:79]
	v_mfma_f32_16x16x32_bf16 v[72:75], v[116:119], v[210:213], v[72:75]
	v_mfma_f32_16x16x32_bf16 v[142:145], v[130:133], v[162:165], v[142:145]
	v_mfma_f32_16x16x32_bf16 v[134:137], v[146:149], v[162:165], v[134:137]
	v_mfma_f32_16x16x32_bf16 v[112:115], v[130:133], v[170:173], v[112:115]
	v_mfma_f32_16x16x32_bf16 v[108:111], v[146:149], v[170:173], v[108:111]
	v_mfma_f32_16x16x32_bf16 v[84:87], v[130:133], v[178:181], v[84:87]
	v_mfma_f32_16x16x32_bf16 v[80:83], v[146:149], v[178:181], v[80:83]
	v_mfma_f32_16x16x32_bf16 v[68:71], v[130:133], v[186:189], v[68:71]
	v_mfma_f32_16x16x32_bf16 v[64:67], v[146:149], v[186:189], v[64:67]
	v_mfma_f32_16x16x32_bf16 v[142:145], v[138:141], v[166:169], v[142:145]
	v_mfma_f32_16x16x32_bf16 v[134:137], v[154:157], v[166:169], v[134:137]
	v_mfma_f32_16x16x32_bf16 v[112:115], v[138:141], v[174:177], v[112:115]
	v_mfma_f32_16x16x32_bf16 v[108:111], v[154:157], v[174:177], v[108:111]
	v_mfma_f32_16x16x32_bf16 v[84:87], v[138:141], v[182:185], v[84:87]
	v_mfma_f32_16x16x32_bf16 v[80:83], v[154:157], v[182:185], v[80:83]
	v_mfma_f32_16x16x32_bf16 v[68:71], v[138:141], v[210:213], v[68:71]
	v_mfma_f32_16x16x32_bf16 v[64:67], v[154:157], v[210:213], v[64:67]
	s_setprio 0
	s_barrier
	s_add_i32 s24, s24, s14
	v_lshl_add_u64 v[226:227], s[10:11], 0, v[128:129]
	s_mov_b32 m0, s24
	ds_read_b128 v[162:165], v225 offset:16384
	ds_read_b128 v[166:169], v225 offset:17408
	ds_read_b128 v[170:173], v225 offset:18432
	ds_read_b128 v[174:177], v225 offset:19456
	ds_read_b128 v[178:181], v225 offset:20480
	ds_read_b128 v[182:185], v225 offset:21504
	ds_read_b128 v[186:189], v225 offset:22528
	ds_read_b128 v[210:213], v225 offset:23552
	global_load_lds_dwordx4 v[226:227], off
	s_add_i32 m0, s24, 0x2000
	s_add_u32 s24, s10, 0x80000
	v_lshl_add_u64 v[228:229], s[10:11], 0, v[200:201]
	s_addc_u32 s25, s11, 0
	s_add_i32 s28, s28, s14
	global_load_lds_dwordx4 v[228:229], off
	v_lshl_add_u64 v[230:231], s[24:25], 0, v[128:129]
	s_mov_b32 m0, s28
	v_lshl_add_u64 v[232:233], s[12:13], 0, v[202:203]
	global_load_lds_dwordx4 v[230:231], off
	v_lshl_add_u64 v[230:231], s[24:25], 0, v[200:201]
	s_add_i32 m0, s28, 0x2000
	s_nop 0
	global_load_lds_dwordx4 v[230:231], off
	v_lshl_add_u64 v[230:231], s[12:13], 0, v[204:205]
	s_mov_b32 m0, s16
	s_nop 0
	global_load_lds_dwordx4 v[230:231], off
	s_mov_b32 m0, s17
	s_nop 0
	global_load_lds_dwordx4 v[232:233], off
	s_waitcnt vmcnt(8)
	s_waitcnt lgkmcnt(0)
	s_barrier
	s_setprio 1
	s_waitcnt lgkmcnt(0)
	v_mfma_f32_16x16x32_bf16 v[60:63], v[88:91], v[162:165], v[60:63]
	v_mfma_f32_16x16x32_bf16 v[56:59], v[104:107], v[162:165], v[56:59]
	v_mfma_f32_16x16x32_bf16 v[44:47], v[88:91], v[170:173], v[44:47]
	v_mfma_f32_16x16x32_bf16 v[40:43], v[104:107], v[170:173], v[40:43]
	v_mfma_f32_16x16x32_bf16 v[28:31], v[88:91], v[178:181], v[28:31]
	v_mfma_f32_16x16x32_bf16 v[24:27], v[104:107], v[178:181], v[24:27]
	v_mfma_f32_16x16x32_bf16 v[12:15], v[88:91], v[186:189], v[12:15]
	v_mfma_f32_16x16x32_bf16 v[8:11], v[104:107], v[186:189], v[8:11]
	v_mfma_f32_16x16x32_bf16 v[60:63], v[96:99], v[166:169], v[60:63]
	v_mfma_f32_16x16x32_bf16 v[56:59], v[116:119], v[166:169], v[56:59]
	v_mfma_f32_16x16x32_bf16 v[44:47], v[96:99], v[174:177], v[44:47]
	v_mfma_f32_16x16x32_bf16 v[40:43], v[116:119], v[174:177], v[40:43]
	v_mfma_f32_16x16x32_bf16 v[28:31], v[96:99], v[182:185], v[28:31]
	v_mfma_f32_16x16x32_bf16 v[24:27], v[116:119], v[182:185], v[24:27]
	v_mfma_f32_16x16x32_bf16 v[12:15], v[96:99], v[210:213], v[12:15]
	v_mfma_f32_16x16x32_bf16 v[8:11], v[116:119], v[210:213], v[8:11]
	v_mfma_f32_16x16x32_bf16 v[52:55], v[130:133], v[162:165], v[52:55]
	v_mfma_f32_16x16x32_bf16 v[48:51], v[146:149], v[162:165], v[48:51]
	v_mfma_f32_16x16x32_bf16 v[36:39], v[130:133], v[170:173], v[36:39]
	v_mfma_f32_16x16x32_bf16 v[32:35], v[146:149], v[170:173], v[32:35]
	v_mfma_f32_16x16x32_bf16 v[20:23], v[130:133], v[178:181], v[20:23]
	v_mfma_f32_16x16x32_bf16 v[16:19], v[146:149], v[178:181], v[16:19]
	v_mfma_f32_16x16x32_bf16 v[4:7], v[130:133], v[186:189], v[4:7]
	v_mfma_f32_16x16x32_bf16 v[0:3], v[146:149], v[186:189], v[0:3]
	v_mfma_f32_16x16x32_bf16 v[52:55], v[138:141], v[166:169], v[52:55]
	v_mfma_f32_16x16x32_bf16 v[48:51], v[154:157], v[166:169], v[48:51]
	v_mfma_f32_16x16x32_bf16 v[36:39], v[138:141], v[174:177], v[36:39]
	v_mfma_f32_16x16x32_bf16 v[32:35], v[154:157], v[174:177], v[32:35]
	v_mfma_f32_16x16x32_bf16 v[20:23], v[138:141], v[182:185], v[20:23]
	v_mfma_f32_16x16x32_bf16 v[16:19], v[154:157], v[182:185], v[16:19]
	v_mfma_f32_16x16x32_bf16 v[4:7], v[138:141], v[210:213], v[4:7]
	v_mfma_f32_16x16x32_bf16 v[0:3], v[154:157], v[210:213], v[0:3]
	s_setprio 0
	s_barrier
	s_add_i32 s24, 0, 0x18000
	s_add_i32 s25, 0, 0x1c000
	v_add_u32_e32 v116, s24, v223
	v_add_u32_e32 v154, s25, v223
	ds_read_b128 v[88:91], v116
	ds_read_b128 v[96:99], v116 offset:1024
	ds_read_b128 v[104:107], v116 offset:2048
	ds_read_b128 v[116:119], v116 offset:3072
	ds_read_b128 v[130:133], v154
	ds_read_b128 v[138:141], v154 offset:1024
	ds_read_b128 v[146:149], v154 offset:2048
	ds_read_b128 v[154:157], v154 offset:3072
	s_add_u32 s12, s12, 0x80000
	s_addc_u32 s13, s13, 0
	s_mov_b32 m0, s18
	v_lshl_add_u64 v[234:235], s[12:13], 0, v[204:205]
	ds_read_b128 v[162:165], v225 offset:32768
	ds_read_b128 v[166:169], v225 offset:33792
	ds_read_b128 v[170:173], v225 offset:34816
	ds_read_b128 v[174:177], v225 offset:35840
	ds_read_b128 v[178:181], v225 offset:36864
	ds_read_b128 v[182:185], v225 offset:37888
	ds_read_b128 v[186:189], v225 offset:38912
	ds_read_b128 v[210:213], v225 offset:39936
	global_load_lds_dwordx4 v[234:235], off
	v_lshl_add_u64 v[234:235], s[12:13], 0, v[202:203]
	s_mov_b32 m0, s19
	s_nop 0
	global_load_lds_dwordx4 v[234:235], off
	s_waitcnt vmcnt(8)
	s_waitcnt lgkmcnt(0)
	s_barrier
	s_setprio 1
	s_waitcnt lgkmcnt(0)
	v_mfma_f32_16x16x32_bf16 v[158:161], v[88:91], v[162:165], v[158:161]
	v_mfma_f32_16x16x32_bf16 v[150:153], v[104:107], v[162:165], v[150:153]
	v_mfma_f32_16x16x32_bf16 v[124:127], v[88:91], v[170:173], v[124:127]
	v_mfma_f32_16x16x32_bf16 v[120:123], v[104:107], v[170:173], v[120:123]
	v_mfma_f32_16x16x32_bf16 v[100:103], v[88:91], v[178:181], v[100:103]
	v_mfma_f32_16x16x32_bf16 v[92:95], v[104:107], v[178:181], v[92:95]
	v_mfma_f32_16x16x32_bf16 v[76:79], v[88:91], v[186:189], v[76:79]
	v_mfma_f32_16x16x32_bf16 v[72:75], v[104:107], v[186:189], v[72:75]
	v_mfma_f32_16x16x32_bf16 v[158:161], v[96:99], v[166:169], v[158:161]
	v_mfma_f32_16x16x32_bf16 v[150:153], v[116:119], v[166:169], v[150:153]
	v_mfma_f32_16x16x32_bf16 v[124:127], v[96:99], v[174:177], v[124:127]
	v_mfma_f32_16x16x32_bf16 v[120:123], v[116:119], v[174:177], v[120:123]
	v_mfma_f32_16x16x32_bf16 v[100:103], v[96:99], v[182:185], v[100:103]
	v_mfma_f32_16x16x32_bf16 v[92:95], v[116:119], v[182:185], v[92:95]
	v_mfma_f32_16x16x32_bf16 v[76:79], v[96:99], v[210:213], v[76:79]
	v_mfma_f32_16x16x32_bf16 v[72:75], v[116:119], v[210:213], v[72:75]
	v_mfma_f32_16x16x32_bf16 v[142:145], v[130:133], v[162:165], v[142:145]
	v_mfma_f32_16x16x32_bf16 v[134:137], v[146:149], v[162:165], v[134:137]
	v_mfma_f32_16x16x32_bf16 v[112:115], v[130:133], v[170:173], v[112:115]
	v_mfma_f32_16x16x32_bf16 v[108:111], v[146:149], v[170:173], v[108:111]
	v_mfma_f32_16x16x32_bf16 v[84:87], v[130:133], v[178:181], v[84:87]
	v_mfma_f32_16x16x32_bf16 v[80:83], v[146:149], v[178:181], v[80:83]
	v_mfma_f32_16x16x32_bf16 v[68:71], v[130:133], v[186:189], v[68:71]
	v_mfma_f32_16x16x32_bf16 v[64:67], v[146:149], v[186:189], v[64:67]
	v_mfma_f32_16x16x32_bf16 v[142:145], v[138:141], v[166:169], v[142:145]
	v_mfma_f32_16x16x32_bf16 v[134:137], v[154:157], v[166:169], v[134:137]
	v_mfma_f32_16x16x32_bf16 v[112:115], v[138:141], v[174:177], v[112:115]
	v_mfma_f32_16x16x32_bf16 v[108:111], v[154:157], v[174:177], v[108:111]
	v_mfma_f32_16x16x32_bf16 v[84:87], v[138:141], v[182:185], v[84:87]
	v_mfma_f32_16x16x32_bf16 v[80:83], v[154:157], v[182:185], v[80:83]
	v_mfma_f32_16x16x32_bf16 v[68:71], v[138:141], v[210:213], v[68:71]
	v_mfma_f32_16x16x32_bf16 v[64:67], v[154:157], v[210:213], v[64:67]
	s_setprio 0
	s_barrier
	s_add_i32 s12, s24, s14
	v_lshl_add_u64 v[226:227], v[226:227], 0, s[26:27]
	s_mov_b32 m0, s12
	ds_read_b128 v[162:165], v225 offset:49152
	ds_read_b128 v[166:169], v225 offset:50176
	ds_read_b128 v[170:173], v225 offset:51200
	ds_read_b128 v[174:177], v225 offset:52224
	ds_read_b128 v[178:181], v225 offset:53248
	ds_read_b128 v[182:185], v225 offset:54272
	ds_read_b128 v[186:189], v225 offset:55296
	ds_read_b128 v[210:213], v225 offset:56320
	global_load_lds_dwordx4 v[226:227], off
	s_add_i32 m0, s12, 0x2000
	s_add_u32 s10, s10, 0x80080
	v_lshl_add_u64 v[226:227], v[228:229], 0, s[26:27]
	s_addc_u32 s11, s11, 0
	s_add_i32 s12, s25, s14
	global_load_lds_dwordx4 v[226:227], off
	v_lshl_add_u64 v[226:227], s[10:11], 0, v[128:129]
	s_mov_b32 m0, s12
	s_nop 0
	global_load_lds_dwordx4 v[226:227], off
	v_lshl_add_u64 v[226:227], s[10:11], 0, v[200:201]
	s_add_i32 m0, s12, 0x2000
	s_nop 0
	global_load_lds_dwordx4 v[226:227], off
	v_lshl_add_u64 v[226:227], v[230:231], 0, s[26:27]
	s_mov_b32 m0, s20
	s_nop 0
	global_load_lds_dwordx4 v[226:227], off
	v_lshl_add_u64 v[226:227], v[232:233], 0, s[26:27]
	s_mov_b32 m0, s21
	s_nop 0
	global_load_lds_dwordx4 v[226:227], off
	s_waitcnt vmcnt(8)
	s_waitcnt lgkmcnt(0)
	s_barrier
	s_setprio 1
	s_waitcnt lgkmcnt(0)
	v_mfma_f32_16x16x32_bf16 v[60:63], v[88:91], v[162:165], v[60:63]
	v_mfma_f32_16x16x32_bf16 v[56:59], v[104:107], v[162:165], v[56:59]
	v_mfma_f32_16x16x32_bf16 v[44:47], v[88:91], v[170:173], v[44:47]
	v_mfma_f32_16x16x32_bf16 v[40:43], v[104:107], v[170:173], v[40:43]
	v_mfma_f32_16x16x32_bf16 v[28:31], v[88:91], v[178:181], v[28:31]
	v_mfma_f32_16x16x32_bf16 v[24:27], v[104:107], v[178:181], v[24:27]
	v_mfma_f32_16x16x32_bf16 v[12:15], v[88:91], v[186:189], v[12:15]
	v_mfma_f32_16x16x32_bf16 v[8:11], v[104:107], v[186:189], v[8:11]
	v_mfma_f32_16x16x32_bf16 v[60:63], v[96:99], v[166:169], v[60:63]
	v_mfma_f32_16x16x32_bf16 v[56:59], v[116:119], v[166:169], v[56:59]
	v_mfma_f32_16x16x32_bf16 v[44:47], v[96:99], v[174:177], v[44:47]
	v_mfma_f32_16x16x32_bf16 v[40:43], v[116:119], v[174:177], v[40:43]
	v_mfma_f32_16x16x32_bf16 v[28:31], v[96:99], v[182:185], v[28:31]
	v_mfma_f32_16x16x32_bf16 v[24:27], v[116:119], v[182:185], v[24:27]
	v_mfma_f32_16x16x32_bf16 v[12:15], v[96:99], v[210:213], v[12:15]
	v_mfma_f32_16x16x32_bf16 v[8:11], v[116:119], v[210:213], v[8:11]
	v_mfma_f32_16x16x32_bf16 v[52:55], v[130:133], v[162:165], v[52:55]
	v_mfma_f32_16x16x32_bf16 v[48:51], v[146:149], v[162:165], v[48:51]
	v_mfma_f32_16x16x32_bf16 v[36:39], v[130:133], v[170:173], v[36:39]
	v_mfma_f32_16x16x32_bf16 v[32:35], v[146:149], v[170:173], v[32:35]
	v_mfma_f32_16x16x32_bf16 v[20:23], v[130:133], v[178:181], v[20:23]
	v_mfma_f32_16x16x32_bf16 v[16:19], v[146:149], v[178:181], v[16:19]
	v_mfma_f32_16x16x32_bf16 v[4:7], v[130:133], v[186:189], v[4:7]
	v_mfma_f32_16x16x32_bf16 v[0:3], v[146:149], v[186:189], v[0:3]
	v_mfma_f32_16x16x32_bf16 v[52:55], v[138:141], v[166:169], v[52:55]
	v_mfma_f32_16x16x32_bf16 v[48:51], v[154:157], v[166:169], v[48:51]
	v_mfma_f32_16x16x32_bf16 v[36:39], v[138:141], v[174:177], v[36:39]
	v_mfma_f32_16x16x32_bf16 v[32:35], v[154:157], v[174:177], v[32:35]
	v_mfma_f32_16x16x32_bf16 v[20:23], v[138:141], v[182:185], v[20:23]
	v_mfma_f32_16x16x32_bf16 v[16:19], v[154:157], v[182:185], v[16:19]
	v_mfma_f32_16x16x32_bf16 v[4:7], v[138:141], v[210:213], v[4:7]
	v_mfma_f32_16x16x32_bf16 v[0:3], v[154:157], v[210:213], v[0:3]
	s_setprio 0
	s_barrier
	s_add_i32 s85, s85, 2
	s_add_u32 s8, s8, 0x100
	s_addc_u32 s9, s9, 0
	s_add_u32 s75, s75, 0x100
	s_addc_u32 s84, s84, 0
	s_cmp_gt_u32 s85, 29
	s_cbranch_scc0 .LBB0_1038
	s_nop 0
	s_nop 0
	s_nop 0
	s_nop 0
	s_nop 0
	s_nop 0
	s_nop 0
	s_nop 0
	s_and_b64 vcc, exec, s[6:7]
	s_cbranch_vccz .LBB0_1041
	s_barrier

.LBB0_1148:
	s_add_u32 s8, s6, 0xfff80080
	s_addc_u32 s9, s7, -1
	s_add_i32 s24, 0, 0x10000
	s_cmp_eq_u32 s75, 28
	s_cselect_b32 s11, s33, s9
	s_cselect_b32 s10, s47, s8
	s_cselect_b32 s9, s45, s74
	s_cselect_b32 s8, s72, s73
	s_add_i32 s28, 0, 0x14000
	v_add_u32_e32 v156, s24, v149
	v_add_u32_e32 v172, s28, v149
	ds_read_b128 v[140:143], v156
	ds_read_b128 v[144:147], v156 offset:1024
	ds_read_b128 v[152:155], v156 offset:2048
	ds_read_b128 v[156:159], v156 offset:3072
	ds_read_b128 v[160:163], v172
	ds_read_b128 v[164:167], v172 offset:1024
	ds_read_b128 v[168:171], v172 offset:2048
	ds_read_b128 v[172:175], v172 offset:3072
	v_lshl_add_u64 v[188:189], s[6:7], 0, v[136:137]
	s_add_i32 m0, s13, 0xc000
	ds_read_b128 v[176:179], v151
	ds_read_b128 v[180:183], v151 offset:1024
	ds_read_b128 v[184:187], v151 offset:2048
	ds_read_b128 v[200:203], v151 offset:3072
	ds_read_b128 v[204:207], v151 offset:4096
	ds_read_b128 v[208:211], v151 offset:5120
	ds_read_b128 v[222:225], v151 offset:6144
	ds_read_b128 v[226:229], v151 offset:7168
	global_load_lds_dwordx4 v[188:189], off
	v_lshl_add_u64 v[188:189], s[6:7], 0, v[138:139]
	s_add_i32 m0, s13, 0xe000
	s_nop 0
	global_load_lds_dwordx4 v[188:189], off
	s_waitcnt vmcnt(8)
	s_waitcnt lgkmcnt(0)
	s_barrier
	s_setprio 1
	s_waitcnt lgkmcnt(0)
	v_mfma_f32_16x16x32_bf16 v[124:127], v[140:143], v[176:179], v[124:127]
	v_mfma_f32_16x16x32_bf16 v[120:123], v[152:155], v[176:179], v[120:123]
	v_mfma_f32_16x16x32_bf16 v[108:111], v[140:143], v[184:187], v[108:111]
	v_mfma_f32_16x16x32_bf16 v[104:107], v[152:155], v[184:187], v[104:107]
	v_mfma_f32_16x16x32_bf16 v[92:95], v[140:143], v[204:207], v[92:95]
	v_mfma_f32_16x16x32_bf16 v[88:91], v[152:155], v[204:207], v[88:91]
	v_mfma_f32_16x16x32_bf16 v[76:79], v[140:143], v[222:225], v[76:79]
	v_mfma_f32_16x16x32_bf16 v[72:75], v[152:155], v[222:225], v[72:75]
	v_mfma_f32_16x16x32_bf16 v[124:127], v[144:147], v[180:183], v[124:127]
	v_mfma_f32_16x16x32_bf16 v[120:123], v[156:159], v[180:183], v[120:123]
	v_mfma_f32_16x16x32_bf16 v[108:111], v[144:147], v[200:203], v[108:111]
	v_mfma_f32_16x16x32_bf16 v[104:107], v[156:159], v[200:203], v[104:107]
	v_mfma_f32_16x16x32_bf16 v[92:95], v[144:147], v[208:211], v[92:95]
	v_mfma_f32_16x16x32_bf16 v[88:91], v[156:159], v[208:211], v[88:91]
	v_mfma_f32_16x16x32_bf16 v[76:79], v[144:147], v[226:229], v[76:79]
	v_mfma_f32_16x16x32_bf16 v[72:75], v[156:159], v[226:229], v[72:75]
	v_mfma_f32_16x16x32_bf16 v[116:119], v[160:163], v[176:179], v[116:119]
	v_mfma_f32_16x16x32_bf16 v[112:115], v[168:171], v[176:179], v[112:115]
	v_mfma_f32_16x16x32_bf16 v[100:103], v[160:163], v[184:187], v[100:103]
	v_mfma_f32_16x16x32_bf16 v[96:99], v[168:171], v[184:187], v[96:99]
	v_mfma_f32_16x16x32_bf16 v[84:87], v[160:163], v[204:207], v[84:87]
	v_mfma_f32_16x16x32_bf16 v[80:83], v[168:171], v[204:207], v[80:83]
	v_mfma_f32_16x16x32_bf16 v[68:71], v[160:163], v[222:225], v[68:71]
	v_mfma_f32_16x16x32_bf16 v[64:67], v[168:171], v[222:225], v[64:67]
	v_mfma_f32_16x16x32_bf16 v[116:119], v[164:167], v[180:183], v[116:119]
	v_mfma_f32_16x16x32_bf16 v[112:115], v[172:175], v[180:183], v[112:115]
	v_mfma_f32_16x16x32_bf16 v[100:103], v[164:167], v[200:203], v[100:103]
	v_mfma_f32_16x16x32_bf16 v[96:99], v[172:175], v[200:203], v[96:99]
	v_mfma_f32_16x16x32_bf16 v[84:87], v[164:167], v[208:211], v[84:87]
	v_mfma_f32_16x16x32_bf16 v[80:83], v[172:175], v[208:211], v[80:83]
	v_mfma_f32_16x16x32_bf16 v[68:71], v[164:167], v[226:229], v[68:71]
	v_mfma_f32_16x16x32_bf16 v[64:67], v[172:175], v[226:229], v[64:67]
	s_setprio 0
	s_barrier
	s_add_i32 s24, s24, s12
	v_lshl_add_u64 v[188:189], s[8:9], 0, v[128:129]
	s_mov_b32 m0, s24
	ds_read_b128 v[176:179], v151 offset:16384
	ds_read_b128 v[180:183], v151 offset:17408
	ds_read_b128 v[184:187], v151 offset:18432
	ds_read_b128 v[200:203], v151 offset:19456
	ds_read_b128 v[204:207], v151 offset:20480
	ds_read_b128 v[208:211], v151 offset:21504
	ds_read_b128 v[222:225], v151 offset:22528
	ds_read_b128 v[226:229], v151 offset:23552
	global_load_lds_dwordx4 v[188:189], off
	s_add_i32 m0, s24, 0x2000
	s_add_u32 s24, s8, 0x80000
	v_lshl_add_u64 v[212:213], s[8:9], 0, v[130:131]
	s_addc_u32 s25, s9, 0
	s_add_i32 s28, s28, s12
	global_load_lds_dwordx4 v[212:213], off
	v_lshl_add_u64 v[230:231], s[24:25], 0, v[128:129]
	s_mov_b32 m0, s28
	v_lshl_add_u64 v[232:233], s[10:11], 0, v[132:133]
	global_load_lds_dwordx4 v[230:231], off
	v_lshl_add_u64 v[230:231], s[24:25], 0, v[130:131]
	s_add_i32 m0, s28, 0x2000
	s_nop 0
	global_load_lds_dwordx4 v[230:231], off
	v_lshl_add_u64 v[230:231], s[10:11], 0, v[134:135]
	s_mov_b32 m0, s13
	s_nop 0
	global_load_lds_dwordx4 v[230:231], off
	s_mov_b32 m0, s17
	s_nop 0
	global_load_lds_dwordx4 v[232:233], off
	s_waitcnt vmcnt(8)
	s_waitcnt lgkmcnt(0)
	s_barrier
	s_setprio 1
	s_waitcnt lgkmcnt(0)
	v_mfma_f32_16x16x32_bf16 v[60:63], v[140:143], v[176:179], v[60:63]
	v_mfma_f32_16x16x32_bf16 v[56:59], v[152:155], v[176:179], v[56:59]
	v_mfma_f32_16x16x32_bf16 v[44:47], v[140:143], v[184:187], v[44:47]
	v_mfma_f32_16x16x32_bf16 v[40:43], v[152:155], v[184:187], v[40:43]
	v_mfma_f32_16x16x32_bf16 v[28:31], v[140:143], v[204:207], v[28:31]
	v_mfma_f32_16x16x32_bf16 v[24:27], v[152:155], v[204:207], v[24:27]
	v_mfma_f32_16x16x32_bf16 v[12:15], v[140:143], v[222:225], v[12:15]
	v_mfma_f32_16x16x32_bf16 v[8:11], v[152:155], v[222:225], v[8:11]
	v_mfma_f32_16x16x32_bf16 v[60:63], v[144:147], v[180:183], v[60:63]
	v_mfma_f32_16x16x32_bf16 v[56:59], v[156:159], v[180:183], v[56:59]
	v_mfma_f32_16x16x32_bf16 v[44:47], v[144:147], v[200:203], v[44:47]
	v_mfma_f32_16x16x32_bf16 v[40:43], v[156:159], v[200:203], v[40:43]
	v_mfma_f32_16x16x32_bf16 v[28:31], v[144:147], v[208:211], v[28:31]
	v_mfma_f32_16x16x32_bf16 v[24:27], v[156:159], v[208:211], v[24:27]
	v_mfma_f32_16x16x32_bf16 v[12:15], v[144:147], v[226:229], v[12:15]
	v_mfma_f32_16x16x32_bf16 v[8:11], v[156:159], v[226:229], v[8:11]
	v_mfma_f32_16x16x32_bf16 v[52:55], v[160:163], v[176:179], v[52:55]
	v_mfma_f32_16x16x32_bf16 v[48:51], v[168:171], v[176:179], v[48:51]
	v_mfma_f32_16x16x32_bf16 v[36:39], v[160:163], v[184:187], v[36:39]
	v_mfma_f32_16x16x32_bf16 v[32:35], v[168:171], v[184:187], v[32:35]
	v_mfma_f32_16x16x32_bf16 v[20:23], v[160:163], v[204:207], v[20:23]
	v_mfma_f32_16x16x32_bf16 v[16:19], v[168:171], v[204:207], v[16:19]
	v_mfma_f32_16x16x32_bf16 v[4:7], v[160:163], v[222:225], v[4:7]
	v_mfma_f32_16x16x32_bf16 v[0:3], v[168:171], v[222:225], v[0:3]
	v_mfma_f32_16x16x32_bf16 v[52:55], v[164:167], v[180:183], v[52:55]
	v_mfma_f32_16x16x32_bf16 v[48:51], v[172:175], v[180:183], v[48:51]
	v_mfma_f32_16x16x32_bf16 v[36:39], v[164:167], v[200:203], v[36:39]
	v_mfma_f32_16x16x32_bf16 v[32:35], v[172:175], v[200:203], v[32:35]
	v_mfma_f32_16x16x32_bf16 v[20:23], v[164:167], v[208:211], v[20:23]
	v_mfma_f32_16x16x32_bf16 v[16:19], v[172:175], v[208:211], v[16:19]
	v_mfma_f32_16x16x32_bf16 v[4:7], v[164:167], v[226:229], v[4:7]
	v_mfma_f32_16x16x32_bf16 v[0:3], v[172:175], v[226:229], v[0:3]
	s_setprio 0
	s_barrier
	s_add_i32 s24, 0, 0x18000
	s_add_i32 s25, 0, 0x1c000
	v_add_u32_e32 v156, s24, v149
	v_add_u32_e32 v172, s25, v149
	ds_read_b128 v[140:143], v156
	ds_read_b128 v[144:147], v156 offset:1024
	ds_read_b128 v[152:155], v156 offset:2048
	ds_read_b128 v[156:159], v156 offset:3072
	ds_read_b128 v[160:163], v172
	ds_read_b128 v[164:167], v172 offset:1024
	ds_read_b128 v[168:171], v172 offset:2048
	ds_read_b128 v[172:175], v172 offset:3072
	s_add_u32 s10, s10, 0x80000
	s_addc_u32 s11, s11, 0
	s_mov_b32 m0, s19
	v_lshl_add_u64 v[234:235], s[10:11], 0, v[134:135]
	ds_read_b128 v[176:179], v151 offset:32768
	ds_read_b128 v[180:183], v151 offset:33792
	ds_read_b128 v[184:187], v151 offset:34816
	ds_read_b128 v[200:203], v151 offset:35840
	ds_read_b128 v[204:207], v151 offset:36864
	ds_read_b128 v[208:211], v151 offset:37888
	ds_read_b128 v[222:225], v151 offset:38912
	ds_read_b128 v[226:229], v151 offset:39936
	global_load_lds_dwordx4 v[234:235], off
	v_lshl_add_u64 v[234:235], s[10:11], 0, v[132:133]
	s_mov_b32 m0, s20
	s_nop 0
	global_load_lds_dwordx4 v[234:235], off
	s_waitcnt vmcnt(8)
	s_waitcnt lgkmcnt(0)
	s_barrier
	s_setprio 1
	s_waitcnt lgkmcnt(0)
	v_mfma_f32_16x16x32_bf16 v[124:127], v[140:143], v[176:179], v[124:127]
	v_mfma_f32_16x16x32_bf16 v[120:123], v[152:155], v[176:179], v[120:123]
	v_mfma_f32_16x16x32_bf16 v[108:111], v[140:143], v[184:187], v[108:111]
	v_mfma_f32_16x16x32_bf16 v[104:107], v[152:155], v[184:187], v[104:107]
	v_mfma_f32_16x16x32_bf16 v[92:95], v[140:143], v[204:207], v[92:95]
	v_mfma_f32_16x16x32_bf16 v[88:91], v[152:155], v[204:207], v[88:91]
	v_mfma_f32_16x16x32_bf16 v[76:79], v[140:143], v[222:225], v[76:79]
	v_mfma_f32_16x16x32_bf16 v[72:75], v[152:155], v[222:225], v[72:75]
	v_mfma_f32_16x16x32_bf16 v[124:127], v[144:147], v[180:183], v[124:127]
	v_mfma_f32_16x16x32_bf16 v[120:123], v[156:159], v[180:183], v[120:123]
	v_mfma_f32_16x16x32_bf16 v[108:111], v[144:147], v[200:203], v[108:111]
	v_mfma_f32_16x16x32_bf16 v[104:107], v[156:159], v[200:203], v[104:107]
	v_mfma_f32_16x16x32_bf16 v[92:95], v[144:147], v[208:211], v[92:95]
	v_mfma_f32_16x16x32_bf16 v[88:91], v[156:159], v[208:211], v[88:91]
	v_mfma_f32_16x16x32_bf16 v[76:79], v[144:147], v[226:229], v[76:79]
	v_mfma_f32_16x16x32_bf16 v[72:75], v[156:159], v[226:229], v[72:75]
	v_mfma_f32_16x16x32_bf16 v[116:119], v[160:163], v[176:179], v[116:119]
	v_mfma_f32_16x16x32_bf16 v[112:115], v[168:171], v[176:179], v[112:115]
	v_mfma_f32_16x16x32_bf16 v[100:103], v[160:163], v[184:187], v[100:103]
	v_mfma_f32_16x16x32_bf16 v[96:99], v[168:171], v[184:187], v[96:99]
	v_mfma_f32_16x16x32_bf16 v[84:87], v[160:163], v[204:207], v[84:87]
	v_mfma_f32_16x16x32_bf16 v[80:83], v[168:171], v[204:207], v[80:83]
	v_mfma_f32_16x16x32_bf16 v[68:71], v[160:163], v[222:225], v[68:71]
	v_mfma_f32_16x16x32_bf16 v[64:67], v[168:171], v[222:225], v[64:67]
	v_mfma_f32_16x16x32_bf16 v[116:119], v[164:167], v[180:183], v[116:119]
	v_mfma_f32_16x16x32_bf16 v[112:115], v[172:175], v[180:183], v[112:115]
	v_mfma_f32_16x16x32_bf16 v[100:103], v[164:167], v[200:203], v[100:103]
	v_mfma_f32_16x16x32_bf16 v[96:99], v[172:175], v[200:203], v[96:99]
	v_mfma_f32_16x16x32_bf16 v[84:87], v[164:167], v[208:211], v[84:87]
	v_mfma_f32_16x16x32_bf16 v[80:83], v[172:175], v[208:211], v[80:83]
	v_mfma_f32_16x16x32_bf16 v[68:71], v[164:167], v[226:229], v[68:71]
	v_mfma_f32_16x16x32_bf16 v[64:67], v[172:175], v[226:229], v[64:67]
	s_setprio 0
	s_barrier
	s_add_i32 s10, s24, s12
	v_lshl_add_u64 v[188:189], v[188:189], 0, s[26:27]
	s_mov_b32 m0, s10
	ds_read_b128 v[176:179], v151 offset:49152
	ds_read_b128 v[180:183], v151 offset:50176
	ds_read_b128 v[184:187], v151 offset:51200
	ds_read_b128 v[200:203], v151 offset:52224
	ds_read_b128 v[204:207], v151 offset:53248
	ds_read_b128 v[208:211], v151 offset:54272
	ds_read_b128 v[222:225], v151 offset:55296
	ds_read_b128 v[226:229], v151 offset:56320
	global_load_lds_dwordx4 v[188:189], off
	s_add_i32 m0, s10, 0x2000
	s_add_u32 s8, s8, 0x80080
	v_lshl_add_u64 v[188:189], v[212:213], 0, s[26:27]
	s_addc_u32 s9, s9, 0
	s_add_i32 s10, s25, s12
	global_load_lds_dwordx4 v[188:189], off
	v_lshl_add_u64 v[188:189], s[8:9], 0, v[128:129]
	s_mov_b32 m0, s10
	s_nop 0
	global_load_lds_dwordx4 v[188:189], off
	v_lshl_add_u64 v[188:189], s[8:9], 0, v[130:131]
	s_add_i32 m0, s10, 0x2000
	s_nop 0
	global_load_lds_dwordx4 v[188:189], off
	v_lshl_add_u64 v[188:189], v[230:231], 0, s[26:27]
	s_mov_b32 m0, s21
	s_nop 0
	global_load_lds_dwordx4 v[188:189], off
	v_lshl_add_u64 v[188:189], v[232:233], 0, s[26:27]
	s_mov_b32 m0, s22
	s_nop 0
	global_load_lds_dwordx4 v[188:189], off
	s_waitcnt vmcnt(8)
	s_waitcnt lgkmcnt(0)
	s_barrier
	s_setprio 1
	s_waitcnt lgkmcnt(0)
	v_mfma_f32_16x16x32_bf16 v[60:63], v[140:143], v[176:179], v[60:63]
	v_mfma_f32_16x16x32_bf16 v[56:59], v[152:155], v[176:179], v[56:59]
	v_mfma_f32_16x16x32_bf16 v[44:47], v[140:143], v[184:187], v[44:47]
	v_mfma_f32_16x16x32_bf16 v[40:43], v[152:155], v[184:187], v[40:43]
	v_mfma_f32_16x16x32_bf16 v[28:31], v[140:143], v[204:207], v[28:31]
	v_mfma_f32_16x16x32_bf16 v[24:27], v[152:155], v[204:207], v[24:27]
	v_mfma_f32_16x16x32_bf16 v[12:15], v[140:143], v[222:225], v[12:15]
	v_mfma_f32_16x16x32_bf16 v[8:11], v[152:155], v[222:225], v[8:11]
	v_mfma_f32_16x16x32_bf16 v[60:63], v[144:147], v[180:183], v[60:63]
	v_mfma_f32_16x16x32_bf16 v[56:59], v[156:159], v[180:183], v[56:59]
	v_mfma_f32_16x16x32_bf16 v[44:47], v[144:147], v[200:203], v[44:47]
	v_mfma_f32_16x16x32_bf16 v[40:43], v[156:159], v[200:203], v[40:43]
	v_mfma_f32_16x16x32_bf16 v[28:31], v[144:147], v[208:211], v[28:31]
	v_mfma_f32_16x16x32_bf16 v[24:27], v[156:159], v[208:211], v[24:27]
	v_mfma_f32_16x16x32_bf16 v[12:15], v[144:147], v[226:229], v[12:15]
	v_mfma_f32_16x16x32_bf16 v[8:11], v[156:159], v[226:229], v[8:11]
	v_mfma_f32_16x16x32_bf16 v[52:55], v[160:163], v[176:179], v[52:55]
	v_mfma_f32_16x16x32_bf16 v[48:51], v[168:171], v[176:179], v[48:51]
	v_mfma_f32_16x16x32_bf16 v[36:39], v[160:163], v[184:187], v[36:39]
	v_mfma_f32_16x16x32_bf16 v[32:35], v[168:171], v[184:187], v[32:35]
	v_mfma_f32_16x16x32_bf16 v[20:23], v[160:163], v[204:207], v[20:23]
	v_mfma_f32_16x16x32_bf16 v[16:19], v[168:171], v[204:207], v[16:19]
	v_mfma_f32_16x16x32_bf16 v[4:7], v[160:163], v[222:225], v[4:7]
	v_mfma_f32_16x16x32_bf16 v[0:3], v[168:171], v[222:225], v[0:3]
	v_mfma_f32_16x16x32_bf16 v[52:55], v[164:167], v[180:183], v[52:55]
	v_mfma_f32_16x16x32_bf16 v[48:51], v[172:175], v[180:183], v[48:51]
	v_mfma_f32_16x16x32_bf16 v[36:39], v[164:167], v[200:203], v[36:39]
	v_mfma_f32_16x16x32_bf16 v[32:35], v[172:175], v[200:203], v[32:35]
	v_mfma_f32_16x16x32_bf16 v[20:23], v[164:167], v[208:211], v[20:23]
	v_mfma_f32_16x16x32_bf16 v[16:19], v[172:175], v[208:211], v[16:19]
	v_mfma_f32_16x16x32_bf16 v[4:7], v[164:167], v[226:229], v[4:7]
	v_mfma_f32_16x16x32_bf16 v[0:3], v[172:175], v[226:229], v[0:3]
	s_setprio 0
	s_barrier
	s_add_i32 s75, s75, 2
	s_add_u32 s6, s6, 0x100
	s_addc_u32 s7, s7, 0
	s_add_u32 s73, s73, 0x100
	s_addc_u32 s74, s74, 0
	s_cmp_gt_u32 s75, 29
	s_cbranch_scc0 .LBB0_1148
	s_nop 0
	s_nop 0
	s_nop 0
	s_nop 0
	s_nop 0
	s_nop 0
	s_nop 0
	s_nop 0
	s_and_b64 vcc, exec, s[42:43]
	v_readlane_b32 s33, v236, 11
	s_cbranch_vccz .LBB0_1151
	s_barrier

.LBB0_1220:
	s_add_u32 s10, s8, 0xfff80080
	s_addc_u32 s11, s9, -1
	s_add_i32 s24, 0, 0x10000
	s_cmp_eq_u32 s75, 28
	s_cselect_b32 s13, s33, s11
	s_cselect_b32 s12, s43, s10
	v_add_u32_e32 v128, s24, v153
	s_cselect_b32 s11, s39, s74
	s_cselect_b32 s10, s72, s73
	s_add_i32 s28, 0, 0x14000
	ds_read_b128 v[138:141], v128
	ds_read_b128 v[142:145], v128 offset:1024
	ds_read_b128 v[146:149], v128 offset:2048
	ds_read_b128 v[156:159], v128 offset:3072
	v_add_u32_e32 v128, s28, v153
	ds_read_b128 v[160:163], v128
	ds_read_b128 v[164:167], v128 offset:1024
	ds_read_b128 v[168:171], v128 offset:2048
	ds_read_b128 v[172:175], v128 offset:3072
	v_lshl_add_u64 v[150:151], s[8:9], 0, v[134:135]
	s_add_i32 m0, s1, 0xc000
	ds_read_b128 v[176:179], v155
	ds_read_b128 v[180:183], v155 offset:1024
	ds_read_b128 v[184:187], v155 offset:2048
	ds_read_b128 v[200:203], v155 offset:3072
	ds_read_b128 v[204:207], v155 offset:4096
	ds_read_b128 v[208:211], v155 offset:5120
	ds_read_b128 v[222:225], v155 offset:6144
	ds_read_b128 v[226:229], v155 offset:7168
	global_load_lds_dwordx4 v[150:151], off
	v_lshl_add_u64 v[150:151], s[8:9], 0, v[136:137]
	s_add_i32 m0, s1, 0xe000
	s_nop 0
	global_load_lds_dwordx4 v[150:151], off
	s_waitcnt vmcnt(8)
	s_waitcnt lgkmcnt(0)
	s_barrier
	s_setprio 1
	s_waitcnt lgkmcnt(0)
	v_mfma_f32_16x16x32_bf16 v[124:127], v[138:141], v[176:179], v[124:127]
	v_mfma_f32_16x16x32_bf16 v[120:123], v[146:149], v[176:179], v[120:123]
	v_mfma_f32_16x16x32_bf16 v[108:111], v[138:141], v[184:187], v[108:111]
	v_mfma_f32_16x16x32_bf16 v[104:107], v[146:149], v[184:187], v[104:107]
	v_mfma_f32_16x16x32_bf16 v[92:95], v[138:141], v[204:207], v[92:95]
	v_mfma_f32_16x16x32_bf16 v[88:91], v[146:149], v[204:207], v[88:91]
	v_mfma_f32_16x16x32_bf16 v[76:79], v[138:141], v[222:225], v[76:79]
	v_mfma_f32_16x16x32_bf16 v[72:75], v[146:149], v[222:225], v[72:75]
	v_mfma_f32_16x16x32_bf16 v[124:127], v[142:145], v[180:183], v[124:127]
	v_mfma_f32_16x16x32_bf16 v[120:123], v[156:159], v[180:183], v[120:123]
	v_mfma_f32_16x16x32_bf16 v[108:111], v[142:145], v[200:203], v[108:111]
	v_mfma_f32_16x16x32_bf16 v[104:107], v[156:159], v[200:203], v[104:107]
	v_mfma_f32_16x16x32_bf16 v[92:95], v[142:145], v[208:211], v[92:95]
	v_mfma_f32_16x16x32_bf16 v[88:91], v[156:159], v[208:211], v[88:91]
	v_mfma_f32_16x16x32_bf16 v[76:79], v[142:145], v[226:229], v[76:79]
	v_mfma_f32_16x16x32_bf16 v[72:75], v[156:159], v[226:229], v[72:75]
	v_mfma_f32_16x16x32_bf16 v[116:119], v[160:163], v[176:179], v[116:119]
	v_mfma_f32_16x16x32_bf16 v[112:115], v[168:171], v[176:179], v[112:115]
	v_mfma_f32_16x16x32_bf16 v[100:103], v[160:163], v[184:187], v[100:103]
	v_mfma_f32_16x16x32_bf16 v[96:99], v[168:171], v[184:187], v[96:99]
	v_mfma_f32_16x16x32_bf16 v[84:87], v[160:163], v[204:207], v[84:87]
	v_mfma_f32_16x16x32_bf16 v[80:83], v[168:171], v[204:207], v[80:83]
	v_mfma_f32_16x16x32_bf16 v[68:71], v[160:163], v[222:225], v[68:71]
	v_mfma_f32_16x16x32_bf16 v[64:67], v[168:171], v[222:225], v[64:67]
	v_mfma_f32_16x16x32_bf16 v[116:119], v[164:167], v[180:183], v[116:119]
	v_mfma_f32_16x16x32_bf16 v[112:115], v[172:175], v[180:183], v[112:115]
	v_mfma_f32_16x16x32_bf16 v[100:103], v[164:167], v[200:203], v[100:103]
	v_mfma_f32_16x16x32_bf16 v[96:99], v[172:175], v[200:203], v[96:99]
	v_mfma_f32_16x16x32_bf16 v[84:87], v[164:167], v[208:211], v[84:87]
	v_mfma_f32_16x16x32_bf16 v[80:83], v[172:175], v[208:211], v[80:83]
	v_mfma_f32_16x16x32_bf16 v[68:71], v[164:167], v[226:229], v[68:71]
	v_mfma_f32_16x16x32_bf16 v[64:67], v[172:175], v[226:229], v[64:67]
	s_setprio 0
	s_barrier
	s_add_i32 s24, s24, s0
	v_lshl_add_u64 v[150:151], s[10:11], 0, v[132:133]
	s_mov_b32 m0, s24
	ds_read_b128 v[176:179], v155 offset:16384
	ds_read_b128 v[180:183], v155 offset:17408
	ds_read_b128 v[184:187], v155 offset:18432
	ds_read_b128 v[200:203], v155 offset:19456
	ds_read_b128 v[204:207], v155 offset:20480
	ds_read_b128 v[208:211], v155 offset:21504
	ds_read_b128 v[222:225], v155 offset:22528
	ds_read_b128 v[226:229], v155 offset:23552
	global_load_lds_dwordx4 v[150:151], off
	s_add_i32 m0, s24, 0x2000
	s_add_u32 s24, s10, 0x80000
	v_lshl_add_u64 v[188:189], s[10:11], 0, v[130:131]
	s_addc_u32 s25, s11, 0
	s_add_i32 s28, s28, s0
	global_load_lds_dwordx4 v[188:189], off
	v_lshl_add_u64 v[212:213], s[24:25], 0, v[132:133]
	s_mov_b32 m0, s28
	v_lshl_add_u64 v[230:231], s[12:13], 0, v[130:131]
	global_load_lds_dwordx4 v[212:213], off
	v_lshl_add_u64 v[212:213], s[24:25], 0, v[130:131]
	s_add_i32 m0, s28, 0x2000
	s_nop 0
	global_load_lds_dwordx4 v[212:213], off
	v_lshl_add_u64 v[212:213], s[12:13], 0, v[132:133]
	s_mov_b32 m0, s1
	s_nop 0
	global_load_lds_dwordx4 v[212:213], off
	s_mov_b32 m0, s14
	s_nop 0
	global_load_lds_dwordx4 v[230:231], off
	s_waitcnt vmcnt(8)
	s_waitcnt lgkmcnt(0)
	s_barrier
	s_setprio 1
	s_waitcnt lgkmcnt(0)
	v_mfma_f32_16x16x32_bf16 v[60:63], v[138:141], v[176:179], v[60:63]
	v_mfma_f32_16x16x32_bf16 v[56:59], v[146:149], v[176:179], v[56:59]
	v_mfma_f32_16x16x32_bf16 v[44:47], v[138:141], v[184:187], v[44:47]
	v_mfma_f32_16x16x32_bf16 v[40:43], v[146:149], v[184:187], v[40:43]
	v_mfma_f32_16x16x32_bf16 v[28:31], v[138:141], v[204:207], v[28:31]
	v_mfma_f32_16x16x32_bf16 v[24:27], v[146:149], v[204:207], v[24:27]
	v_mfma_f32_16x16x32_bf16 v[12:15], v[138:141], v[222:225], v[12:15]
	v_mfma_f32_16x16x32_bf16 v[8:11], v[146:149], v[222:225], v[8:11]
	v_mfma_f32_16x16x32_bf16 v[60:63], v[142:145], v[180:183], v[60:63]
	v_mfma_f32_16x16x32_bf16 v[56:59], v[156:159], v[180:183], v[56:59]
	v_mfma_f32_16x16x32_bf16 v[44:47], v[142:145], v[200:203], v[44:47]
	v_mfma_f32_16x16x32_bf16 v[40:43], v[156:159], v[200:203], v[40:43]
	v_mfma_f32_16x16x32_bf16 v[28:31], v[142:145], v[208:211], v[28:31]
	v_mfma_f32_16x16x32_bf16 v[24:27], v[156:159], v[208:211], v[24:27]
	v_mfma_f32_16x16x32_bf16 v[12:15], v[142:145], v[226:229], v[12:15]
	v_mfma_f32_16x16x32_bf16 v[8:11], v[156:159], v[226:229], v[8:11]
	v_mfma_f32_16x16x32_bf16 v[52:55], v[160:163], v[176:179], v[52:55]
	v_mfma_f32_16x16x32_bf16 v[48:51], v[168:171], v[176:179], v[48:51]
	v_mfma_f32_16x16x32_bf16 v[36:39], v[160:163], v[184:187], v[36:39]
	v_mfma_f32_16x16x32_bf16 v[32:35], v[168:171], v[184:187], v[32:35]
	v_mfma_f32_16x16x32_bf16 v[20:23], v[160:163], v[204:207], v[20:23]
	v_mfma_f32_16x16x32_bf16 v[16:19], v[168:171], v[204:207], v[16:19]
	v_mfma_f32_16x16x32_bf16 v[4:7], v[160:163], v[222:225], v[4:7]
	v_mfma_f32_16x16x32_bf16 v[0:3], v[168:171], v[222:225], v[0:3]
	v_mfma_f32_16x16x32_bf16 v[52:55], v[164:167], v[180:183], v[52:55]
	v_mfma_f32_16x16x32_bf16 v[48:51], v[172:175], v[180:183], v[48:51]
	v_mfma_f32_16x16x32_bf16 v[36:39], v[164:167], v[200:203], v[36:39]
	v_mfma_f32_16x16x32_bf16 v[32:35], v[172:175], v[200:203], v[32:35]
	v_mfma_f32_16x16x32_bf16 v[20:23], v[164:167], v[208:211], v[20:23]
	v_mfma_f32_16x16x32_bf16 v[16:19], v[172:175], v[208:211], v[16:19]
	v_mfma_f32_16x16x32_bf16 v[4:7], v[164:167], v[226:229], v[4:7]
	v_mfma_f32_16x16x32_bf16 v[0:3], v[172:175], v[226:229], v[0:3]
	s_setprio 0
	s_barrier
	s_add_i32 s24, 0, 0x18000
	v_add_u32_e32 v128, s24, v153
	s_add_i32 s25, 0, 0x1c000
	ds_read_b128 v[138:141], v128
	ds_read_b128 v[142:145], v128 offset:1024
	ds_read_b128 v[146:149], v128 offset:2048
	ds_read_b128 v[156:159], v128 offset:3072
	v_add_u32_e32 v128, s25, v153
	ds_read_b128 v[160:163], v128
	ds_read_b128 v[164:167], v128 offset:1024
	ds_read_b128 v[168:171], v128 offset:2048
	ds_read_b128 v[172:175], v128 offset:3072
	s_add_u32 s12, s12, 0x80000
	s_addc_u32 s13, s13, 0
	s_mov_b32 m0, s16
	v_lshl_add_u64 v[232:233], s[12:13], 0, v[132:133]
	ds_read_b128 v[176:179], v155 offset:32768
	ds_read_b128 v[180:183], v155 offset:33792
	ds_read_b128 v[184:187], v155 offset:34816
	ds_read_b128 v[200:203], v155 offset:35840
	ds_read_b128 v[204:207], v155 offset:36864
	ds_read_b128 v[208:211], v155 offset:37888
	ds_read_b128 v[222:225], v155 offset:38912
	ds_read_b128 v[226:229], v155 offset:39936
	global_load_lds_dwordx4 v[232:233], off
	v_lshl_add_u64 v[232:233], s[12:13], 0, v[130:131]
	s_mov_b32 m0, s17
	s_nop 0
	global_load_lds_dwordx4 v[232:233], off
	s_waitcnt vmcnt(8)
	s_waitcnt lgkmcnt(0)
	s_barrier
	s_setprio 1
	s_waitcnt lgkmcnt(0)
	v_mfma_f32_16x16x32_bf16 v[124:127], v[138:141], v[176:179], v[124:127]
	v_mfma_f32_16x16x32_bf16 v[120:123], v[146:149], v[176:179], v[120:123]
	v_mfma_f32_16x16x32_bf16 v[108:111], v[138:141], v[184:187], v[108:111]
	v_mfma_f32_16x16x32_bf16 v[104:107], v[146:149], v[184:187], v[104:107]
	v_mfma_f32_16x16x32_bf16 v[92:95], v[138:141], v[204:207], v[92:95]
	v_mfma_f32_16x16x32_bf16 v[88:91], v[146:149], v[204:207], v[88:91]
	v_mfma_f32_16x16x32_bf16 v[76:79], v[138:141], v[222:225], v[76:79]
	v_mfma_f32_16x16x32_bf16 v[72:75], v[146:149], v[222:225], v[72:75]
	v_mfma_f32_16x16x32_bf16 v[124:127], v[142:145], v[180:183], v[124:127]
	v_mfma_f32_16x16x32_bf16 v[120:123], v[156:159], v[180:183], v[120:123]
	v_mfma_f32_16x16x32_bf16 v[108:111], v[142:145], v[200:203], v[108:111]
	v_mfma_f32_16x16x32_bf16 v[104:107], v[156:159], v[200:203], v[104:107]
	v_mfma_f32_16x16x32_bf16 v[92:95], v[142:145], v[208:211], v[92:95]
	v_mfma_f32_16x16x32_bf16 v[88:91], v[156:159], v[208:211], v[88:91]
	v_mfma_f32_16x16x32_bf16 v[76:79], v[142:145], v[226:229], v[76:79]
	v_mfma_f32_16x16x32_bf16 v[72:75], v[156:159], v[226:229], v[72:75]
	v_mfma_f32_16x16x32_bf16 v[116:119], v[160:163], v[176:179], v[116:119]
	v_mfma_f32_16x16x32_bf16 v[112:115], v[168:171], v[176:179], v[112:115]
	v_mfma_f32_16x16x32_bf16 v[100:103], v[160:163], v[184:187], v[100:103]
	v_mfma_f32_16x16x32_bf16 v[96:99], v[168:171], v[184:187], v[96:99]
	v_mfma_f32_16x16x32_bf16 v[84:87], v[160:163], v[204:207], v[84:87]
	v_mfma_f32_16x16x32_bf16 v[80:83], v[168:171], v[204:207], v[80:83]
	v_mfma_f32_16x16x32_bf16 v[68:71], v[160:163], v[222:225], v[68:71]
	v_mfma_f32_16x16x32_bf16 v[64:67], v[168:171], v[222:225], v[64:67]
	v_mfma_f32_16x16x32_bf16 v[116:119], v[164:167], v[180:183], v[116:119]
	v_mfma_f32_16x16x32_bf16 v[112:115], v[172:175], v[180:183], v[112:115]
	v_mfma_f32_16x16x32_bf16 v[100:103], v[164:167], v[200:203], v[100:103]
	v_mfma_f32_16x16x32_bf16 v[96:99], v[172:175], v[200:203], v[96:99]
	v_mfma_f32_16x16x32_bf16 v[84:87], v[164:167], v[208:211], v[84:87]
	v_mfma_f32_16x16x32_bf16 v[80:83], v[172:175], v[208:211], v[80:83]
	v_mfma_f32_16x16x32_bf16 v[68:71], v[164:167], v[226:229], v[68:71]
	v_mfma_f32_16x16x32_bf16 v[64:67], v[172:175], v[226:229], v[64:67]
	s_setprio 0
	s_barrier
	s_add_i32 s12, s24, s0
	v_lshl_add_u64 v[150:151], v[150:151], 0, s[26:27]
	s_mov_b32 m0, s12
	ds_read_b128 v[176:179], v155 offset:49152
	ds_read_b128 v[180:183], v155 offset:50176
	ds_read_b128 v[184:187], v155 offset:51200
	ds_read_b128 v[200:203], v155 offset:52224
	ds_read_b128 v[204:207], v155 offset:53248
	ds_read_b128 v[208:211], v155 offset:54272
	ds_read_b128 v[222:225], v155 offset:55296
	ds_read_b128 v[226:229], v155 offset:56320
	global_load_lds_dwordx4 v[150:151], off
	s_add_i32 m0, s12, 0x2000
	s_add_u32 s10, s10, 0x80080
	v_lshl_add_u64 v[150:151], v[188:189], 0, s[26:27]
	s_addc_u32 s11, s11, 0
	s_add_i32 s12, s25, s0
	global_load_lds_dwordx4 v[150:151], off
	v_lshl_add_u64 v[150:151], s[10:11], 0, v[132:133]
	s_mov_b32 m0, s12
	s_nop 0
	global_load_lds_dwordx4 v[150:151], off
	v_lshl_add_u64 v[150:151], s[10:11], 0, v[130:131]
	s_add_i32 m0, s12, 0x2000
	s_nop 0
	global_load_lds_dwordx4 v[150:151], off
	v_lshl_add_u64 v[150:151], v[212:213], 0, s[26:27]
	s_mov_b32 m0, s18
	s_nop 0
	global_load_lds_dwordx4 v[150:151], off
	v_lshl_add_u64 v[150:151], v[230:231], 0, s[26:27]
	s_mov_b32 m0, s19
	s_nop 0
	global_load_lds_dwordx4 v[150:151], off
	s_waitcnt vmcnt(8)
	s_waitcnt lgkmcnt(0)
	s_barrier
	s_setprio 1
	s_waitcnt lgkmcnt(0)
	v_mfma_f32_16x16x32_bf16 v[60:63], v[138:141], v[176:179], v[60:63]
	v_mfma_f32_16x16x32_bf16 v[56:59], v[146:149], v[176:179], v[56:59]
	v_mfma_f32_16x16x32_bf16 v[44:47], v[138:141], v[184:187], v[44:47]
	v_mfma_f32_16x16x32_bf16 v[40:43], v[146:149], v[184:187], v[40:43]
	v_mfma_f32_16x16x32_bf16 v[28:31], v[138:141], v[204:207], v[28:31]
	v_mfma_f32_16x16x32_bf16 v[24:27], v[146:149], v[204:207], v[24:27]
	v_mfma_f32_16x16x32_bf16 v[12:15], v[138:141], v[222:225], v[12:15]
	v_mfma_f32_16x16x32_bf16 v[8:11], v[146:149], v[222:225], v[8:11]
	v_mfma_f32_16x16x32_bf16 v[60:63], v[142:145], v[180:183], v[60:63]
	v_mfma_f32_16x16x32_bf16 v[56:59], v[156:159], v[180:183], v[56:59]
	v_mfma_f32_16x16x32_bf16 v[44:47], v[142:145], v[200:203], v[44:47]
	v_mfma_f32_16x16x32_bf16 v[40:43], v[156:159], v[200:203], v[40:43]
	v_mfma_f32_16x16x32_bf16 v[28:31], v[142:145], v[208:211], v[28:31]
	v_mfma_f32_16x16x32_bf16 v[24:27], v[156:159], v[208:211], v[24:27]
	v_mfma_f32_16x16x32_bf16 v[12:15], v[142:145], v[226:229], v[12:15]
	v_mfma_f32_16x16x32_bf16 v[8:11], v[156:159], v[226:229], v[8:11]
	v_mfma_f32_16x16x32_bf16 v[52:55], v[160:163], v[176:179], v[52:55]
	v_mfma_f32_16x16x32_bf16 v[48:51], v[168:171], v[176:179], v[48:51]
	v_mfma_f32_16x16x32_bf16 v[36:39], v[160:163], v[184:187], v[36:39]
	v_mfma_f32_16x16x32_bf16 v[32:35], v[168:171], v[184:187], v[32:35]
	v_mfma_f32_16x16x32_bf16 v[20:23], v[160:163], v[204:207], v[20:23]
	v_mfma_f32_16x16x32_bf16 v[16:19], v[168:171], v[204:207], v[16:19]
	v_mfma_f32_16x16x32_bf16 v[4:7], v[160:163], v[222:225], v[4:7]
	v_mfma_f32_16x16x32_bf16 v[0:3], v[168:171], v[222:225], v[0:3]
	v_mfma_f32_16x16x32_bf16 v[52:55], v[164:167], v[180:183], v[52:55]
	v_mfma_f32_16x16x32_bf16 v[48:51], v[172:175], v[180:183], v[48:51]
	v_mfma_f32_16x16x32_bf16 v[36:39], v[164:167], v[200:203], v[36:39]
	v_mfma_f32_16x16x32_bf16 v[32:35], v[172:175], v[200:203], v[32:35]
	v_mfma_f32_16x16x32_bf16 v[20:23], v[164:167], v[208:211], v[20:23]
	v_mfma_f32_16x16x32_bf16 v[16:19], v[172:175], v[208:211], v[16:19]
	v_mfma_f32_16x16x32_bf16 v[4:7], v[164:167], v[226:229], v[4:7]
	v_mfma_f32_16x16x32_bf16 v[0:3], v[172:175], v[226:229], v[0:3]
	s_setprio 0
	s_barrier
	s_add_i32 s75, s75, 2
	s_add_u32 s8, s8, 0x100
	s_addc_u32 s9, s9, 0
	s_add_u32 s73, s73, 0x100
	s_addc_u32 s74, s74, 0
	s_cmp_gt_u32 s75, 29
	s_cbranch_scc0 .LBB0_1220
	s_nop 0
	s_nop 0
	s_nop 0
	s_nop 0
	s_nop 0
	s_nop 0
	s_nop 0
	s_nop 0
	s_and_b64 vcc, exec, s[6:7]
	v_readlane_b32 s33, v236, 11
	s_cbranch_vccz .LBB0_1223
	s_barrier

.LBB0_1384:
	s_add_u32 s10, s8, 0xfffe0080
	s_addc_u32 s11, s9, -1
	s_add_i32 s24, 0, 0x10000
	s_cmp_eq_u32 s85, 4
	s_cselect_b32 s13, s45, s11
	s_cselect_b32 s12, s73, s10
	s_cselect_b32 s11, s39, s84
	s_cselect_b32 s10, s74, s75
	s_add_i32 s28, 0, 0x14000
	v_add_u32_e32 v116, s24, v223
	v_add_u32_e32 v154, s28, v223
	ds_read_b128 v[88:91], v116
	ds_read_b128 v[92:95], v116 offset:1024
	ds_read_b128 v[104:107], v116 offset:2048
	ds_read_b128 v[116:119], v116 offset:3072
	ds_read_b128 v[130:133], v154
	ds_read_b128 v[138:141], v154 offset:1024
	ds_read_b128 v[146:149], v154 offset:2048
	ds_read_b128 v[154:157], v154 offset:3072
	v_lshl_add_u64 v[226:227], s[8:9], 0, v[206:207]
	s_add_i32 m0, s16, 0xc000
	ds_read_b128 v[162:165], v225
	ds_read_b128 v[166:169], v225 offset:1024
	ds_read_b128 v[170:173], v225 offset:2048
	ds_read_b128 v[174:177], v225 offset:3072
	ds_read_b128 v[178:181], v225 offset:4096
	ds_read_b128 v[182:185], v225 offset:5120
	ds_read_b128 v[186:189], v225 offset:6144
	ds_read_b128 v[210:213], v225 offset:7168
	global_load_lds_dwordx4 v[226:227], off
	v_lshl_add_u64 v[226:227], s[8:9], 0, v[208:209]
	s_add_i32 m0, s16, 0xe000
	s_nop 0
	global_load_lds_dwordx4 v[226:227], off
	s_waitcnt vmcnt(8)
	s_waitcnt lgkmcnt(0)
	s_barrier
	s_setprio 1
	s_waitcnt lgkmcnt(0)
	v_mfma_f32_16x16x32_bf16 v[158:161], v[88:91], v[162:165], v[158:161]
	v_mfma_f32_16x16x32_bf16 v[150:153], v[104:107], v[162:165], v[150:153]
	v_mfma_f32_16x16x32_bf16 v[124:127], v[88:91], v[170:173], v[124:127]
	v_mfma_f32_16x16x32_bf16 v[120:123], v[104:107], v[170:173], v[120:123]
	v_mfma_f32_16x16x32_bf16 v[100:103], v[88:91], v[178:181], v[100:103]
	v_mfma_f32_16x16x32_bf16 v[96:99], v[104:107], v[178:181], v[96:99]
	v_mfma_f32_16x16x32_bf16 v[76:79], v[88:91], v[186:189], v[76:79]
	v_mfma_f32_16x16x32_bf16 v[72:75], v[104:107], v[186:189], v[72:75]
	v_mfma_f32_16x16x32_bf16 v[158:161], v[92:95], v[166:169], v[158:161]
	v_mfma_f32_16x16x32_bf16 v[150:153], v[116:119], v[166:169], v[150:153]
	v_mfma_f32_16x16x32_bf16 v[124:127], v[92:95], v[174:177], v[124:127]
	v_mfma_f32_16x16x32_bf16 v[120:123], v[116:119], v[174:177], v[120:123]
	v_mfma_f32_16x16x32_bf16 v[100:103], v[92:95], v[182:185], v[100:103]
	v_mfma_f32_16x16x32_bf16 v[96:99], v[116:119], v[182:185], v[96:99]
	v_mfma_f32_16x16x32_bf16 v[76:79], v[92:95], v[210:213], v[76:79]
	v_mfma_f32_16x16x32_bf16 v[72:75], v[116:119], v[210:213], v[72:75]
	v_mfma_f32_16x16x32_bf16 v[142:145], v[130:133], v[162:165], v[142:145]
	v_mfma_f32_16x16x32_bf16 v[134:137], v[146:149], v[162:165], v[134:137]
	v_mfma_f32_16x16x32_bf16 v[112:115], v[130:133], v[170:173], v[112:115]
	v_mfma_f32_16x16x32_bf16 v[108:111], v[146:149], v[170:173], v[108:111]
	v_mfma_f32_16x16x32_bf16 v[84:87], v[130:133], v[178:181], v[84:87]
	v_mfma_f32_16x16x32_bf16 v[80:83], v[146:149], v[178:181], v[80:83]
	v_mfma_f32_16x16x32_bf16 v[68:71], v[130:133], v[186:189], v[68:71]
	v_mfma_f32_16x16x32_bf16 v[64:67], v[146:149], v[186:189], v[64:67]
	v_mfma_f32_16x16x32_bf16 v[142:145], v[138:141], v[166:169], v[142:145]
	v_mfma_f32_16x16x32_bf16 v[134:137], v[154:157], v[166:169], v[134:137]
	v_mfma_f32_16x16x32_bf16 v[112:115], v[138:141], v[174:177], v[112:115]
	v_mfma_f32_16x16x32_bf16 v[108:111], v[154:157], v[174:177], v[108:111]
	v_mfma_f32_16x16x32_bf16 v[84:87], v[138:141], v[182:185], v[84:87]
	v_mfma_f32_16x16x32_bf16 v[80:83], v[154:157], v[182:185], v[80:83]
	v_mfma_f32_16x16x32_bf16 v[68:71], v[138:141], v[210:213], v[68:71]
	v_mfma_f32_16x16x32_bf16 v[64:67], v[154:157], v[210:213], v[64:67]
	s_setprio 0
	s_barrier
	s_add_i32 s24, s24, s14
	v_lshl_add_u64 v[226:227], s[10:11], 0, v[128:129]
	s_mov_b32 m0, s24
	ds_read_b128 v[162:165], v225 offset:16384
	ds_read_b128 v[166:169], v225 offset:17408
	ds_read_b128 v[170:173], v225 offset:18432
	ds_read_b128 v[174:177], v225 offset:19456
	ds_read_b128 v[178:181], v225 offset:20480
	ds_read_b128 v[182:185], v225 offset:21504
	ds_read_b128 v[186:189], v225 offset:22528
	ds_read_b128 v[210:213], v225 offset:23552
	global_load_lds_dwordx4 v[226:227], off
	s_add_i32 m0, s24, 0x2000
	s_add_u32 s24, s10, 0x20000
	v_lshl_add_u64 v[228:229], s[10:11], 0, v[200:201]
	s_addc_u32 s25, s11, 0
	s_add_i32 s28, s28, s14
	global_load_lds_dwordx4 v[228:229], off
	v_lshl_add_u64 v[230:231], s[24:25], 0, v[128:129]
	s_mov_b32 m0, s28
	v_lshl_add_u64 v[232:233], s[12:13], 0, v[202:203]
	global_load_lds_dwordx4 v[230:231], off
	v_lshl_add_u64 v[230:231], s[24:25], 0, v[200:201]
	s_add_i32 m0, s28, 0x2000
	s_nop 0
	global_load_lds_dwordx4 v[230:231], off
	v_lshl_add_u64 v[230:231], s[12:13], 0, v[204:205]
	s_mov_b32 m0, s16
	s_nop 0
	global_load_lds_dwordx4 v[230:231], off
	s_mov_b32 m0, s17
	s_nop 0
	global_load_lds_dwordx4 v[232:233], off
	s_waitcnt vmcnt(8)
	s_waitcnt lgkmcnt(0)
	s_barrier
	s_setprio 1
	s_waitcnt lgkmcnt(0)
	v_mfma_f32_16x16x32_bf16 v[60:63], v[88:91], v[162:165], v[60:63]
	v_mfma_f32_16x16x32_bf16 v[56:59], v[104:107], v[162:165], v[56:59]
	v_mfma_f32_16x16x32_bf16 v[44:47], v[88:91], v[170:173], v[44:47]
	v_mfma_f32_16x16x32_bf16 v[40:43], v[104:107], v[170:173], v[40:43]
	v_mfma_f32_16x16x32_bf16 v[28:31], v[88:91], v[178:181], v[28:31]
	v_mfma_f32_16x16x32_bf16 v[24:27], v[104:107], v[178:181], v[24:27]
	v_mfma_f32_16x16x32_bf16 v[12:15], v[88:91], v[186:189], v[12:15]
	v_mfma_f32_16x16x32_bf16 v[8:11], v[104:107], v[186:189], v[8:11]
	v_mfma_f32_16x16x32_bf16 v[60:63], v[92:95], v[166:169], v[60:63]
	v_mfma_f32_16x16x32_bf16 v[56:59], v[116:119], v[166:169], v[56:59]
	v_mfma_f32_16x16x32_bf16 v[44:47], v[92:95], v[174:177], v[44:47]
	v_mfma_f32_16x16x32_bf16 v[40:43], v[116:119], v[174:177], v[40:43]
	v_mfma_f32_16x16x32_bf16 v[28:31], v[92:95], v[182:185], v[28:31]
	v_mfma_f32_16x16x32_bf16 v[24:27], v[116:119], v[182:185], v[24:27]
	v_mfma_f32_16x16x32_bf16 v[12:15], v[92:95], v[210:213], v[12:15]
	v_mfma_f32_16x16x32_bf16 v[8:11], v[116:119], v[210:213], v[8:11]
	v_mfma_f32_16x16x32_bf16 v[52:55], v[130:133], v[162:165], v[52:55]
	v_mfma_f32_16x16x32_bf16 v[48:51], v[146:149], v[162:165], v[48:51]
	v_mfma_f32_16x16x32_bf16 v[36:39], v[130:133], v[170:173], v[36:39]
	v_mfma_f32_16x16x32_bf16 v[32:35], v[146:149], v[170:173], v[32:35]
	v_mfma_f32_16x16x32_bf16 v[20:23], v[130:133], v[178:181], v[20:23]
	v_mfma_f32_16x16x32_bf16 v[16:19], v[146:149], v[178:181], v[16:19]
	v_mfma_f32_16x16x32_bf16 v[4:7], v[130:133], v[186:189], v[4:7]
	v_mfma_f32_16x16x32_bf16 v[0:3], v[146:149], v[186:189], v[0:3]
	v_mfma_f32_16x16x32_bf16 v[52:55], v[138:141], v[166:169], v[52:55]
	v_mfma_f32_16x16x32_bf16 v[48:51], v[154:157], v[166:169], v[48:51]
	v_mfma_f32_16x16x32_bf16 v[36:39], v[138:141], v[174:177], v[36:39]
	v_mfma_f32_16x16x32_bf16 v[32:35], v[154:157], v[174:177], v[32:35]
	v_mfma_f32_16x16x32_bf16 v[20:23], v[138:141], v[182:185], v[20:23]
	v_mfma_f32_16x16x32_bf16 v[16:19], v[154:157], v[182:185], v[16:19]
	v_mfma_f32_16x16x32_bf16 v[4:7], v[138:141], v[210:213], v[4:7]
	v_mfma_f32_16x16x32_bf16 v[0:3], v[154:157], v[210:213], v[0:3]
	s_setprio 0
	s_barrier
	s_add_i32 s24, 0, 0x18000
	s_add_i32 s25, 0, 0x1c000
	v_add_u32_e32 v116, s24, v223
	v_add_u32_e32 v154, s25, v223
	ds_read_b128 v[88:91], v116
	ds_read_b128 v[92:95], v116 offset:1024
	ds_read_b128 v[104:107], v116 offset:2048
	ds_read_b128 v[116:119], v116 offset:3072
	ds_read_b128 v[130:133], v154
	ds_read_b128 v[138:141], v154 offset:1024
	ds_read_b128 v[146:149], v154 offset:2048
	ds_read_b128 v[154:157], v154 offset:3072
	s_add_u32 s12, s12, 0x20000
	s_addc_u32 s13, s13, 0
	s_mov_b32 m0, s18
	v_lshl_add_u64 v[234:235], s[12:13], 0, v[204:205]
	ds_read_b128 v[162:165], v225 offset:32768
	ds_read_b128 v[166:169], v225 offset:33792
	ds_read_b128 v[170:173], v225 offset:34816
	ds_read_b128 v[174:177], v225 offset:35840
	ds_read_b128 v[178:181], v225 offset:36864
	ds_read_b128 v[182:185], v225 offset:37888
	ds_read_b128 v[186:189], v225 offset:38912
	ds_read_b128 v[210:213], v225 offset:39936
	global_load_lds_dwordx4 v[234:235], off
	v_lshl_add_u64 v[234:235], s[12:13], 0, v[202:203]
	s_mov_b32 m0, s19
	s_nop 0
	global_load_lds_dwordx4 v[234:235], off
	s_waitcnt vmcnt(8)
	s_waitcnt lgkmcnt(0)
	s_barrier
	s_setprio 1
	s_waitcnt lgkmcnt(0)
	v_mfma_f32_16x16x32_bf16 v[158:161], v[88:91], v[162:165], v[158:161]
	v_mfma_f32_16x16x32_bf16 v[150:153], v[104:107], v[162:165], v[150:153]
	v_mfma_f32_16x16x32_bf16 v[124:127], v[88:91], v[170:173], v[124:127]
	v_mfma_f32_16x16x32_bf16 v[120:123], v[104:107], v[170:173], v[120:123]
	v_mfma_f32_16x16x32_bf16 v[100:103], v[88:91], v[178:181], v[100:103]
	v_mfma_f32_16x16x32_bf16 v[96:99], v[104:107], v[178:181], v[96:99]
	v_mfma_f32_16x16x32_bf16 v[76:79], v[88:91], v[186:189], v[76:79]
	v_mfma_f32_16x16x32_bf16 v[72:75], v[104:107], v[186:189], v[72:75]
	v_mfma_f32_16x16x32_bf16 v[158:161], v[92:95], v[166:169], v[158:161]
	v_mfma_f32_16x16x32_bf16 v[150:153], v[116:119], v[166:169], v[150:153]
	v_mfma_f32_16x16x32_bf16 v[124:127], v[92:95], v[174:177], v[124:127]
	v_mfma_f32_16x16x32_bf16 v[120:123], v[116:119], v[174:177], v[120:123]
	v_mfma_f32_16x16x32_bf16 v[100:103], v[92:95], v[182:185], v[100:103]
	v_mfma_f32_16x16x32_bf16 v[96:99], v[116:119], v[182:185], v[96:99]
	v_mfma_f32_16x16x32_bf16 v[76:79], v[92:95], v[210:213], v[76:79]
	v_mfma_f32_16x16x32_bf16 v[72:75], v[116:119], v[210:213], v[72:75]
	v_mfma_f32_16x16x32_bf16 v[142:145], v[130:133], v[162:165], v[142:145]
	v_mfma_f32_16x16x32_bf16 v[134:137], v[146:149], v[162:165], v[134:137]
	v_mfma_f32_16x16x32_bf16 v[112:115], v[130:133], v[170:173], v[112:115]
	v_mfma_f32_16x16x32_bf16 v[108:111], v[146:149], v[170:173], v[108:111]
	v_mfma_f32_16x16x32_bf16 v[84:87], v[130:133], v[178:181], v[84:87]
	v_mfma_f32_16x16x32_bf16 v[80:83], v[146:149], v[178:181], v[80:83]
	v_mfma_f32_16x16x32_bf16 v[68:71], v[130:133], v[186:189], v[68:71]
	v_mfma_f32_16x16x32_bf16 v[64:67], v[146:149], v[186:189], v[64:67]
	v_mfma_f32_16x16x32_bf16 v[142:145], v[138:141], v[166:169], v[142:145]
	v_mfma_f32_16x16x32_bf16 v[134:137], v[154:157], v[166:169], v[134:137]
	v_mfma_f32_16x16x32_bf16 v[112:115], v[138:141], v[174:177], v[112:115]
	v_mfma_f32_16x16x32_bf16 v[108:111], v[154:157], v[174:177], v[108:111]
	v_mfma_f32_16x16x32_bf16 v[84:87], v[138:141], v[182:185], v[84:87]
	v_mfma_f32_16x16x32_bf16 v[80:83], v[154:157], v[182:185], v[80:83]
	v_mfma_f32_16x16x32_bf16 v[68:71], v[138:141], v[210:213], v[68:71]
	v_mfma_f32_16x16x32_bf16 v[64:67], v[154:157], v[210:213], v[64:67]
	s_setprio 0
	s_barrier
	s_add_i32 s12, s24, s14
	v_lshl_add_u64 v[226:227], v[226:227], 0, s[26:27]
	s_mov_b32 m0, s12
	ds_read_b128 v[162:165], v225 offset:49152
	ds_read_b128 v[166:169], v225 offset:50176
	ds_read_b128 v[170:173], v225 offset:51200
	ds_read_b128 v[174:177], v225 offset:52224
	ds_read_b128 v[178:181], v225 offset:53248
	ds_read_b128 v[182:185], v225 offset:54272
	ds_read_b128 v[186:189], v225 offset:55296
	ds_read_b128 v[210:213], v225 offset:56320
	global_load_lds_dwordx4 v[226:227], off
	s_add_i32 m0, s12, 0x2000
	s_add_u32 s10, s10, 0x20080
	v_lshl_add_u64 v[226:227], v[228:229], 0, s[26:27]
	s_addc_u32 s11, s11, 0
	s_add_i32 s12, s25, s14
	global_load_lds_dwordx4 v[226:227], off
	v_lshl_add_u64 v[226:227], s[10:11], 0, v[128:129]
	s_mov_b32 m0, s12
	s_nop 0
	global_load_lds_dwordx4 v[226:227], off
	v_lshl_add_u64 v[226:227], s[10:11], 0, v[200:201]
	s_add_i32 m0, s12, 0x2000
	s_nop 0
	global_load_lds_dwordx4 v[226:227], off
	v_lshl_add_u64 v[226:227], v[230:231], 0, s[26:27]
	s_mov_b32 m0, s20
	s_nop 0
	global_load_lds_dwordx4 v[226:227], off
	v_lshl_add_u64 v[226:227], v[232:233], 0, s[26:27]
	s_mov_b32 m0, s21
	s_nop 0
	global_load_lds_dwordx4 v[226:227], off
	s_waitcnt vmcnt(8)
	s_waitcnt lgkmcnt(0)
	s_barrier
	s_setprio 1
	s_waitcnt lgkmcnt(0)
	v_mfma_f32_16x16x32_bf16 v[60:63], v[88:91], v[162:165], v[60:63]
	v_mfma_f32_16x16x32_bf16 v[56:59], v[104:107], v[162:165], v[56:59]
	v_mfma_f32_16x16x32_bf16 v[44:47], v[88:91], v[170:173], v[44:47]
	v_mfma_f32_16x16x32_bf16 v[40:43], v[104:107], v[170:173], v[40:43]
	v_mfma_f32_16x16x32_bf16 v[28:31], v[88:91], v[178:181], v[28:31]
	v_mfma_f32_16x16x32_bf16 v[24:27], v[104:107], v[178:181], v[24:27]
	v_mfma_f32_16x16x32_bf16 v[12:15], v[88:91], v[186:189], v[12:15]
	v_mfma_f32_16x16x32_bf16 v[8:11], v[104:107], v[186:189], v[8:11]
	v_mfma_f32_16x16x32_bf16 v[60:63], v[92:95], v[166:169], v[60:63]
	v_mfma_f32_16x16x32_bf16 v[56:59], v[116:119], v[166:169], v[56:59]
	v_mfma_f32_16x16x32_bf16 v[44:47], v[92:95], v[174:177], v[44:47]
	v_mfma_f32_16x16x32_bf16 v[40:43], v[116:119], v[174:177], v[40:43]
	v_mfma_f32_16x16x32_bf16 v[28:31], v[92:95], v[182:185], v[28:31]
	v_mfma_f32_16x16x32_bf16 v[24:27], v[116:119], v[182:185], v[24:27]
	v_mfma_f32_16x16x32_bf16 v[12:15], v[92:95], v[210:213], v[12:15]
	v_mfma_f32_16x16x32_bf16 v[8:11], v[116:119], v[210:213], v[8:11]
	v_mfma_f32_16x16x32_bf16 v[52:55], v[130:133], v[162:165], v[52:55]
	v_mfma_f32_16x16x32_bf16 v[48:51], v[146:149], v[162:165], v[48:51]
	v_mfma_f32_16x16x32_bf16 v[36:39], v[130:133], v[170:173], v[36:39]
	v_mfma_f32_16x16x32_bf16 v[32:35], v[146:149], v[170:173], v[32:35]
	v_mfma_f32_16x16x32_bf16 v[20:23], v[130:133], v[178:181], v[20:23]
	v_mfma_f32_16x16x32_bf16 v[16:19], v[146:149], v[178:181], v[16:19]
	v_mfma_f32_16x16x32_bf16 v[4:7], v[130:133], v[186:189], v[4:7]
	v_mfma_f32_16x16x32_bf16 v[0:3], v[146:149], v[186:189], v[0:3]
	v_mfma_f32_16x16x32_bf16 v[52:55], v[138:141], v[166:169], v[52:55]
	v_mfma_f32_16x16x32_bf16 v[48:51], v[154:157], v[166:169], v[48:51]
	v_mfma_f32_16x16x32_bf16 v[36:39], v[138:141], v[174:177], v[36:39]
	v_mfma_f32_16x16x32_bf16 v[32:35], v[154:157], v[174:177], v[32:35]
	v_mfma_f32_16x16x32_bf16 v[20:23], v[138:141], v[182:185], v[20:23]
	v_mfma_f32_16x16x32_bf16 v[16:19], v[154:157], v[182:185], v[16:19]
	v_mfma_f32_16x16x32_bf16 v[4:7], v[138:141], v[210:213], v[4:7]
	v_mfma_f32_16x16x32_bf16 v[0:3], v[154:157], v[210:213], v[0:3]
	s_setprio 0
	s_barrier
	s_add_i32 s85, s85, 2
	s_add_u32 s8, s8, 0x100
	s_addc_u32 s9, s9, 0
	s_add_u32 s75, s75, 0x100
	s_addc_u32 s84, s84, 0
	s_cmp_gt_u32 s85, 5
	s_cbranch_scc0 .LBB0_1384
	s_nop 0
	s_nop 0
	s_nop 0
	s_nop 0
	s_nop 0
	s_nop 0
	s_nop 0
	s_nop 0
	s_and_b64 vcc, exec, s[6:7]
	s_cbranch_vccz .LBB0_1387
	s_barrier

.LBB0_1486:
	s_add_u32 s8, s6, 0xfff80080
	s_addc_u32 s9, s7, -1
	s_add_i32 s24, 0, 0x10000
	s_cmp_eq_u32 s84, 28
	s_cselect_b32 s11, s18, s9
	s_cselect_b32 s10, s72, s8
	v_add_u32_e32 v144, s24, v147
	s_cselect_b32 s9, s45, s75
	s_cselect_b32 s8, s73, s74
	s_add_i32 s28, 0, 0x14000
	ds_read_b128 v[140:143], v144
	ds_read_b128 v[150:153], v144 offset:1024
	ds_read_b128 v[154:157], v144 offset:2048
	ds_read_b128 v[158:161], v144 offset:3072
	v_add_u32_e32 v144, s28, v147
	ds_read_b128 v[162:165], v144
	ds_read_b128 v[166:169], v144 offset:1024
	ds_read_b128 v[170:173], v144 offset:2048
	ds_read_b128 v[174:177], v144 offset:3072
	v_lshl_add_u64 v[144:145], s[6:7], 0, v[136:137]
	s_add_i32 m0, s19, 0xc000
	ds_read_b128 v[178:181], v149
	ds_read_b128 v[182:185], v149 offset:1024
	ds_read_b128 v[186:189], v149 offset:2048
	ds_read_b128 v[200:203], v149 offset:3072
	ds_read_b128 v[204:207], v149 offset:4096
	ds_read_b128 v[208:211], v149 offset:5120
	ds_read_b128 v[222:225], v149 offset:6144
	ds_read_b128 v[226:229], v149 offset:7168
	global_load_lds_dwordx4 v[144:145], off
	v_lshl_add_u64 v[144:145], s[6:7], 0, v[138:139]
	s_add_i32 m0, s19, 0xe000
	s_nop 0
	global_load_lds_dwordx4 v[144:145], off
	s_waitcnt vmcnt(8)
	s_waitcnt lgkmcnt(0)
	s_barrier
	s_setprio 1
	s_waitcnt lgkmcnt(0)
	v_mfma_f32_16x16x32_bf16 v[124:127], v[140:143], v[178:181], v[124:127]
	v_mfma_f32_16x16x32_bf16 v[120:123], v[154:157], v[178:181], v[120:123]
	v_mfma_f32_16x16x32_bf16 v[108:111], v[140:143], v[186:189], v[108:111]
	v_mfma_f32_16x16x32_bf16 v[104:107], v[154:157], v[186:189], v[104:107]
	v_mfma_f32_16x16x32_bf16 v[92:95], v[140:143], v[204:207], v[92:95]
	v_mfma_f32_16x16x32_bf16 v[88:91], v[154:157], v[204:207], v[88:91]
	v_mfma_f32_16x16x32_bf16 v[76:79], v[140:143], v[222:225], v[76:79]
	v_mfma_f32_16x16x32_bf16 v[72:75], v[154:157], v[222:225], v[72:75]
	v_mfma_f32_16x16x32_bf16 v[124:127], v[150:153], v[182:185], v[124:127]
	v_mfma_f32_16x16x32_bf16 v[120:123], v[158:161], v[182:185], v[120:123]
	v_mfma_f32_16x16x32_bf16 v[108:111], v[150:153], v[200:203], v[108:111]
	v_mfma_f32_16x16x32_bf16 v[104:107], v[158:161], v[200:203], v[104:107]
	v_mfma_f32_16x16x32_bf16 v[92:95], v[150:153], v[208:211], v[92:95]
	v_mfma_f32_16x16x32_bf16 v[88:91], v[158:161], v[208:211], v[88:91]
	v_mfma_f32_16x16x32_bf16 v[76:79], v[150:153], v[226:229], v[76:79]
	v_mfma_f32_16x16x32_bf16 v[72:75], v[158:161], v[226:229], v[72:75]
	v_mfma_f32_16x16x32_bf16 v[116:119], v[162:165], v[178:181], v[116:119]
	v_mfma_f32_16x16x32_bf16 v[112:115], v[170:173], v[178:181], v[112:115]
	v_mfma_f32_16x16x32_bf16 v[100:103], v[162:165], v[186:189], v[100:103]
	v_mfma_f32_16x16x32_bf16 v[96:99], v[170:173], v[186:189], v[96:99]
	v_mfma_f32_16x16x32_bf16 v[84:87], v[162:165], v[204:207], v[84:87]
	v_mfma_f32_16x16x32_bf16 v[80:83], v[170:173], v[204:207], v[80:83]
	v_mfma_f32_16x16x32_bf16 v[68:71], v[162:165], v[222:225], v[68:71]
	v_mfma_f32_16x16x32_bf16 v[64:67], v[170:173], v[222:225], v[64:67]
	v_mfma_f32_16x16x32_bf16 v[116:119], v[166:169], v[182:185], v[116:119]
	v_mfma_f32_16x16x32_bf16 v[112:115], v[174:177], v[182:185], v[112:115]
	v_mfma_f32_16x16x32_bf16 v[100:103], v[166:169], v[200:203], v[100:103]
	v_mfma_f32_16x16x32_bf16 v[96:99], v[174:177], v[200:203], v[96:99]
	v_mfma_f32_16x16x32_bf16 v[84:87], v[166:169], v[208:211], v[84:87]
	v_mfma_f32_16x16x32_bf16 v[80:83], v[174:177], v[208:211], v[80:83]
	v_mfma_f32_16x16x32_bf16 v[68:71], v[166:169], v[226:229], v[68:71]
	v_mfma_f32_16x16x32_bf16 v[64:67], v[174:177], v[226:229], v[64:67]
	s_setprio 0
	s_barrier
	s_add_i32 s24, s24, s12
	v_lshl_add_u64 v[144:145], s[8:9], 0, v[128:129]
	s_mov_b32 m0, s24
	ds_read_b128 v[178:181], v149 offset:16384
	ds_read_b128 v[182:185], v149 offset:17408
	ds_read_b128 v[186:189], v149 offset:18432
	ds_read_b128 v[200:203], v149 offset:19456
	ds_read_b128 v[204:207], v149 offset:20480
	ds_read_b128 v[208:211], v149 offset:21504
	ds_read_b128 v[222:225], v149 offset:22528
	ds_read_b128 v[226:229], v149 offset:23552
	global_load_lds_dwordx4 v[144:145], off
	s_add_i32 m0, s24, 0x2000
	s_add_u32 s24, s8, 0x80000
	v_lshl_add_u64 v[212:213], s[8:9], 0, v[130:131]
	s_addc_u32 s25, s9, 0
	s_add_i32 s28, s28, s12
	global_load_lds_dwordx4 v[212:213], off
	v_lshl_add_u64 v[230:231], s[24:25], 0, v[128:129]
	s_mov_b32 m0, s28
	v_lshl_add_u64 v[232:233], s[10:11], 0, v[132:133]
	global_load_lds_dwordx4 v[230:231], off
	v_lshl_add_u64 v[230:231], s[24:25], 0, v[130:131]
	s_add_i32 m0, s28, 0x2000
	s_nop 0
	global_load_lds_dwordx4 v[230:231], off
	v_lshl_add_u64 v[230:231], s[10:11], 0, v[134:135]
	s_mov_b32 m0, s19
	s_nop 0
	global_load_lds_dwordx4 v[230:231], off
	s_mov_b32 m0, s20
	s_nop 0
	global_load_lds_dwordx4 v[232:233], off
	s_waitcnt vmcnt(8)
	s_waitcnt lgkmcnt(0)
	s_barrier
	s_setprio 1
	s_waitcnt lgkmcnt(0)
	v_mfma_f32_16x16x32_bf16 v[60:63], v[140:143], v[178:181], v[60:63]
	v_mfma_f32_16x16x32_bf16 v[56:59], v[154:157], v[178:181], v[56:59]
	v_mfma_f32_16x16x32_bf16 v[44:47], v[140:143], v[186:189], v[44:47]
	v_mfma_f32_16x16x32_bf16 v[40:43], v[154:157], v[186:189], v[40:43]
	v_mfma_f32_16x16x32_bf16 v[28:31], v[140:143], v[204:207], v[28:31]
	v_mfma_f32_16x16x32_bf16 v[24:27], v[154:157], v[204:207], v[24:27]
	v_mfma_f32_16x16x32_bf16 v[12:15], v[140:143], v[222:225], v[12:15]
	v_mfma_f32_16x16x32_bf16 v[8:11], v[154:157], v[222:225], v[8:11]
	v_mfma_f32_16x16x32_bf16 v[60:63], v[150:153], v[182:185], v[60:63]
	v_mfma_f32_16x16x32_bf16 v[56:59], v[158:161], v[182:185], v[56:59]
	v_mfma_f32_16x16x32_bf16 v[44:47], v[150:153], v[200:203], v[44:47]
	v_mfma_f32_16x16x32_bf16 v[40:43], v[158:161], v[200:203], v[40:43]
	v_mfma_f32_16x16x32_bf16 v[28:31], v[150:153], v[208:211], v[28:31]
	v_mfma_f32_16x16x32_bf16 v[24:27], v[158:161], v[208:211], v[24:27]
	v_mfma_f32_16x16x32_bf16 v[12:15], v[150:153], v[226:229], v[12:15]
	v_mfma_f32_16x16x32_bf16 v[8:11], v[158:161], v[226:229], v[8:11]
	v_mfma_f32_16x16x32_bf16 v[52:55], v[162:165], v[178:181], v[52:55]
	v_mfma_f32_16x16x32_bf16 v[48:51], v[170:173], v[178:181], v[48:51]
	v_mfma_f32_16x16x32_bf16 v[36:39], v[162:165], v[186:189], v[36:39]
	v_mfma_f32_16x16x32_bf16 v[32:35], v[170:173], v[186:189], v[32:35]
	v_mfma_f32_16x16x32_bf16 v[20:23], v[162:165], v[204:207], v[20:23]
	v_mfma_f32_16x16x32_bf16 v[16:19], v[170:173], v[204:207], v[16:19]
	v_mfma_f32_16x16x32_bf16 v[4:7], v[162:165], v[222:225], v[4:7]
	v_mfma_f32_16x16x32_bf16 v[0:3], v[170:173], v[222:225], v[0:3]
	v_mfma_f32_16x16x32_bf16 v[52:55], v[166:169], v[182:185], v[52:55]
	v_mfma_f32_16x16x32_bf16 v[48:51], v[174:177], v[182:185], v[48:51]
	v_mfma_f32_16x16x32_bf16 v[36:39], v[166:169], v[200:203], v[36:39]
	v_mfma_f32_16x16x32_bf16 v[32:35], v[174:177], v[200:203], v[32:35]
	v_mfma_f32_16x16x32_bf16 v[20:23], v[166:169], v[208:211], v[20:23]
	v_mfma_f32_16x16x32_bf16 v[16:19], v[174:177], v[208:211], v[16:19]
	v_mfma_f32_16x16x32_bf16 v[4:7], v[166:169], v[226:229], v[4:7]
	v_mfma_f32_16x16x32_bf16 v[0:3], v[174:177], v[226:229], v[0:3]
	s_setprio 0
	s_barrier
	s_add_i32 s24, 0, 0x18000
	s_add_i32 s25, 0, 0x1c000
	v_add_u32_e32 v158, s24, v147
	v_add_u32_e32 v174, s25, v147
	ds_read_b128 v[140:143], v158
	ds_read_b128 v[150:153], v158 offset:1024
	ds_read_b128 v[154:157], v158 offset:2048
	ds_read_b128 v[158:161], v158 offset:3072
	ds_read_b128 v[162:165], v174
	ds_read_b128 v[166:169], v174 offset:1024
	ds_read_b128 v[170:173], v174 offset:2048
	ds_read_b128 v[174:177], v174 offset:3072
	s_add_u32 s10, s10, 0x80000
	s_addc_u32 s11, s11, 0
	s_mov_b32 m0, s33
	v_lshl_add_u64 v[234:235], s[10:11], 0, v[134:135]
	ds_read_b128 v[178:181], v149 offset:32768
	ds_read_b128 v[182:185], v149 offset:33792
	ds_read_b128 v[186:189], v149 offset:34816
	ds_read_b128 v[200:203], v149 offset:35840
	ds_read_b128 v[204:207], v149 offset:36864
	ds_read_b128 v[208:211], v149 offset:37888
	ds_read_b128 v[222:225], v149 offset:38912
	ds_read_b128 v[226:229], v149 offset:39936
	global_load_lds_dwordx4 v[234:235], off
	v_lshl_add_u64 v[234:235], s[10:11], 0, v[132:133]
	s_mov_b32 m0, s0
	s_nop 0
	global_load_lds_dwordx4 v[234:235], off
	s_waitcnt vmcnt(8)
	s_waitcnt lgkmcnt(0)
	s_barrier
	s_setprio 1
	s_waitcnt lgkmcnt(0)
	v_mfma_f32_16x16x32_bf16 v[124:127], v[140:143], v[178:181], v[124:127]
	v_mfma_f32_16x16x32_bf16 v[120:123], v[154:157], v[178:181], v[120:123]
	v_mfma_f32_16x16x32_bf16 v[108:111], v[140:143], v[186:189], v[108:111]
	v_mfma_f32_16x16x32_bf16 v[104:107], v[154:157], v[186:189], v[104:107]
	v_mfma_f32_16x16x32_bf16 v[92:95], v[140:143], v[204:207], v[92:95]
	v_mfma_f32_16x16x32_bf16 v[88:91], v[154:157], v[204:207], v[88:91]
	v_mfma_f32_16x16x32_bf16 v[76:79], v[140:143], v[222:225], v[76:79]
	v_mfma_f32_16x16x32_bf16 v[72:75], v[154:157], v[222:225], v[72:75]
	v_mfma_f32_16x16x32_bf16 v[124:127], v[150:153], v[182:185], v[124:127]
	v_mfma_f32_16x16x32_bf16 v[120:123], v[158:161], v[182:185], v[120:123]
	v_mfma_f32_16x16x32_bf16 v[108:111], v[150:153], v[200:203], v[108:111]
	v_mfma_f32_16x16x32_bf16 v[104:107], v[158:161], v[200:203], v[104:107]
	v_mfma_f32_16x16x32_bf16 v[92:95], v[150:153], v[208:211], v[92:95]
	v_mfma_f32_16x16x32_bf16 v[88:91], v[158:161], v[208:211], v[88:91]
	v_mfma_f32_16x16x32_bf16 v[76:79], v[150:153], v[226:229], v[76:79]
	v_mfma_f32_16x16x32_bf16 v[72:75], v[158:161], v[226:229], v[72:75]
	v_mfma_f32_16x16x32_bf16 v[116:119], v[162:165], v[178:181], v[116:119]
	v_mfma_f32_16x16x32_bf16 v[112:115], v[170:173], v[178:181], v[112:115]
	v_mfma_f32_16x16x32_bf16 v[100:103], v[162:165], v[186:189], v[100:103]
	v_mfma_f32_16x16x32_bf16 v[96:99], v[170:173], v[186:189], v[96:99]
	v_mfma_f32_16x16x32_bf16 v[84:87], v[162:165], v[204:207], v[84:87]
	v_mfma_f32_16x16x32_bf16 v[80:83], v[170:173], v[204:207], v[80:83]
	v_mfma_f32_16x16x32_bf16 v[68:71], v[162:165], v[222:225], v[68:71]
	v_mfma_f32_16x16x32_bf16 v[64:67], v[170:173], v[222:225], v[64:67]
	v_mfma_f32_16x16x32_bf16 v[116:119], v[166:169], v[182:185], v[116:119]
	v_mfma_f32_16x16x32_bf16 v[112:115], v[174:177], v[182:185], v[112:115]
	v_mfma_f32_16x16x32_bf16 v[100:103], v[166:169], v[200:203], v[100:103]
	v_mfma_f32_16x16x32_bf16 v[96:99], v[174:177], v[200:203], v[96:99]
	v_mfma_f32_16x16x32_bf16 v[84:87], v[166:169], v[208:211], v[84:87]
	v_mfma_f32_16x16x32_bf16 v[80:83], v[174:177], v[208:211], v[80:83]
	v_mfma_f32_16x16x32_bf16 v[68:71], v[166:169], v[226:229], v[68:71]
	v_mfma_f32_16x16x32_bf16 v[64:67], v[174:177], v[226:229], v[64:67]
	s_setprio 0
	s_barrier
	s_add_i32 s10, s24, s12
	v_lshl_add_u64 v[144:145], v[144:145], 0, s[26:27]
	s_mov_b32 m0, s10
	ds_read_b128 v[178:181], v149 offset:49152
	ds_read_b128 v[182:185], v149 offset:50176
	ds_read_b128 v[186:189], v149 offset:51200
	ds_read_b128 v[200:203], v149 offset:52224
	ds_read_b128 v[204:207], v149 offset:53248
	ds_read_b128 v[208:211], v149 offset:54272
	ds_read_b128 v[222:225], v149 offset:55296
	ds_read_b128 v[226:229], v149 offset:56320
	global_load_lds_dwordx4 v[144:145], off
	s_add_i32 m0, s10, 0x2000
	s_add_u32 s8, s8, 0x80080
	v_lshl_add_u64 v[144:145], v[212:213], 0, s[26:27]
	s_addc_u32 s9, s9, 0
	s_add_i32 s10, s25, s12
	global_load_lds_dwordx4 v[144:145], off
	v_lshl_add_u64 v[144:145], s[8:9], 0, v[128:129]
	s_mov_b32 m0, s10
	s_nop 0
	global_load_lds_dwordx4 v[144:145], off
	v_lshl_add_u64 v[144:145], s[8:9], 0, v[130:131]
	s_add_i32 m0, s10, 0x2000
	s_nop 0
	global_load_lds_dwordx4 v[144:145], off
	v_lshl_add_u64 v[144:145], v[230:231], 0, s[26:27]
	s_mov_b32 m0, s1
	s_nop 0
	global_load_lds_dwordx4 v[144:145], off
	v_lshl_add_u64 v[144:145], v[232:233], 0, s[26:27]
	s_mov_b32 m0, s17
	s_nop 0
	global_load_lds_dwordx4 v[144:145], off
	s_waitcnt vmcnt(8)
	s_waitcnt lgkmcnt(0)
	s_barrier
	s_setprio 1
	s_waitcnt lgkmcnt(0)
	v_mfma_f32_16x16x32_bf16 v[60:63], v[140:143], v[178:181], v[60:63]
	v_mfma_f32_16x16x32_bf16 v[56:59], v[154:157], v[178:181], v[56:59]
	v_mfma_f32_16x16x32_bf16 v[44:47], v[140:143], v[186:189], v[44:47]
	v_mfma_f32_16x16x32_bf16 v[40:43], v[154:157], v[186:189], v[40:43]
	v_mfma_f32_16x16x32_bf16 v[28:31], v[140:143], v[204:207], v[28:31]
	v_mfma_f32_16x16x32_bf16 v[24:27], v[154:157], v[204:207], v[24:27]
	v_mfma_f32_16x16x32_bf16 v[12:15], v[140:143], v[222:225], v[12:15]
	v_mfma_f32_16x16x32_bf16 v[8:11], v[154:157], v[222:225], v[8:11]
	v_mfma_f32_16x16x32_bf16 v[60:63], v[150:153], v[182:185], v[60:63]
	v_mfma_f32_16x16x32_bf16 v[56:59], v[158:161], v[182:185], v[56:59]
	v_mfma_f32_16x16x32_bf16 v[44:47], v[150:153], v[200:203], v[44:47]
	v_mfma_f32_16x16x32_bf16 v[40:43], v[158:161], v[200:203], v[40:43]
	v_mfma_f32_16x16x32_bf16 v[28:31], v[150:153], v[208:211], v[28:31]
	v_mfma_f32_16x16x32_bf16 v[24:27], v[158:161], v[208:211], v[24:27]
	v_mfma_f32_16x16x32_bf16 v[12:15], v[150:153], v[226:229], v[12:15]
	v_mfma_f32_16x16x32_bf16 v[8:11], v[158:161], v[226:229], v[8:11]
	v_mfma_f32_16x16x32_bf16 v[52:55], v[162:165], v[178:181], v[52:55]
	v_mfma_f32_16x16x32_bf16 v[48:51], v[170:173], v[178:181], v[48:51]
	v_mfma_f32_16x16x32_bf16 v[36:39], v[162:165], v[186:189], v[36:39]
	v_mfma_f32_16x16x32_bf16 v[32:35], v[170:173], v[186:189], v[32:35]
	v_mfma_f32_16x16x32_bf16 v[20:23], v[162:165], v[204:207], v[20:23]
	v_mfma_f32_16x16x32_bf16 v[16:19], v[170:173], v[204:207], v[16:19]
	v_mfma_f32_16x16x32_bf16 v[4:7], v[162:165], v[222:225], v[4:7]
	v_mfma_f32_16x16x32_bf16 v[0:3], v[170:173], v[222:225], v[0:3]
	v_mfma_f32_16x16x32_bf16 v[52:55], v[166:169], v[182:185], v[52:55]
	v_mfma_f32_16x16x32_bf16 v[48:51], v[174:177], v[182:185], v[48:51]
	v_mfma_f32_16x16x32_bf16 v[36:39], v[166:169], v[200:203], v[36:39]
	v_mfma_f32_16x16x32_bf16 v[32:35], v[174:177], v[200:203], v[32:35]
	v_mfma_f32_16x16x32_bf16 v[20:23], v[166:169], v[208:211], v[20:23]
	v_mfma_f32_16x16x32_bf16 v[16:19], v[174:177], v[208:211], v[16:19]
	v_mfma_f32_16x16x32_bf16 v[4:7], v[166:169], v[226:229], v[4:7]
	v_mfma_f32_16x16x32_bf16 v[0:3], v[174:177], v[226:229], v[0:3]
	s_setprio 0
	s_barrier
	s_add_i32 s84, s84, 2
	s_add_u32 s6, s6, 0x100
	s_addc_u32 s7, s7, 0
	s_add_u32 s74, s74, 0x100
	s_addc_u32 s75, s75, 0
	s_cmp_gt_u32 s84, 29
	s_cbranch_scc0 .LBB0_1486
	s_nop 0
	s_nop 0
	s_nop 0
	s_nop 0
	s_nop 0
	s_nop 0
	s_nop 0
	s_nop 0
	s_and_b64 vcc, exec, s[42:43]
	s_cbranch_vccz .LBB0_1489
	s_barrier

.LBB0_1618:
	s_add_u32 s88, s8, 0x100
	s_addc_u32 s89, s9, 0
	s_add_i32 s24, 0, 0x10000
	s_cmpk_eq_i32 s85, 0x54
	s_cselect_b32 s13, s43, s89
	s_cselect_b32 s12, s42, s88
	s_cselect_b32 s11, s47, s84
	s_cselect_b32 s10, s46, s75
	s_add_i32 s25, 0, 0x14000
	v_add_u32_e32 v116, s24, v223
	v_add_u32_e32 v154, s25, v223
	ds_read_b128 v[88:91], v116
	ds_read_b128 v[92:95], v116 offset:1024
	ds_read_b128 v[104:107], v116 offset:2048
	ds_read_b128 v[116:119], v116 offset:3072
	ds_read_b128 v[130:133], v154
	ds_read_b128 v[134:137], v154 offset:1024
	ds_read_b128 v[146:149], v154 offset:2048
	ds_read_b128 v[154:157], v154 offset:3072
	v_lshl_add_u64 v[226:227], s[8:9], 0, v[206:207]
	s_add_i32 m0, s16, 0xc000
	ds_read_b128 v[162:165], v225
	ds_read_b128 v[166:169], v225 offset:1024
	ds_read_b128 v[170:173], v225 offset:2048
	ds_read_b128 v[174:177], v225 offset:3072
	ds_read_b128 v[178:181], v225 offset:4096
	ds_read_b128 v[182:185], v225 offset:5120
	ds_read_b128 v[186:189], v225 offset:6144
	ds_read_b128 v[210:213], v225 offset:7168
	global_load_lds_dwordx4 v[226:227], off
	v_lshl_add_u64 v[226:227], s[8:9], 0, v[208:209]
	s_add_i32 m0, s16, 0xe000
	s_nop 0
	global_load_lds_dwordx4 v[226:227], off
	s_waitcnt vmcnt(8)
	s_waitcnt lgkmcnt(0)
	s_barrier
	s_setprio 1
	s_waitcnt lgkmcnt(0)
	v_mfma_f32_16x16x32_bf16 v[158:161], v[88:91], v[162:165], v[158:161]
	v_mfma_f32_16x16x32_bf16 v[150:153], v[104:107], v[162:165], v[150:153]
	v_mfma_f32_16x16x32_bf16 v[124:127], v[88:91], v[170:173], v[124:127]
	v_mfma_f32_16x16x32_bf16 v[120:123], v[104:107], v[170:173], v[120:123]
	v_mfma_f32_16x16x32_bf16 v[100:103], v[88:91], v[178:181], v[100:103]
	v_mfma_f32_16x16x32_bf16 v[96:99], v[104:107], v[178:181], v[96:99]
	v_mfma_f32_16x16x32_bf16 v[76:79], v[88:91], v[186:189], v[76:79]
	v_mfma_f32_16x16x32_bf16 v[72:75], v[104:107], v[186:189], v[72:75]
	v_mfma_f32_16x16x32_bf16 v[158:161], v[92:95], v[166:169], v[158:161]
	v_mfma_f32_16x16x32_bf16 v[150:153], v[116:119], v[166:169], v[150:153]
	v_mfma_f32_16x16x32_bf16 v[124:127], v[92:95], v[174:177], v[124:127]
	v_mfma_f32_16x16x32_bf16 v[120:123], v[116:119], v[174:177], v[120:123]
	v_mfma_f32_16x16x32_bf16 v[100:103], v[92:95], v[182:185], v[100:103]
	v_mfma_f32_16x16x32_bf16 v[96:99], v[116:119], v[182:185], v[96:99]
	v_mfma_f32_16x16x32_bf16 v[76:79], v[92:95], v[210:213], v[76:79]
	v_mfma_f32_16x16x32_bf16 v[72:75], v[116:119], v[210:213], v[72:75]
	v_mfma_f32_16x16x32_bf16 v[142:145], v[130:133], v[162:165], v[142:145]
	v_mfma_f32_16x16x32_bf16 v[138:141], v[146:149], v[162:165], v[138:141]
	v_mfma_f32_16x16x32_bf16 v[112:115], v[130:133], v[170:173], v[112:115]
	v_mfma_f32_16x16x32_bf16 v[108:111], v[146:149], v[170:173], v[108:111]
	v_mfma_f32_16x16x32_bf16 v[84:87], v[130:133], v[178:181], v[84:87]
	v_mfma_f32_16x16x32_bf16 v[80:83], v[146:149], v[178:181], v[80:83]
	v_mfma_f32_16x16x32_bf16 v[68:71], v[130:133], v[186:189], v[68:71]
	v_mfma_f32_16x16x32_bf16 v[64:67], v[146:149], v[186:189], v[64:67]
	v_mfma_f32_16x16x32_bf16 v[142:145], v[134:137], v[166:169], v[142:145]
	v_mfma_f32_16x16x32_bf16 v[138:141], v[154:157], v[166:169], v[138:141]
	v_mfma_f32_16x16x32_bf16 v[112:115], v[134:137], v[174:177], v[112:115]
	v_mfma_f32_16x16x32_bf16 v[108:111], v[154:157], v[174:177], v[108:111]
	v_mfma_f32_16x16x32_bf16 v[84:87], v[134:137], v[182:185], v[84:87]
	v_mfma_f32_16x16x32_bf16 v[80:83], v[154:157], v[182:185], v[80:83]
	v_mfma_f32_16x16x32_bf16 v[68:71], v[134:137], v[210:213], v[68:71]
	v_mfma_f32_16x16x32_bf16 v[64:67], v[154:157], v[210:213], v[64:67]
	s_setprio 0
	s_barrier
	s_add_i32 s8, s24, s14
	v_lshl_add_u64 v[226:227], s[10:11], 0, v[128:129]
	s_mov_b32 m0, s8
	ds_read_b128 v[162:165], v225 offset:16384
	ds_read_b128 v[166:169], v225 offset:17408
	ds_read_b128 v[170:173], v225 offset:18432
	ds_read_b128 v[174:177], v225 offset:19456
	ds_read_b128 v[178:181], v225 offset:20480
	ds_read_b128 v[182:185], v225 offset:21504
	ds_read_b128 v[186:189], v225 offset:22528
	ds_read_b128 v[210:213], v225 offset:23552
	global_load_lds_dwordx4 v[226:227], off
	s_add_i32 m0, s8, 0x2000
	s_add_u32 s8, s10, 0x160000
	v_lshl_add_u64 v[228:229], s[10:11], 0, v[200:201]
	s_addc_u32 s9, s11, 0
	s_add_i32 s24, s25, s14
	global_load_lds_dwordx4 v[228:229], off
	v_lshl_add_u64 v[230:231], s[8:9], 0, v[128:129]
	s_mov_b32 m0, s24
	v_lshl_add_u64 v[232:233], s[12:13], 0, v[202:203]
	global_load_lds_dwordx4 v[230:231], off
	v_lshl_add_u64 v[230:231], s[8:9], 0, v[200:201]
	s_add_i32 m0, s24, 0x2000
	s_nop 0
	global_load_lds_dwordx4 v[230:231], off
	v_lshl_add_u64 v[230:231], s[12:13], 0, v[204:205]
	s_mov_b32 m0, s16
	s_nop 0
	global_load_lds_dwordx4 v[230:231], off
	s_mov_b32 m0, s17
	s_nop 0
	global_load_lds_dwordx4 v[232:233], off
	s_waitcnt vmcnt(8)
	s_waitcnt lgkmcnt(0)
	s_barrier
	s_setprio 1
	s_waitcnt lgkmcnt(0)
	v_mfma_f32_16x16x32_bf16 v[60:63], v[88:91], v[162:165], v[60:63]
	v_mfma_f32_16x16x32_bf16 v[56:59], v[104:107], v[162:165], v[56:59]
	v_mfma_f32_16x16x32_bf16 v[44:47], v[88:91], v[170:173], v[44:47]
	v_mfma_f32_16x16x32_bf16 v[40:43], v[104:107], v[170:173], v[40:43]
	v_mfma_f32_16x16x32_bf16 v[28:31], v[88:91], v[178:181], v[28:31]
	v_mfma_f32_16x16x32_bf16 v[24:27], v[104:107], v[178:181], v[24:27]
	v_mfma_f32_16x16x32_bf16 v[12:15], v[88:91], v[186:189], v[12:15]
	v_mfma_f32_16x16x32_bf16 v[8:11], v[104:107], v[186:189], v[8:11]
	v_mfma_f32_16x16x32_bf16 v[60:63], v[92:95], v[166:169], v[60:63]
	v_mfma_f32_16x16x32_bf16 v[56:59], v[116:119], v[166:169], v[56:59]
	v_mfma_f32_16x16x32_bf16 v[44:47], v[92:95], v[174:177], v[44:47]
	v_mfma_f32_16x16x32_bf16 v[40:43], v[116:119], v[174:177], v[40:43]
	v_mfma_f32_16x16x32_bf16 v[28:31], v[92:95], v[182:185], v[28:31]
	v_mfma_f32_16x16x32_bf16 v[24:27], v[116:119], v[182:185], v[24:27]
	v_mfma_f32_16x16x32_bf16 v[12:15], v[92:95], v[210:213], v[12:15]
	v_mfma_f32_16x16x32_bf16 v[8:11], v[116:119], v[210:213], v[8:11]
	v_mfma_f32_16x16x32_bf16 v[52:55], v[130:133], v[162:165], v[52:55]
	v_mfma_f32_16x16x32_bf16 v[48:51], v[146:149], v[162:165], v[48:51]
	v_mfma_f32_16x16x32_bf16 v[36:39], v[130:133], v[170:173], v[36:39]
	v_mfma_f32_16x16x32_bf16 v[32:35], v[146:149], v[170:173], v[32:35]
	v_mfma_f32_16x16x32_bf16 v[20:23], v[130:133], v[178:181], v[20:23]
	v_mfma_f32_16x16x32_bf16 v[16:19], v[146:149], v[178:181], v[16:19]
	v_mfma_f32_16x16x32_bf16 v[4:7], v[130:133], v[186:189], v[4:7]
	v_mfma_f32_16x16x32_bf16 v[0:3], v[146:149], v[186:189], v[0:3]
	v_mfma_f32_16x16x32_bf16 v[52:55], v[134:137], v[166:169], v[52:55]
	v_mfma_f32_16x16x32_bf16 v[48:51], v[154:157], v[166:169], v[48:51]
	v_mfma_f32_16x16x32_bf16 v[36:39], v[134:137], v[174:177], v[36:39]
	v_mfma_f32_16x16x32_bf16 v[32:35], v[154:157], v[174:177], v[32:35]
	v_mfma_f32_16x16x32_bf16 v[20:23], v[134:137], v[182:185], v[20:23]
	v_mfma_f32_16x16x32_bf16 v[16:19], v[154:157], v[182:185], v[16:19]
	v_mfma_f32_16x16x32_bf16 v[4:7], v[134:137], v[210:213], v[4:7]
	v_mfma_f32_16x16x32_bf16 v[0:3], v[154:157], v[210:213], v[0:3]
	s_setprio 0
	s_barrier
	s_add_i32 s24, 0, 0x18000
	s_add_i32 s25, 0, 0x1c000
	v_add_u32_e32 v116, s24, v223
	v_add_u32_e32 v154, s25, v223
	ds_read_b128 v[88:91], v116
	ds_read_b128 v[92:95], v116 offset:1024
	ds_read_b128 v[104:107], v116 offset:2048
	ds_read_b128 v[116:119], v116 offset:3072
	ds_read_b128 v[130:133], v154
	ds_read_b128 v[134:137], v154 offset:1024
	ds_read_b128 v[146:149], v154 offset:2048
	ds_read_b128 v[154:157], v154 offset:3072
	s_add_u32 s8, s12, 0x160000
	s_addc_u32 s9, s13, 0
	s_mov_b32 m0, s18
	v_lshl_add_u64 v[234:235], s[8:9], 0, v[204:205]
	ds_read_b128 v[162:165], v225 offset:32768
	ds_read_b128 v[166:169], v225 offset:33792
	ds_read_b128 v[170:173], v225 offset:34816
	ds_read_b128 v[174:177], v225 offset:35840
	ds_read_b128 v[178:181], v225 offset:36864
	ds_read_b128 v[182:185], v225 offset:37888
	ds_read_b128 v[186:189], v225 offset:38912
	ds_read_b128 v[210:213], v225 offset:39936
	global_load_lds_dwordx4 v[234:235], off
	v_lshl_add_u64 v[234:235], s[8:9], 0, v[202:203]
	s_mov_b32 m0, s19
	s_nop 0
	global_load_lds_dwordx4 v[234:235], off
	s_waitcnt vmcnt(8)
	s_waitcnt lgkmcnt(0)
	s_barrier
	s_setprio 1
	s_waitcnt lgkmcnt(0)
	v_mfma_f32_16x16x32_bf16 v[158:161], v[88:91], v[162:165], v[158:161]
	v_mfma_f32_16x16x32_bf16 v[150:153], v[104:107], v[162:165], v[150:153]
	v_mfma_f32_16x16x32_bf16 v[124:127], v[88:91], v[170:173], v[124:127]
	v_mfma_f32_16x16x32_bf16 v[120:123], v[104:107], v[170:173], v[120:123]
	v_mfma_f32_16x16x32_bf16 v[100:103], v[88:91], v[178:181], v[100:103]
	v_mfma_f32_16x16x32_bf16 v[96:99], v[104:107], v[178:181], v[96:99]
	v_mfma_f32_16x16x32_bf16 v[76:79], v[88:91], v[186:189], v[76:79]
	v_mfma_f32_16x16x32_bf16 v[72:75], v[104:107], v[186:189], v[72:75]
	v_mfma_f32_16x16x32_bf16 v[158:161], v[92:95], v[166:169], v[158:161]
	v_mfma_f32_16x16x32_bf16 v[150:153], v[116:119], v[166:169], v[150:153]
	v_mfma_f32_16x16x32_bf16 v[124:127], v[92:95], v[174:177], v[124:127]
	v_mfma_f32_16x16x32_bf16 v[120:123], v[116:119], v[174:177], v[120:123]
	v_mfma_f32_16x16x32_bf16 v[100:103], v[92:95], v[182:185], v[100:103]
	v_mfma_f32_16x16x32_bf16 v[96:99], v[116:119], v[182:185], v[96:99]
	v_mfma_f32_16x16x32_bf16 v[76:79], v[92:95], v[210:213], v[76:79]
	v_mfma_f32_16x16x32_bf16 v[72:75], v[116:119], v[210:213], v[72:75]
	v_mfma_f32_16x16x32_bf16 v[142:145], v[130:133], v[162:165], v[142:145]
	v_mfma_f32_16x16x32_bf16 v[138:141], v[146:149], v[162:165], v[138:141]
	v_mfma_f32_16x16x32_bf16 v[112:115], v[130:133], v[170:173], v[112:115]
	v_mfma_f32_16x16x32_bf16 v[108:111], v[146:149], v[170:173], v[108:111]
	v_mfma_f32_16x16x32_bf16 v[84:87], v[130:133], v[178:181], v[84:87]
	v_mfma_f32_16x16x32_bf16 v[80:83], v[146:149], v[178:181], v[80:83]
	v_mfma_f32_16x16x32_bf16 v[68:71], v[130:133], v[186:189], v[68:71]
	v_mfma_f32_16x16x32_bf16 v[64:67], v[146:149], v[186:189], v[64:67]
	v_mfma_f32_16x16x32_bf16 v[142:145], v[134:137], v[166:169], v[142:145]
	v_mfma_f32_16x16x32_bf16 v[138:141], v[154:157], v[166:169], v[138:141]
	v_mfma_f32_16x16x32_bf16 v[112:115], v[134:137], v[174:177], v[112:115]
	v_mfma_f32_16x16x32_bf16 v[108:111], v[154:157], v[174:177], v[108:111]
	v_mfma_f32_16x16x32_bf16 v[84:87], v[134:137], v[182:185], v[84:87]
	v_mfma_f32_16x16x32_bf16 v[80:83], v[154:157], v[182:185], v[80:83]
	v_mfma_f32_16x16x32_bf16 v[68:71], v[134:137], v[210:213], v[68:71]
	v_mfma_f32_16x16x32_bf16 v[64:67], v[154:157], v[210:213], v[64:67]
	s_setprio 0
	s_barrier
	s_add_i32 s8, s24, s14
	v_lshl_add_u64 v[226:227], v[226:227], 0, s[26:27]
	s_mov_b32 m0, s8
	ds_read_b128 v[162:165], v225 offset:49152
	ds_read_b128 v[166:169], v225 offset:50176
	ds_read_b128 v[170:173], v225 offset:51200
	ds_read_b128 v[174:177], v225 offset:52224
	ds_read_b128 v[178:181], v225 offset:53248
	ds_read_b128 v[182:185], v225 offset:54272
	ds_read_b128 v[186:189], v225 offset:55296
	ds_read_b128 v[210:213], v225 offset:56320
	global_load_lds_dwordx4 v[226:227], off
	s_add_i32 m0, s8, 0x2000
	s_add_u32 s8, s10, 0x160080
	v_lshl_add_u64 v[226:227], v[228:229], 0, s[26:27]
	s_addc_u32 s9, s11, 0
	s_add_i32 s10, s25, s14
	global_load_lds_dwordx4 v[226:227], off
	v_lshl_add_u64 v[226:227], s[8:9], 0, v[128:129]
	s_mov_b32 m0, s10
	s_nop 0
	global_load_lds_dwordx4 v[226:227], off
	v_lshl_add_u64 v[226:227], s[8:9], 0, v[200:201]
	s_add_i32 m0, s10, 0x2000
	s_nop 0
	global_load_lds_dwordx4 v[226:227], off
	v_lshl_add_u64 v[226:227], v[230:231], 0, s[26:27]
	s_mov_b32 m0, s20
	s_nop 0
	global_load_lds_dwordx4 v[226:227], off
	v_lshl_add_u64 v[226:227], v[232:233], 0, s[26:27]
	s_mov_b32 m0, s21
	s_nop 0
	global_load_lds_dwordx4 v[226:227], off
	s_waitcnt vmcnt(8)
	s_waitcnt lgkmcnt(0)
	s_barrier
	s_setprio 1
	s_waitcnt lgkmcnt(0)
	v_mfma_f32_16x16x32_bf16 v[60:63], v[88:91], v[162:165], v[60:63]
	v_mfma_f32_16x16x32_bf16 v[56:59], v[104:107], v[162:165], v[56:59]
	v_mfma_f32_16x16x32_bf16 v[44:47], v[88:91], v[170:173], v[44:47]
	v_mfma_f32_16x16x32_bf16 v[40:43], v[104:107], v[170:173], v[40:43]
	v_mfma_f32_16x16x32_bf16 v[28:31], v[88:91], v[178:181], v[28:31]
	v_mfma_f32_16x16x32_bf16 v[24:27], v[104:107], v[178:181], v[24:27]
	v_mfma_f32_16x16x32_bf16 v[12:15], v[88:91], v[186:189], v[12:15]
	v_mfma_f32_16x16x32_bf16 v[8:11], v[104:107], v[186:189], v[8:11]
	v_mfma_f32_16x16x32_bf16 v[60:63], v[92:95], v[166:169], v[60:63]
	v_mfma_f32_16x16x32_bf16 v[56:59], v[116:119], v[166:169], v[56:59]
	v_mfma_f32_16x16x32_bf16 v[44:47], v[92:95], v[174:177], v[44:47]
	v_mfma_f32_16x16x32_bf16 v[40:43], v[116:119], v[174:177], v[40:43]
	v_mfma_f32_16x16x32_bf16 v[28:31], v[92:95], v[182:185], v[28:31]
	v_mfma_f32_16x16x32_bf16 v[24:27], v[116:119], v[182:185], v[24:27]
	v_mfma_f32_16x16x32_bf16 v[12:15], v[92:95], v[210:213], v[12:15]
	v_mfma_f32_16x16x32_bf16 v[8:11], v[116:119], v[210:213], v[8:11]
	v_mfma_f32_16x16x32_bf16 v[52:55], v[130:133], v[162:165], v[52:55]
	v_mfma_f32_16x16x32_bf16 v[48:51], v[146:149], v[162:165], v[48:51]
	v_mfma_f32_16x16x32_bf16 v[36:39], v[130:133], v[170:173], v[36:39]
	v_mfma_f32_16x16x32_bf16 v[32:35], v[146:149], v[170:173], v[32:35]
	v_mfma_f32_16x16x32_bf16 v[20:23], v[130:133], v[178:181], v[20:23]
	v_mfma_f32_16x16x32_bf16 v[16:19], v[146:149], v[178:181], v[16:19]
	v_mfma_f32_16x16x32_bf16 v[4:7], v[130:133], v[186:189], v[4:7]
	v_mfma_f32_16x16x32_bf16 v[0:3], v[146:149], v[186:189], v[0:3]
	v_mfma_f32_16x16x32_bf16 v[52:55], v[134:137], v[166:169], v[52:55]
	v_mfma_f32_16x16x32_bf16 v[48:51], v[154:157], v[166:169], v[48:51]
	v_mfma_f32_16x16x32_bf16 v[36:39], v[134:137], v[174:177], v[36:39]
	v_mfma_f32_16x16x32_bf16 v[32:35], v[154:157], v[174:177], v[32:35]
	v_mfma_f32_16x16x32_bf16 v[20:23], v[134:137], v[182:185], v[20:23]
	v_mfma_f32_16x16x32_bf16 v[16:19], v[154:157], v[182:185], v[16:19]
	v_mfma_f32_16x16x32_bf16 v[4:7], v[134:137], v[210:213], v[4:7]
	v_mfma_f32_16x16x32_bf16 v[0:3], v[154:157], v[210:213], v[0:3]
	s_setprio 0
	s_barrier
	s_add_i32 s85, s85, 2
	s_add_u32 s75, s75, 0x100
	s_addc_u32 s84, s84, 0
	s_cmpk_gt_u32 s85, 0x55
	s_mov_b64 s[8:9], s[88:89]
	s_cbranch_scc0 .LBB0_1618
	s_nop 0
	s_nop 0
	s_nop 0
	s_nop 0
	s_nop 0
	s_nop 0
	s_nop 0
	s_nop 0
	s_and_b64 vcc, exec, s[6:7]
	s_cbranch_vccz .LBB0_1621
	s_barrier
